# sigmoid reciprocal: v_rcp_f32 instead of the 11-instruction IEEE division chain (ffn conv, qk conv, GEMM sigmoid epilogues); f32 throughout
# speedup vs baseline: 1.0541x; 1.0143x over previous
; __device__ __forceinline__ float sigm(float x) { return 1.f / (1.f + __expf(-x)); }
; __device__ __forceinline__ u32x4 pack8(const float (&f)[8]) { u32x4 w; w.x = pk2(f[0], f[1]); w.y = pk2(f[2], f[3]); w.z = pk2(f[4], f[5]); w.w = pk2(f[6], f[7]); return w; }
; __device__ __forceinline__ void ffn_conv_item(int tid_in, int b, int strip, bf16_t* h1, const bf16_t* h2, const float* cw, const float* cb, bool st = true) {
;     ...
;         for (int j = 0; j < 4; ++j) {
;             const size_t off = off0 + (size_t)(32 * blk + 8 * j + rl) * 5632;
;             const u32x4 cgv = cg4[j], cvv = cv4[j];
;             float xg[8], xv[8], yg[8], yv[8]; unpack8(cgv, xg); unpack8(cvv, xv);
; #pragma unroll
;             for (int e = 0; e < 8; ++e) { yg[e] = bg[e] + wg[2][e] * xg[e]; yv[e] = bv[e] + wv[2][e] * xv[e]; }
; #pragma unroll
;             for (int d = 1; d <= 2; ++d) {
;                 const bool own = (rl + d <= 7); const int src = (lane + 64 - 8 * d) & 63;
;                 const u32x4 sg = own ? cgv : pg, sv = own ? cvv : pv;
;                 u32x4 g, v; g.x = __shfl(sg.x, src); g.y = __shfl(sg.y, src); g.z = __shfl(sg.z, src); g.w = __shfl(sg.w, src);
;                 v.x = __shfl(sv.x, src); v.y = __shfl(sv.y, src); v.z = __shfl(sv.z, src); v.w = __shfl(sv.w, src);
;                 float dg[8], dv[8]; unpack8(g, dg); unpack8(v, dv);
; #pragma unroll
;                 for (int e = 0; e < 8; ++e) { yg[e] += wg[2 - d][e] * dg[e]; yv[e] += wv[2 - d][e] * dv[e]; }
;             }
; #pragma unroll
;             for (int e = 0; e < 8; ++e) yg[e] = yg[e] * sigm(yg[e]) * yv[e];
;             { const u32x4 o_ = pack8(yg); if (st) *(u32x4*)(h1 + off) = o_; else asm volatile("" :: "v"(o_)); }
;             pg = cgv; pv = cvv;
.LBB0_24:
	v_cndmask_b32_e64 v142, v97, v105, s[40:41]
	v_cndmask_b32_e64 v145, v94, v102, s[40:41]
	v_cndmask_b32_e64 v151, v98, v90, s[40:41]
	v_cndmask_b32_e64 v143, v96, v104, s[40:41]
	ds_bpermute_b32 v145, v0, v145
	ds_bpermute_b32 v154, v0, v142
	ds_bpermute_b32 v142, v0, v151
	v_cndmask_b32_e64 v104, v104, v96, s[42:43]
	v_cndmask_b32_e64 v102, v102, v94, s[42:43]
	v_cndmask_b32_e64 v90, v90, v98, s[42:43]
	ds_bpermute_b32 v102, v147, v102
	ds_bpermute_b32 v157, v147, v104
	ds_bpermute_b32 v104, v147, v90
	v_cndmask_b32_e64 v150, v99, v91, s[40:41]
	v_cndmask_b32_e64 v105, v105, v97, s[42:43]
	v_cndmask_b32_e64 v91, v91, v99, s[42:43]
	v_cndmask_b32_e64 v148, v101, v93, s[40:41]
	v_cndmask_b32_e64 v149, v100, v92, s[40:41]
	v_cndmask_b32_e64 v93, v93, v101, s[42:43]
	v_cndmask_b32_e64 v92, v92, v100, s[42:43]
	ds_bpermute_b32 v158, v147, v105
	ds_bpermute_b32 v105, v147, v91
	v_lshlrev_b32_e32 v91, 16, v94
	v_lshlrev_b32_e32 v90, 16, v98
	v_cndmask_b32_e64 v144, v95, v103, s[40:41]
	ds_bpermute_b32 v159, v147, v92
	ds_bpermute_b32 v160, v147, v93
	v_pk_fma_f32 v[90:91], v[132:133], v[90:91], v[130:131]
	s_waitcnt lgkmcnt(9)
	v_lshlrev_b32_e32 v93, 16, v145
	s_waitcnt lgkmcnt(7)
	v_lshlrev_b32_e32 v92, 16, v142
	ds_bpermute_b32 v152, v0, v144
	ds_bpermute_b32 v153, v0, v143
	ds_bpermute_b32 v143, v0, v150
	v_cndmask_b32_e64 v103, v103, v95, s[42:43]
	v_pk_fma_f32 v[90:91], v[134:135], v[92:93], v[90:91]
	s_waitcnt lgkmcnt(9)
	v_lshlrev_b32_e32 v93, 16, v102
	s_waitcnt lgkmcnt(7)
	v_lshlrev_b32_e32 v92, 16, v104
	ds_bpermute_b32 v155, v0, v149
	ds_bpermute_b32 v156, v0, v148
	ds_bpermute_b32 v103, v147, v103
	v_pk_fma_f32 v[148:149], v[136:137], v[92:93], v[90:91]
	v_and_b32_e32 v91, 0xffff0000, v94
	v_and_b32_e32 v90, 0xffff0000, v98
	v_pk_fma_f32 v[90:91], v[22:23], v[90:91], v[30:31]
	v_and_b32_e32 v93, 0xffff0000, v145
	v_and_b32_e32 v92, 0xffff0000, v142
	v_pk_fma_f32 v[90:91], v[14:15], v[92:93], v[90:91]
	v_and_b32_e32 v93, 0xffff0000, v102
	v_and_b32_e32 v92, 0xffff0000, v104
	v_pk_fma_f32 v[150:151], v[6:7], v[92:93], v[90:91]
	v_lshlrev_b32_e32 v91, 16, v95
	v_lshlrev_b32_e32 v90, 16, v99
	v_pk_fma_f32 v[90:91], v[124:125], v[90:91], v[122:123]
	s_waitcnt lgkmcnt(5)
	v_lshlrev_b32_e32 v93, 16, v152
	s_waitcnt lgkmcnt(3)
	v_lshlrev_b32_e32 v92, 16, v143
	v_pk_fma_f32 v[90:91], v[126:127], v[92:93], v[90:91]
	s_waitcnt lgkmcnt(0)
	v_lshlrev_b32_e32 v93, 16, v103
	v_lshlrev_b32_e32 v92, 16, v105
	v_pk_fma_f32 v[144:145], v[128:129], v[92:93], v[90:91]
	v_and_b32_e32 v91, 0xffff0000, v95
	v_and_b32_e32 v90, 0xffff0000, v99
	v_pk_fma_f32 v[90:91], v[24:25], v[90:91], v[32:33]
	v_and_b32_e32 v93, 0xffff0000, v152
	v_and_b32_e32 v92, 0xffff0000, v143
	v_pk_fma_f32 v[90:91], v[16:17], v[92:93], v[90:91]
	v_and_b32_e32 v93, 0xffff0000, v103
	v_and_b32_e32 v92, 0xffff0000, v105
	v_pk_fma_f32 v[142:143], v[8:9], v[92:93], v[90:91]
	v_lshlrev_b32_e32 v91, 16, v96
	v_lshlrev_b32_e32 v90, 16, v100
	v_pk_fma_f32 v[90:91], v[116:117], v[90:91], v[114:115]
	v_lshlrev_b32_e32 v93, 16, v153
	v_lshlrev_b32_e32 v92, 16, v155
	v_pk_fma_f32 v[90:91], v[118:119], v[92:93], v[90:91]
	v_lshlrev_b32_e32 v93, 16, v157
	v_lshlrev_b32_e32 v92, 16, v159
	v_pk_fma_f32 v[104:105], v[120:121], v[92:93], v[90:91]
	v_and_b32_e32 v91, 0xffff0000, v96
	v_and_b32_e32 v90, 0xffff0000, v100
	v_pk_fma_f32 v[90:91], v[18:19], v[90:91], v[26:27]
	v_and_b32_e32 v93, 0xffff0000, v153
	v_and_b32_e32 v92, 0xffff0000, v155
	v_pk_fma_f32 v[90:91], v[10:11], v[92:93], v[90:91]
	v_and_b32_e32 v93, 0xffff0000, v157
	v_and_b32_e32 v92, 0xffff0000, v159
	v_pk_fma_f32 v[102:103], v[2:3], v[92:93], v[90:91]
	v_lshlrev_b32_e32 v91, 16, v97
	v_lshlrev_b32_e32 v90, 16, v101
	v_pk_fma_f32 v[90:91], v[108:109], v[90:91], v[106:107]
	v_lshlrev_b32_e32 v93, 16, v154
	v_lshlrev_b32_e32 v92, 16, v156
	v_pk_fma_f32 v[90:91], v[110:111], v[92:93], v[90:91]
	v_lshlrev_b32_e32 v93, 16, v158
	v_lshlrev_b32_e32 v92, 16, v160
	v_pk_fma_f32 v[92:93], v[112:113], v[92:93], v[90:91]
	v_and_b32_e32 v91, 0xffff0000, v97
	v_and_b32_e32 v90, 0xffff0000, v101
	v_pk_fma_f32 v[90:91], v[20:21], v[90:91], v[28:29]
	v_and_b32_e32 v153, 0xffff0000, v154
	v_and_b32_e32 v152, 0xffff0000, v156
	v_pk_fma_f32 v[90:91], v[12:13], v[152:153], v[90:91]
	v_and_b32_e32 v153, 0xffff0000, v158
	v_and_b32_e32 v152, 0xffff0000, v160
	v_pk_fma_f32 v[90:91], v[4:5], v[152:153], v[90:91]
	v_mul_f32_e32 v152, 0xbfb8aa3b, v149
	v_exp_f32_e32 v152, v152
	s_mov_b32 s9, 0x4a00000
	s_add_u32 s34, s34, 0x58000
	s_addc_u32 s35, s35, 0
	v_add_f32_e32 v152, 1.0, v152
	s_cmp_lg_u32 s34, 0x580000
	v_rcp_f32_e32 v152, v152
	s_nop 0
	v_mul_f32_e32 v149, v149, v152
	v_mul_f32_e32 v148, v148, v149
	v_mul_f32_e32 v149, 0xbfb8aa3b, v151
	v_exp_f32_e32 v149, v149
	s_nop 0
	v_add_f32_e32 v149, 1.0, v149
	s_nop 0
	v_rcp_f32_e32 v149, v149
	s_nop 0
	v_mul_f32_e32 v149, v151, v149
	v_mul_f32_e32 v149, v150, v149
	v_mul_f32_e32 v150, 0xbfb8aa3b, v145
	v_exp_f32_e32 v150, v150
	s_nop 0
	v_add_f32_e32 v150, 1.0, v150
	s_nop 0
	v_rcp_f32_e32 v150, v150
	s_nop 0
	v_mul_f32_e32 v145, v145, v150
	v_mul_f32_e32 v144, v144, v145
	v_mul_f32_e32 v145, 0xbfb8aa3b, v143
	v_exp_f32_e32 v145, v145
	s_nop 0
	v_add_f32_e32 v145, 1.0, v145
	s_nop 0
	v_rcp_f32_e32 v145, v145
	s_nop 0
	v_mul_f32_e32 v143, v143, v145
	v_mul_f32_e32 v142, v142, v143
	v_mul_f32_e32 v143, 0xbfb8aa3b, v105
	v_exp_f32_e32 v143, v143
	s_nop 0
	v_add_f32_e32 v143, 1.0, v143
	s_nop 0
	v_rcp_f32_e32 v143, v143
	s_nop 0
	v_mul_f32_e32 v105, v105, v143
	v_mul_f32_e32 v104, v104, v105
	v_mul_f32_e32 v105, 0xbfb8aa3b, v103
	v_exp_f32_e32 v105, v105
	s_nop 0
	v_add_f32_e32 v105, 1.0, v105
; __device__ __forceinline__ float sigm(float x) { return 1.f / (1.f + __expf(-x)); }
; __device__ __forceinline__ u32x4 pack8(const float (&f)[8]) { u32x4 w; w.x = pk2(f[0], f[1]); w.y = pk2(f[2], f[3]); w.z = pk2(f[4], f[5]); w.w = pk2(f[6], f[7]); return w; }
; __device__ __forceinline__ void ffn_conv_item(int tid_in, int b, int strip, bf16_t* h1, const bf16_t* h2, const float* cw, const float* cb, bool st = true) {
;     ...
;         for (int j = 0; j < 4; ++j) {
;             const size_t off = off0 + (size_t)(32 * blk + 8 * j + rl) * 5632;
;             const u32x4 cgv = cg4[j], cvv = cv4[j];
;             float xg[8], xv[8], yg[8], yv[8]; unpack8(cgv, xg); unpack8(cvv, xv);
; #pragma unroll
;             for (int e = 0; e < 8; ++e) { yg[e] = bg[e] + wg[2][e] * xg[e]; yv[e] = bv[e] + wv[2][e] * xv[e]; }
; #pragma unroll
;             for (int d = 1; d <= 2; ++d) {
;                 const bool own = (rl + d <= 7); const int src = (lane + 64 - 8 * d) & 63;
;                 const u32x4 sg = own ? cgv : pg, sv = own ? cvv : pv;
;                 u32x4 g, v; g.x = __shfl(sg.x, src); g.y = __shfl(sg.y, src); g.z = __shfl(sg.z, src); g.w = __shfl(sg.w, src);
;                 v.x = __shfl(sv.x, src); v.y = __shfl(sv.y, src); v.z = __shfl(sv.z, src); v.w = __shfl(sv.w, src);
;                 float dg[8], dv[8]; unpack8(g, dg); unpack8(v, dv);
; #pragma unroll
;                 for (int e = 0; e < 8; ++e) { yg[e] += wg[2 - d][e] * dg[e]; yv[e] += wv[2 - d][e] * dv[e]; }
;             }
; #pragma unroll
;             for (int e = 0; e < 8; ++e) yg[e] = yg[e] * sigm(yg[e]) * yv[e];
;             { const u32x4 o_ = pack8(yg); if (st) *(u32x4*)(h1 + off) = o_; else asm volatile("" :: "v"(o_)); }
;             pg = cgv; pv = cvv;
	s_nop 0
	v_rcp_f32_e32 v105, v105
	s_nop 0
	v_mul_f32_e32 v103, v103, v105
	v_mul_f32_e32 v102, v102, v103
	v_mul_f32_e32 v103, 0xbfb8aa3b, v93
	v_exp_f32_e32 v103, v103
	s_nop 0
	v_add_f32_e32 v103, 1.0, v103
	s_nop 0
	v_rcp_f32_e32 v103, v103
	s_nop 0
	v_mul_f32_e32 v93, v93, v103
	v_mul_f32_e32 v93, v92, v93
	v_mul_f32_e32 v92, 0xbfb8aa3b, v91
	v_exp_f32_e32 v92, v92
	s_nop 0
	v_add_f32_e32 v92, 1.0, v92
	s_nop 0
	v_rcp_f32_e32 v92, v92
	s_nop 0
	v_mul_f32_e32 v91, v91, v92
	v_mul_f32_e32 v103, v90, v91
	v_cvt_pk_bf16_f32 v90, v148, v149
	v_cvt_pk_bf16_f32 v91, v144, v142
	v_cvt_pk_bf16_f32 v92, v104, v102
	v_add_co_u32_e32 v102, vcc, s9, v140
	v_cvt_pk_bf16_f32 v93, v93, v103
	v_cndmask_b32_e64 v105, v86, v98, s[40:41]
	s_nop 0
	v_addc_co_u32_e32 v103, vcc, 0, v141, vcc
	global_store_dwordx4 v[102:103], v[90:93], off
	ds_bpermute_b32 v105, v0, v105
	v_cndmask_b32_e64 v104, v87, v99, s[40:41]
	v_cndmask_b32_e64 v90, v85, v97, s[40:41]
	v_cndmask_b32_e64 v93, v82, v94, s[40:41]
	ds_bpermute_b32 v142, v0, v93
	ds_bpermute_b32 v145, v0, v90
	v_cndmask_b32_e64 v90, v97, v85, s[42:43]
	v_cndmask_b32_e64 v93, v94, v82, s[42:43]
	v_cndmask_b32_e64 v97, v98, v86, s[42:43]
	ds_bpermute_b32 v98, v147, v93
	ds_bpermute_b32 v97, v147, v97
	v_cndmask_b32_e64 v91, v84, v96, s[40:41]
	v_cndmask_b32_e64 v92, v83, v95, s[40:41]
	ds_bpermute_b32 v144, v0, v91
	v_cndmask_b32_e64 v91, v96, v84, s[42:43]
	ds_bpermute_b32 v143, v0, v92
	v_cndmask_b32_e64 v92, v95, v83, s[42:43]
	ds_bpermute_b32 v151, v147, v91
	ds_bpermute_b32 v152, v147, v90
	v_lshlrev_b32_e32 v91, 16, v82
	v_lshlrev_b32_e32 v90, 16, v86
	v_cndmask_b32_e64 v96, v99, v87, s[42:43]
	ds_bpermute_b32 v99, v147, v92
	v_pk_fma_f32 v[90:91], v[132:133], v[90:91], v[130:131]
	s_waitcnt lgkmcnt(8)
	v_lshlrev_b32_e32 v93, 16, v142
	v_lshlrev_b32_e32 v92, 16, v105
	v_cndmask_b32_e64 v102, v89, v101, s[40:41]
	v_cndmask_b32_e64 v103, v88, v100, s[40:41]
	ds_bpermute_b32 v148, v0, v104
	v_pk_fma_f32 v[90:91], v[134:135], v[92:93], v[90:91]
	s_waitcnt lgkmcnt(7)
	v_lshlrev_b32_e32 v93, 16, v98
	s_waitcnt lgkmcnt(6)
	v_lshlrev_b32_e32 v92, 16, v97
	ds_bpermute_b32 v149, v0, v103
	ds_bpermute_b32 v150, v0, v102
	ds_bpermute_b32 v96, v147, v96
	v_pk_fma_f32 v[102:103], v[136:137], v[92:93], v[90:91]
	v_and_b32_e32 v91, 0xffff0000, v82
	v_and_b32_e32 v90, 0xffff0000, v86
	v_pk_fma_f32 v[90:91], v[22:23], v[90:91], v[30:31]
	v_and_b32_e32 v93, 0xffff0000, v142
	v_and_b32_e32 v92, 0xffff0000, v105
	v_pk_fma_f32 v[90:91], v[14:15], v[92:93], v[90:91]
	v_and_b32_e32 v93, 0xffff0000, v98
	v_and_b32_e32 v92, 0xffff0000, v97
	v_pk_fma_f32 v[104:105], v[6:7], v[92:93], v[90:91]
	v_lshlrev_b32_e32 v91, 16, v83
	v_lshlrev_b32_e32 v90, 16, v87
	v_pk_fma_f32 v[90:91], v[124:125], v[90:91], v[122:123]
	s_waitcnt lgkmcnt(7)
	v_lshlrev_b32_e32 v93, 16, v143
	s_waitcnt lgkmcnt(3)
	v_lshlrev_b32_e32 v92, 16, v148
	v_cndmask_b32_e64 v95, v100, v88, s[42:43]
	v_pk_fma_f32 v[90:91], v[126:127], v[92:93], v[90:91]
	v_lshlrev_b32_e32 v93, 16, v99
	s_waitcnt lgkmcnt(0)
	v_lshlrev_b32_e32 v92, 16, v96
	v_cndmask_b32_e64 v94, v101, v89, s[42:43]
	ds_bpermute_b32 v95, v147, v95
	v_pk_fma_f32 v[100:101], v[128:129], v[92:93], v[90:91]
	v_and_b32_e32 v91, 0xffff0000, v83
	v_and_b32_e32 v90, 0xffff0000, v87
	v_pk_fma_f32 v[90:91], v[24:25], v[90:91], v[32:33]
	v_and_b32_e32 v93, 0xffff0000, v143
	v_and_b32_e32 v92, 0xffff0000, v148
	v_pk_fma_f32 v[90:91], v[16:17], v[92:93], v[90:91]
	v_and_b32_e32 v93, 0xffff0000, v99
	v_and_b32_e32 v92, 0xffff0000, v96
	v_pk_fma_f32 v[98:99], v[8:9], v[92:93], v[90:91]
	v_lshlrev_b32_e32 v91, 16, v84
	v_lshlrev_b32_e32 v90, 16, v88
	v_pk_fma_f32 v[90:91], v[116:117], v[90:91], v[114:115]
	v_lshlrev_b32_e32 v93, 16, v144
	v_lshlrev_b32_e32 v92, 16, v149
	v_pk_fma_f32 v[90:91], v[118:119], v[92:93], v[90:91]
	v_lshlrev_b32_e32 v93, 16, v151
	s_waitcnt lgkmcnt(0)
	v_lshlrev_b32_e32 v92, 16, v95
	ds_bpermute_b32 v153, v147, v94
	v_pk_fma_f32 v[96:97], v[120:121], v[92:93], v[90:91]
	v_and_b32_e32 v91, 0xffff0000, v84
	v_and_b32_e32 v90, 0xffff0000, v88
	v_pk_fma_f32 v[90:91], v[18:19], v[90:91], v[26:27]
	v_and_b32_e32 v93, 0xffff0000, v144
	v_and_b32_e32 v92, 0xffff0000, v149
	v_pk_fma_f32 v[90:91], v[10:11], v[92:93], v[90:91]
	v_and_b32_e32 v93, 0xffff0000, v151
	v_and_b32_e32 v92, 0xffff0000, v95
	v_pk_fma_f32 v[94:95], v[2:3], v[92:93], v[90:91]
	v_lshlrev_b32_e32 v91, 16, v85
	v_lshlrev_b32_e32 v90, 16, v89
	v_pk_fma_f32 v[90:91], v[108:109], v[90:91], v[106:107]
	v_lshlrev_b32_e32 v93, 16, v145
	v_lshlrev_b32_e32 v92, 16, v150
	v_pk_fma_f32 v[90:91], v[110:111], v[92:93], v[90:91]
	v_lshlrev_b32_e32 v93, 16, v152
	s_waitcnt lgkmcnt(0)
; __device__ __forceinline__ float sigm(float x) { return 1.f / (1.f + __expf(-x)); }
; __device__ __forceinline__ u32x4 pack8(const float (&f)[8]) { u32x4 w; w.x = pk2(f[0], f[1]); w.y = pk2(f[2], f[3]); w.z = pk2(f[4], f[5]); w.w = pk2(f[6], f[7]); return w; }
; __device__ __forceinline__ void ffn_conv_item(int tid_in, int b, int strip, bf16_t* h1, const bf16_t* h2, const float* cw, const float* cb, bool st = true) {
;     ...
;         for (int j = 0; j < 4; ++j) {
;             const size_t off = off0 + (size_t)(32 * blk + 8 * j + rl) * 5632;
;             const u32x4 cgv = cg4[j], cvv = cv4[j];
;             float xg[8], xv[8], yg[8], yv[8]; unpack8(cgv, xg); unpack8(cvv, xv);
; #pragma unroll
;             for (int e = 0; e < 8; ++e) { yg[e] = bg[e] + wg[2][e] * xg[e]; yv[e] = bv[e] + wv[2][e] * xv[e]; }
; #pragma unroll
;             for (int d = 1; d <= 2; ++d) {
;                 const bool own = (rl + d <= 7); const int src = (lane + 64 - 8 * d) & 63;
;                 const u32x4 sg = own ? cgv : pg, sv = own ? cvv : pv;
;                 u32x4 g, v; g.x = __shfl(sg.x, src); g.y = __shfl(sg.y, src); g.z = __shfl(sg.z, src); g.w = __shfl(sg.w, src);
;                 v.x = __shfl(sv.x, src); v.y = __shfl(sv.y, src); v.z = __shfl(sv.z, src); v.w = __shfl(sv.w, src);
;                 float dg[8], dv[8]; unpack8(g, dg); unpack8(v, dv);
; #pragma unroll
;                 for (int e = 0; e < 8; ++e) { yg[e] += wg[2 - d][e] * dg[e]; yv[e] += wv[2 - d][e] * dv[e]; }
;             }
; #pragma unroll
;             for (int e = 0; e < 8; ++e) yg[e] = yg[e] * sigm(yg[e]) * yv[e];
;             { const u32x4 o_ = pack8(yg); if (st) *(u32x4*)(h1 + off) = o_; else asm volatile("" :: "v"(o_)); }
;             pg = cgv; pv = cvv;
	v_lshlrev_b32_e32 v92, 16, v153
	v_pk_fma_f32 v[92:93], v[112:113], v[92:93], v[90:91]
	v_and_b32_e32 v91, 0xffff0000, v85
	v_and_b32_e32 v90, 0xffff0000, v89
	v_pk_fma_f32 v[90:91], v[20:21], v[90:91], v[28:29]
	v_and_b32_e32 v143, 0xffff0000, v145
	v_and_b32_e32 v142, 0xffff0000, v150
	v_pk_fma_f32 v[90:91], v[12:13], v[142:143], v[90:91]
	v_and_b32_e32 v143, 0xffff0000, v152
	v_and_b32_e32 v142, 0xffff0000, v153
	v_pk_fma_f32 v[90:91], v[4:5], v[142:143], v[90:91]
	v_mul_f32_e32 v142, 0xbfb8aa3b, v103
	v_exp_f32_e32 v142, v142
	s_mov_b32 s9, 0x4a16000
	v_add_f32_e32 v142, 1.0, v142
	s_nop 0
	v_rcp_f32_e32 v142, v142
	s_nop 0
	v_mul_f32_e32 v103, v103, v142
	v_mul_f32_e32 v102, v102, v103
	v_mul_f32_e32 v103, 0xbfb8aa3b, v105
	v_exp_f32_e32 v103, v103
	s_nop 0
	v_add_f32_e32 v103, 1.0, v103
	s_nop 0
	v_rcp_f32_e32 v103, v103
	s_nop 0
	v_mul_f32_e32 v103, v105, v103
	v_mul_f32_e32 v103, v104, v103
	v_mul_f32_e32 v104, 0xbfb8aa3b, v101
	v_exp_f32_e32 v104, v104
	s_nop 0
	v_add_f32_e32 v104, 1.0, v104
	s_nop 0
	v_rcp_f32_e32 v104, v104
	s_nop 0
	v_mul_f32_e32 v101, v101, v104
	v_mul_f32_e32 v100, v100, v101
	v_mul_f32_e32 v101, 0xbfb8aa3b, v99
	v_exp_f32_e32 v101, v101
	s_nop 0
	v_add_f32_e32 v101, 1.0, v101
	s_nop 0
	v_rcp_f32_e32 v101, v101
	s_nop 0
	v_mul_f32_e32 v99, v99, v101
	v_mul_f32_e32 v98, v98, v99
	v_mul_f32_e32 v99, 0xbfb8aa3b, v97
	v_exp_f32_e32 v99, v99
	s_nop 0
	v_add_f32_e32 v99, 1.0, v99
	s_nop 0
	v_rcp_f32_e32 v99, v99
	s_nop 0
	v_mul_f32_e32 v97, v97, v99
	v_mul_f32_e32 v96, v96, v97
	v_mul_f32_e32 v97, 0xbfb8aa3b, v95
	v_exp_f32_e32 v97, v97
	s_nop 0
	v_add_f32_e32 v97, 1.0, v97
	s_nop 0
	v_rcp_f32_e32 v97, v97
	s_nop 0
	v_mul_f32_e32 v95, v95, v97
	v_mul_f32_e32 v94, v94, v95
	v_mul_f32_e32 v95, 0xbfb8aa3b, v93
	v_exp_f32_e32 v95, v95
	s_nop 0
	v_add_f32_e32 v95, 1.0, v95
	s_nop 0
	v_rcp_f32_e32 v95, v95
	s_nop 0
	v_mul_f32_e32 v93, v93, v95
	v_mul_f32_e32 v93, v92, v93
	v_mul_f32_e32 v92, 0xbfb8aa3b, v91
	v_exp_f32_e32 v92, v92
	s_nop 0
	v_add_f32_e32 v92, 1.0, v92
	s_nop 0
	v_rcp_f32_e32 v92, v92
	s_nop 0
	v_mul_f32_e32 v91, v91, v92
	v_mul_f32_e32 v95, v90, v91
	v_cvt_pk_bf16_f32 v90, v102, v103
	v_cvt_pk_bf16_f32 v91, v100, v98
	v_cvt_pk_bf16_f32 v92, v96, v94
	v_add_co_u32_e32 v94, vcc, s9, v140
	v_cvt_pk_bf16_f32 v93, v93, v95
	v_cndmask_b32_e64 v97, v78, v86, s[40:41]
	s_nop 0
	v_addc_co_u32_e32 v95, vcc, 0, v141, vcc
	global_store_dwordx4 v[94:95], v[90:93], off
	v_cndmask_b32_e64 v86, v86, v78, s[42:43]
	ds_bpermute_b32 v86, v147, v86
	v_cndmask_b32_e64 v90, v77, v85, s[40:41]
	v_cndmask_b32_e64 v93, v74, v82, s[40:41]
	v_cndmask_b32_e64 v92, v75, v83, s[40:41]
	ds_bpermute_b32 v93, v0, v93
	ds_bpermute_b32 v100, v0, v90
	ds_bpermute_b32 v90, v0, v97
	v_cndmask_b32_e64 v82, v82, v74, s[42:43]
	ds_bpermute_b32 v98, v0, v92
	ds_bpermute_b32 v92, v147, v82
	v_cndmask_b32_e64 v83, v83, v75, s[42:43]
	v_cndmask_b32_e64 v91, v76, v84, s[40:41]
	v_cndmask_b32_e64 v85, v85, v77, s[42:43]
	v_cndmask_b32_e64 v84, v84, v76, s[42:43]
	ds_bpermute_b32 v103, v147, v83
	v_lshlrev_b32_e32 v83, 16, v74
	v_lshlrev_b32_e32 v82, 16, v78
	v_cndmask_b32_e64 v96, v79, v87, s[40:41]
	ds_bpermute_b32 v104, v147, v84
	ds_bpermute_b32 v105, v147, v85
	v_pk_fma_f32 v[82:83], v[132:133], v[82:83], v[130:131]
	s_waitcnt lgkmcnt(7)
	v_lshlrev_b32_e32 v85, 16, v93
	s_waitcnt lgkmcnt(5)
	v_lshlrev_b32_e32 v84, 16, v90
	v_cndmask_b32_e64 v94, v81, v89, s[40:41]
	v_cndmask_b32_e64 v95, v80, v88, s[40:41]
	ds_bpermute_b32 v99, v0, v91
	ds_bpermute_b32 v91, v0, v96
	v_cndmask_b32_e64 v87, v87, v79, s[42:43]
	v_pk_fma_f32 v[82:83], v[134:135], v[84:85], v[82:83]
	s_waitcnt lgkmcnt(5)
	v_lshlrev_b32_e32 v85, 16, v92
	v_lshlrev_b32_e32 v84, 16, v86
	ds_bpermute_b32 v101, v0, v95
	ds_bpermute_b32 v102, v0, v94
	ds_bpermute_b32 v87, v147, v87
	v_pk_fma_f32 v[94:95], v[136:137], v[84:85], v[82:83]
	v_and_b32_e32 v83, 0xffff0000, v74
	v_and_b32_e32 v82, 0xffff0000, v78
	v_pk_fma_f32 v[82:83], v[22:23], v[82:83], v[30:31]
	v_and_b32_e32 v85, 0xffff0000, v93
	v_and_b32_e32 v84, 0xffff0000, v90
	v_pk_fma_f32 v[82:83], v[14:15], v[84:85], v[82:83]
	v_and_b32_e32 v85, 0xffff0000, v92
	v_and_b32_e32 v84, 0xffff0000, v86
	v_pk_fma_f32 v[96:97], v[6:7], v[84:85], v[82:83]
	v_lshlrev_b32_e32 v83, 16, v75
	v_lshlrev_b32_e32 v82, 16, v79
	v_pk_fma_f32 v[82:83], v[124:125], v[82:83], v[122:123]
	v_lshlrev_b32_e32 v85, 16, v98
	s_waitcnt lgkmcnt(3)
	v_lshlrev_b32_e32 v84, 16, v91
	v_cndmask_b32_e64 v88, v88, v80, s[42:43]
	v_pk_fma_f32 v[82:83], v[126:127], v[84:85], v[82:83]
	v_lshlrev_b32_e32 v85, 16, v103
	s_waitcnt lgkmcnt(0)
	v_lshlrev_b32_e32 v84, 16, v87
	ds_bpermute_b32 v142, v147, v88
	v_pk_fma_f32 v[92:93], v[128:129], v[84:85], v[82:83]
	v_and_b32_e32 v83, 0xffff0000, v75
	v_and_b32_e32 v82, 0xffff0000, v79
	v_pk_fma_f32 v[82:83], v[24:25], v[82:83], v[32:33]
	v_and_b32_e32 v85, 0xffff0000, v98
	v_and_b32_e32 v84, 0xffff0000, v91
	v_pk_fma_f32 v[82:83], v[16:17], v[84:85], v[82:83]
	v_and_b32_e32 v85, 0xffff0000, v103
	v_and_b32_e32 v84, 0xffff0000, v87
	v_pk_fma_f32 v[90:91], v[8:9], v[84:85], v[82:83]
	v_lshlrev_b32_e32 v83, 16, v76
	v_lshlrev_b32_e32 v82, 16, v80
	v_pk_fma_f32 v[82:83], v[116:117], v[82:83], v[114:115]
	v_lshlrev_b32_e32 v85, 16, v99
	v_lshlrev_b32_e32 v84, 16, v101
	v_cndmask_b32_e64 v89, v89, v81, s[42:43]
	v_pk_fma_f32 v[82:83], v[118:119], v[84:85], v[82:83]
	v_lshlrev_b32_e32 v85, 16, v104
	s_waitcnt lgkmcnt(0)
; __device__ __forceinline__ float sigm(float x) { return 1.f / (1.f + __expf(-x)); }
; __device__ __forceinline__ u32x4 pack8(const float (&f)[8]) { u32x4 w; w.x = pk2(f[0], f[1]); w.y = pk2(f[2], f[3]); w.z = pk2(f[4], f[5]); w.w = pk2(f[6], f[7]); return w; }
; __device__ __forceinline__ void ffn_conv_item(int tid_in, int b, int strip, bf16_t* h1, const bf16_t* h2, const float* cw, const float* cb, bool st = true) {
;     ...
;         for (int j = 0; j < 4; ++j) {
;             const size_t off = off0 + (size_t)(32 * blk + 8 * j + rl) * 5632;
;             const u32x4 cgv = cg4[j], cvv = cv4[j];
;             float xg[8], xv[8], yg[8], yv[8]; unpack8(cgv, xg); unpack8(cvv, xv);
; #pragma unroll
;             for (int e = 0; e < 8; ++e) { yg[e] = bg[e] + wg[2][e] * xg[e]; yv[e] = bv[e] + wv[2][e] * xv[e]; }
; #pragma unroll
;             for (int d = 1; d <= 2; ++d) {
;                 const bool own = (rl + d <= 7); const int src = (lane + 64 - 8 * d) & 63;
;                 const u32x4 sg = own ? cgv : pg, sv = own ? cvv : pv;
;                 u32x4 g, v; g.x = __shfl(sg.x, src); g.y = __shfl(sg.y, src); g.z = __shfl(sg.z, src); g.w = __shfl(sg.w, src);
;                 v.x = __shfl(sv.x, src); v.y = __shfl(sv.y, src); v.z = __shfl(sv.z, src); v.w = __shfl(sv.w, src);
;                 float dg[8], dv[8]; unpack8(g, dg); unpack8(v, dv);
; #pragma unroll
;                 for (int e = 0; e < 8; ++e) { yg[e] += wg[2 - d][e] * dg[e]; yv[e] += wv[2 - d][e] * dv[e]; }
;             }
; #pragma unroll
;             for (int e = 0; e < 8; ++e) yg[e] = yg[e] * sigm(yg[e]) * yv[e];
;             { const u32x4 o_ = pack8(yg); if (st) *(u32x4*)(h1 + off) = o_; else asm volatile("" :: "v"(o_)); }
;             pg = cgv; pv = cvv;
	v_lshlrev_b32_e32 v84, 16, v142
	ds_bpermute_b32 v143, v147, v89
	v_pk_fma_f32 v[88:89], v[120:121], v[84:85], v[82:83]
	v_and_b32_e32 v83, 0xffff0000, v76
	v_and_b32_e32 v82, 0xffff0000, v80
	v_pk_fma_f32 v[82:83], v[18:19], v[82:83], v[26:27]
	v_and_b32_e32 v85, 0xffff0000, v99
	v_and_b32_e32 v84, 0xffff0000, v101
	v_pk_fma_f32 v[82:83], v[10:11], v[84:85], v[82:83]
	v_and_b32_e32 v85, 0xffff0000, v104
	v_and_b32_e32 v84, 0xffff0000, v142
	v_pk_fma_f32 v[86:87], v[2:3], v[84:85], v[82:83]
	v_lshlrev_b32_e32 v83, 16, v77
	v_lshlrev_b32_e32 v82, 16, v81
	v_pk_fma_f32 v[82:83], v[108:109], v[82:83], v[106:107]
	v_lshlrev_b32_e32 v85, 16, v100
	v_lshlrev_b32_e32 v84, 16, v102
	v_pk_fma_f32 v[82:83], v[110:111], v[84:85], v[82:83]
	v_lshlrev_b32_e32 v85, 16, v105
	s_waitcnt lgkmcnt(0)
	v_lshlrev_b32_e32 v84, 16, v143
	v_pk_fma_f32 v[84:85], v[112:113], v[84:85], v[82:83]
	v_and_b32_e32 v83, 0xffff0000, v77
	v_and_b32_e32 v82, 0xffff0000, v81
	v_pk_fma_f32 v[82:83], v[20:21], v[82:83], v[28:29]
	v_and_b32_e32 v99, 0xffff0000, v100
	v_and_b32_e32 v98, 0xffff0000, v102
	v_pk_fma_f32 v[82:83], v[12:13], v[98:99], v[82:83]
	v_and_b32_e32 v99, 0xffff0000, v105
	v_and_b32_e32 v98, 0xffff0000, v143
	v_pk_fma_f32 v[82:83], v[4:5], v[98:99], v[82:83]
	v_mul_f32_e32 v98, 0xbfb8aa3b, v95
	v_exp_f32_e32 v98, v98
	s_mov_b32 s9, 0x4a2c000
	v_add_f32_e32 v98, 1.0, v98
	s_nop 0
	v_rcp_f32_e32 v98, v98
	s_nop 0
	v_mul_f32_e32 v95, v95, v98
	v_mul_f32_e32 v94, v94, v95
	v_mul_f32_e32 v95, 0xbfb8aa3b, v97
	v_exp_f32_e32 v95, v95
	s_nop 0
	v_add_f32_e32 v95, 1.0, v95
	s_nop 0
	v_rcp_f32_e32 v95, v95
	s_nop 0
	v_mul_f32_e32 v95, v97, v95
	v_mul_f32_e32 v95, v96, v95
	v_mul_f32_e32 v96, 0xbfb8aa3b, v93
	v_exp_f32_e32 v96, v96
	s_nop 0
	v_add_f32_e32 v96, 1.0, v96
	s_nop 0
	v_rcp_f32_e32 v96, v96
	s_nop 0
	v_mul_f32_e32 v93, v93, v96
	v_mul_f32_e32 v92, v92, v93
	v_mul_f32_e32 v93, 0xbfb8aa3b, v91
	v_exp_f32_e32 v93, v93
	s_nop 0
	v_add_f32_e32 v93, 1.0, v93
	s_nop 0
	v_rcp_f32_e32 v93, v93
	s_nop 0
	v_mul_f32_e32 v91, v91, v93
	v_mul_f32_e32 v90, v90, v91
	v_mul_f32_e32 v91, 0xbfb8aa3b, v89
	v_exp_f32_e32 v91, v91
	s_nop 0
	v_add_f32_e32 v91, 1.0, v91
	s_nop 0
	v_rcp_f32_e32 v91, v91
	s_nop 0
	v_mul_f32_e32 v89, v89, v91
	v_mul_f32_e32 v88, v88, v89
	v_mul_f32_e32 v89, 0xbfb8aa3b, v87
	v_exp_f32_e32 v89, v89
	s_nop 0
	v_add_f32_e32 v89, 1.0, v89
	s_nop 0
	v_rcp_f32_e32 v89, v89
	s_nop 0
	v_mul_f32_e32 v87, v87, v89
	v_mul_f32_e32 v86, v86, v87
	v_mul_f32_e32 v87, 0xbfb8aa3b, v85
	v_exp_f32_e32 v87, v87
	s_nop 0
	v_add_f32_e32 v87, 1.0, v87
	s_nop 0
	v_rcp_f32_e32 v87, v87
	s_nop 0
	v_mul_f32_e32 v85, v85, v87
	v_mul_f32_e32 v85, v84, v85
	v_mul_f32_e32 v84, 0xbfb8aa3b, v83
	v_exp_f32_e32 v84, v84
	s_nop 0
	v_add_f32_e32 v84, 1.0, v84
	s_nop 0
	v_rcp_f32_e32 v84, v84
	s_nop 0
	v_mul_f32_e32 v83, v83, v84
	v_mul_f32_e32 v87, v82, v83
	v_cvt_pk_bf16_f32 v82, v94, v95
	v_cvt_pk_bf16_f32 v83, v92, v90
	v_cvt_pk_bf16_f32 v84, v88, v86
	v_add_co_u32_e32 v86, vcc, s9, v140
	v_cvt_pk_bf16_f32 v85, v85, v87
	s_waitcnt vmcnt(2)
	v_cndmask_b32_e64 v89, v70, v78, s[40:41]
	v_addc_co_u32_e32 v87, vcc, 0, v141, vcc
	global_store_dwordx4 v[86:87], v[82:85], off
	v_cndmask_b32_e64 v78, v78, v70, s[42:43]
	ds_bpermute_b32 v78, v147, v78
	v_cndmask_b32_e64 v82, v49, v77, s[40:41]
	v_cndmask_b32_e64 v85, v46, v74, s[40:41]
	v_cndmask_b32_e64 v83, v48, v76, s[40:41]
	ds_bpermute_b32 v94, v0, v85
	ds_bpermute_b32 v97, v0, v82
	ds_bpermute_b32 v82, v0, v89
	v_cndmask_b32_e64 v74, v74, v46, s[42:43]
	ds_bpermute_b32 v96, v0, v83
	ds_bpermute_b32 v83, v147, v74
	v_cndmask_b32_e64 v84, v47, v75, s[40:41]
	v_cndmask_b32_e64 v75, v75, v47, s[42:43]
	v_cndmask_b32_e64 v77, v77, v49, s[42:43]
	v_cndmask_b32_e64 v76, v76, v48, s[42:43]
	ds_bpermute_b32 v99, v147, v75
	v_lshlrev_b32_e32 v75, 16, v46
	v_lshlrev_b32_e32 v74, 16, v70
	v_cndmask_b32_e64 v88, v71, v79, s[40:41]
	ds_bpermute_b32 v100, v147, v76
	ds_bpermute_b32 v101, v147, v77
	v_pk_fma_f32 v[74:75], v[132:133], v[74:75], v[130:131]
	s_waitcnt lgkmcnt(7)
	v_lshlrev_b32_e32 v77, 16, v94
	s_waitcnt lgkmcnt(5)
	v_lshlrev_b32_e32 v76, 16, v82
	ds_bpermute_b32 v95, v0, v84
	ds_bpermute_b32 v88, v0, v88
	v_cndmask_b32_e64 v79, v79, v71, s[42:43]
	v_pk_fma_f32 v[74:75], v[134:135], v[76:77], v[74:75]
	s_waitcnt lgkmcnt(5)
	v_lshlrev_b32_e32 v77, 16, v83
	v_lshlrev_b32_e32 v76, 16, v78
	ds_bpermute_b32 v79, v147, v79
	v_pk_fma_f32 v[84:85], v[136:137], v[76:77], v[74:75]
	v_and_b32_e32 v75, 0xffff0000, v46
	v_and_b32_e32 v74, 0xffff0000, v70
	v_pk_fma_f32 v[74:75], v[22:23], v[74:75], v[30:31]
	v_and_b32_e32 v77, 0xffff0000, v94
	v_and_b32_e32 v76, 0xffff0000, v82
	v_cndmask_b32_e64 v86, v73, v81, s[40:41]
	v_cndmask_b32_e64 v87, v72, v80, s[40:41]
	v_pk_fma_f32 v[74:75], v[14:15], v[76:77], v[74:75]
	v_and_b32_e32 v77, 0xffff0000, v83
	v_and_b32_e32 v76, 0xffff0000, v78
	ds_bpermute_b32 v89, v0, v87
	ds_bpermute_b32 v98, v0, v86
	v_pk_fma_f32 v[86:87], v[6:7], v[76:77], v[74:75]
	v_lshlrev_b32_e32 v75, 16, v47
	v_lshlrev_b32_e32 v74, 16, v71
	v_pk_fma_f32 v[74:75], v[124:125], v[74:75], v[122:123]
	s_waitcnt lgkmcnt(4)
	v_lshlrev_b32_e32 v77, 16, v95
	s_waitcnt lgkmcnt(3)
	v_lshlrev_b32_e32 v76, 16, v88
	v_cndmask_b32_e64 v80, v80, v72, s[42:43]
	v_pk_fma_f32 v[74:75], v[126:127], v[76:77], v[74:75]
	v_lshlrev_b32_e32 v77, 16, v99
	s_waitcnt lgkmcnt(2)
; __device__ __forceinline__ float sigm(float x) { return 1.f / (1.f + __expf(-x)); }
; __device__ __forceinline__ u32x4 pack8(const float (&f)[8]) { u32x4 w; w.x = pk2(f[0], f[1]); w.y = pk2(f[2], f[3]); w.z = pk2(f[4], f[5]); w.w = pk2(f[6], f[7]); return w; }
; __device__ __forceinline__ void ffn_conv_item(int tid_in, int b, int strip, bf16_t* h1, const bf16_t* h2, const float* cw, const float* cb, bool st = true) {
;     ...
;         for (int j = 0; j < 4; ++j) {
;             const size_t off = off0 + (size_t)(32 * blk + 8 * j + rl) * 5632;
;             const u32x4 cgv = cg4[j], cvv = cv4[j];
;             float xg[8], xv[8], yg[8], yv[8]; unpack8(cgv, xg); unpack8(cvv, xv);
; #pragma unroll
;             for (int e = 0; e < 8; ++e) { yg[e] = bg[e] + wg[2][e] * xg[e]; yv[e] = bv[e] + wv[2][e] * xv[e]; }
; #pragma unroll
;             for (int d = 1; d <= 2; ++d) {
;                 const bool own = (rl + d <= 7); const int src = (lane + 64 - 8 * d) & 63;
;                 const u32x4 sg = own ? cgv : pg, sv = own ? cvv : pv;
;                 u32x4 g, v; g.x = __shfl(sg.x, src); g.y = __shfl(sg.y, src); g.z = __shfl(sg.z, src); g.w = __shfl(sg.w, src);
;                 v.x = __shfl(sv.x, src); v.y = __shfl(sv.y, src); v.z = __shfl(sv.z, src); v.w = __shfl(sv.w, src);
;                 float dg[8], dv[8]; unpack8(g, dg); unpack8(v, dv);
; #pragma unroll
;                 for (int e = 0; e < 8; ++e) { yg[e] += wg[2 - d][e] * dg[e]; yv[e] += wv[2 - d][e] * dv[e]; }
;             }
; #pragma unroll
;             for (int e = 0; e < 8; ++e) yg[e] = yg[e] * sigm(yg[e]) * yv[e];
;             { const u32x4 o_ = pack8(yg); if (st) *(u32x4*)(h1 + off) = o_; else asm volatile("" :: "v"(o_)); }
;             pg = cgv; pv = cvv;
;         }
; #pragma unroll
;         for (int j = 0; j < 4; ++j) { cg4[j] = ng4[j]; cv4[j] = nv4[j]; }
	v_lshlrev_b32_e32 v76, 16, v79
	v_mov_b64_e32 v[92:93], v[72:73]
	ds_bpermute_b32 v102, v147, v80
	v_pk_fma_f32 v[82:83], v[128:129], v[76:77], v[74:75]
	v_and_b32_e32 v75, 0xffff0000, v47
	v_and_b32_e32 v74, 0xffff0000, v71
	v_mov_b64_e32 v[90:91], v[70:71]
	v_pk_fma_f32 v[70:71], v[24:25], v[74:75], v[32:33]
	v_and_b32_e32 v75, 0xffff0000, v95
	v_and_b32_e32 v74, 0xffff0000, v88
	v_cndmask_b32_e64 v81, v81, v73, s[42:43]
	v_pk_fma_f32 v[70:71], v[16:17], v[74:75], v[70:71]
	v_and_b32_e32 v75, 0xffff0000, v99
	v_and_b32_e32 v74, 0xffff0000, v79
	ds_bpermute_b32 v103, v147, v81
	v_pk_fma_f32 v[80:81], v[8:9], v[74:75], v[70:71]
	v_lshlrev_b32_e32 v71, 16, v48
	v_lshlrev_b32_e32 v70, 16, v72
	v_pk_fma_f32 v[70:71], v[116:117], v[70:71], v[114:115]
	v_lshlrev_b32_e32 v75, 16, v96
	s_waitcnt lgkmcnt(3)
	v_lshlrev_b32_e32 v74, 16, v89
	v_pk_fma_f32 v[70:71], v[118:119], v[74:75], v[70:71]
	v_lshlrev_b32_e32 v75, 16, v100
	s_waitcnt lgkmcnt(1)
	v_lshlrev_b32_e32 v74, 16, v102
	v_pk_fma_f32 v[78:79], v[120:121], v[74:75], v[70:71]
	v_and_b32_e32 v71, 0xffff0000, v48
	v_and_b32_e32 v70, 0xffff0000, v72
	v_pk_fma_f32 v[70:71], v[18:19], v[70:71], v[26:27]
	v_and_b32_e32 v75, 0xffff0000, v96
	v_and_b32_e32 v74, 0xffff0000, v89
	v_pk_fma_f32 v[70:71], v[10:11], v[74:75], v[70:71]
	v_and_b32_e32 v75, 0xffff0000, v100
	v_and_b32_e32 v74, 0xffff0000, v102
	v_pk_fma_f32 v[76:77], v[2:3], v[74:75], v[70:71]
	v_lshlrev_b32_e32 v71, 16, v49
	v_lshlrev_b32_e32 v70, 16, v73
	v_pk_fma_f32 v[70:71], v[108:109], v[70:71], v[106:107]
	v_lshlrev_b32_e32 v75, 16, v97
	v_lshlrev_b32_e32 v74, 16, v98
	v_pk_fma_f32 v[70:71], v[110:111], v[74:75], v[70:71]
	v_lshlrev_b32_e32 v75, 16, v101
	s_waitcnt lgkmcnt(0)
	v_lshlrev_b32_e32 v74, 16, v103
	v_pk_fma_f32 v[74:75], v[112:113], v[74:75], v[70:71]
	v_and_b32_e32 v71, 0xffff0000, v49
	v_and_b32_e32 v70, 0xffff0000, v73
	v_pk_fma_f32 v[70:71], v[20:21], v[70:71], v[28:29]
	v_and_b32_e32 v73, 0xffff0000, v97
	v_and_b32_e32 v72, 0xffff0000, v98
	v_pk_fma_f32 v[70:71], v[12:13], v[72:73], v[70:71]
	v_and_b32_e32 v73, 0xffff0000, v101
	v_and_b32_e32 v72, 0xffff0000, v103
	v_pk_fma_f32 v[70:71], v[4:5], v[72:73], v[70:71]
	v_mul_f32_e32 v72, 0xbfb8aa3b, v85
	v_exp_f32_e32 v72, v72
	v_mov_b64_e32 v[100:101], v[44:45]
	v_mov_b64_e32 v[104:105], v[48:49]
	v_mov_b64_e32 v[98:99], v[42:43]
	v_add_f32_e32 v72, 1.0, v72
	v_mov_b64_e32 v[102:103], v[46:47]
	v_rcp_f32_e32 v72, v72
	s_nop 0
	v_mul_f32_e32 v73, 0xbfb8aa3b, v87
	v_exp_f32_e32 v73, v73
	v_mul_f32_e32 v72, v85, v72
	v_mul_f32_e32 v72, v84, v72
	v_add_f32_e32 v73, 1.0, v73
	s_nop 0
	v_rcp_f32_e32 v73, v73
	s_nop 0
	v_mul_f32_e32 v84, 0xbfb8aa3b, v83
	v_exp_f32_e32 v84, v84
	v_mul_f32_e32 v73, v87, v73
	v_mul_f32_e32 v73, v86, v73
	v_mov_b64_e32 v[96:97], v[40:41]
	v_add_f32_e32 v84, 1.0, v84
	v_mov_b64_e32 v[94:95], v[38:39]
	v_rcp_f32_e32 v84, v84
	s_nop 0
	v_mul_f32_e32 v83, v83, v84
	v_mul_f32_e32 v82, v82, v83
	v_mul_f32_e32 v83, 0xbfb8aa3b, v81
	v_exp_f32_e32 v83, v83
	s_nop 0
	v_add_f32_e32 v83, 1.0, v83
	s_nop 0
	v_rcp_f32_e32 v83, v83
	s_nop 0
	v_mul_f32_e32 v81, v81, v83
	v_mul_f32_e32 v80, v80, v81
	v_mul_f32_e32 v81, 0xbfb8aa3b, v79
	v_exp_f32_e32 v81, v81
	s_nop 0
	v_add_f32_e32 v81, 1.0, v81
	s_nop 0
	v_rcp_f32_e32 v81, v81
	s_nop 0
	v_mul_f32_e32 v79, v79, v81
	v_mul_f32_e32 v78, v78, v79
	v_mul_f32_e32 v79, 0xbfb8aa3b, v77
	v_exp_f32_e32 v79, v79
	s_nop 0
	v_add_f32_e32 v79, 1.0, v79
	s_nop 0
	v_rcp_f32_e32 v79, v79
	s_nop 0
	v_mul_f32_e32 v77, v77, v79
	v_mul_f32_e32 v76, v76, v77
	v_mul_f32_e32 v77, 0xbfb8aa3b, v75
	v_exp_f32_e32 v77, v77
	v_mov_b64_e32 v[88:89], v[56:57]
	v_mov_b64_e32 v[86:87], v[54:55]
	v_add_f32_e32 v77, 1.0, v77
	s_nop 0
	v_rcp_f32_e32 v77, v77
	s_nop 0
	v_mul_f32_e32 v75, v75, v77
	v_mul_f32_e32 v74, v74, v75
	v_mul_f32_e32 v75, 0xbfb8aa3b, v71
	v_exp_f32_e32 v75, v75
	s_nop 0
	v_add_f32_e32 v75, 1.0, v75
	s_nop 0
	v_rcp_f32_e32 v75, v75
	s_nop 0
	v_mul_f32_e32 v71, v71, v75
	v_mul_f32_e32 v75, v70, v71
	v_cvt_pk_bf16_f32 v70, v72, v73
	v_cvt_pk_bf16_f32 v71, v82, v80
	v_cvt_pk_bf16_f32 v72, v78, v76
	v_cvt_pk_bf16_f32 v73, v74, v75
	v_add_co_u32_e32 v74, vcc, 0x4a42000, v140
	v_mov_b64_e32 v[84:85], v[52:53]
	s_nop 0
	v_addc_co_u32_e32 v75, vcc, 0, v141, vcc
	global_store_dwordx4 v[74:75], v[70:73], off
	v_mov_b64_e32 v[76:77], v[60:61]
	v_mov_b64_e32 v[80:81], v[64:65]
	v_mov_b64_e32 v[72:73], v[68:69]
	v_mov_b64_e32 v[74:75], v[58:59]
	v_mov_b64_e32 v[82:83], v[50:51]
	v_mov_b64_e32 v[70:71], v[66:67]
	v_mov_b64_e32 v[78:79], v[62:63]
	s_cbranch_scc0 .LBB0_17
; __device__ __forceinline__ void ffn_conv_item(int tid_in, int b, int strip, bf16_t* h1, const bf16_t* h2, const float* cw, const float* cb, bool st = true) {
;     ...
;     for (int blk = 0; blk < 16; ++blk) {
;         u32x4 ng4[4], nv4[4];
;         if (blk + 1 < 16) {
; #pragma unroll
;             for (int j = 0; j < 4; ++j) { const size_t o_ = off0 + (size_t)(32 * (blk + 1) + 8 * j + rl) * 5632; ng4[j] = __builtin_nontemporal_load((const u32x4*)(h1 + o_)); nv4[j] = __builtin_nontemporal_load((const u32x4*)(h2 + o_)); }
;         }
.LBB0_25:
	s_waitcnt vmcnt(1)
	v_mov_b64_e32 v[48:49], v[36:37]
	v_mov_b64_e32 v[46:47], v[34:35]
	s_cmp_eq_u32 s34, 0x528000
	v_lshl_add_u64 v[140:141], v[138:139], 0, s[34:35]
	s_cbranch_scc1 .LBB0_24
	v_add_co_u32_e32 v34, vcc, 0x4a58000, v140
	s_nop 1
	v_addc_co_u32_e32 v35, vcc, 0, v141, vcc
	v_add_co_u32_e32 v36, vcc, 0xfa58000, v140
	s_nop 1
	v_addc_co_u32_e32 v37, vcc, 0, v141, vcc
	global_load_dwordx4 v[38:41], v[34:35], off nt
	global_load_dwordx4 v[42:45], v[36:37], off nt
	v_add_co_u32_e32 v34, vcc, 0x4a6e000, v140
	s_nop 1
	v_addc_co_u32_e32 v35, vcc, 0, v141, vcc
	v_add_co_u32_e32 v36, vcc, 0xfa6e000, v140
	s_nop 1
	v_addc_co_u32_e32 v37, vcc, 0, v141, vcc
	global_load_dwordx4 v[50:53], v[34:35], off nt
	global_load_dwordx4 v[54:57], v[36:37], off nt
	v_add_co_u32_e32 v34, vcc, 0x4a84000, v140
	s_nop 1
	v_addc_co_u32_e32 v35, vcc, 0, v141, vcc
	v_add_co_u32_e32 v36, vcc, 0xfa84000, v140
	s_nop 1
	v_addc_co_u32_e32 v37, vcc, 0, v141, vcc
	global_load_dwordx4 v[58:61], v[34:35], off nt
	global_load_dwordx4 v[62:65], v[36:37], off nt
	v_add_co_u32_e32 v34, vcc, 0x4a9a000, v140
	s_nop 1
	v_addc_co_u32_e32 v35, vcc, 0, v141, vcc
	v_add_co_u32_e32 v66, vcc, 0xfa9a000, v140
	s_nop 1
	v_addc_co_u32_e32 v67, vcc, 0, v141, vcc
	global_load_dwordx4 v[34:37], v[34:35], off nt
	s_nop 0
	global_load_dwordx4 v[66:69], v[66:67], off nt
	s_branch .LBB0_24
	s_nop 0
	s_nop 0
	s_nop 0
	s_nop 0
	s_nop 0
	s_nop 0
	s_nop 0
	s_nop 0
	s_nop 0
	s_nop 0
	s_nop 0
	s_nop 0
	s_nop 0
	s_nop 0
	s_nop 0
	s_nop 0
	s_nop 0
	s_nop 0
	s_nop 0
	s_nop 0
	s_nop 0
	s_nop 0
	s_nop 0
	s_nop 0
	s_nop 0
	s_nop 0
	s_nop 0
	s_nop 0
	s_nop 0
	s_nop 0
	s_nop 0
	s_nop 0
	s_nop 0
	s_nop 0
	s_nop 0
	s_nop 0
	s_nop 0
	s_nop 0
	s_nop 0
	s_nop 0
	s_nop 0
	s_nop 0
	s_nop 0
	s_nop 0
	s_nop 0
	s_nop 0
	s_nop 0
	s_nop 0
	s_nop 0
	s_nop 0
	s_nop 0
	s_nop 0
	s_nop 0
	s_nop 0
	s_nop 0
	s_nop 0
	s_nop 0
	s_nop 0
	s_nop 0
	s_nop 0
	s_nop 0
	s_nop 0
	s_nop 0
	s_nop 0
	s_nop 0
	s_nop 0
	s_nop 0
	s_nop 0
	s_nop 0
	s_nop 0
	s_nop 0
	s_nop 0
	s_nop 0
	s_nop 0
	s_nop 0
	s_nop 0
	s_nop 0
	s_nop 0
	s_nop 0
	s_nop 0
	s_nop 0
	s_nop 0
	s_nop 0
	s_nop 0
	s_nop 0
	s_nop 0
	s_nop 0
	s_nop 0
	s_nop 0
	s_nop 0
	s_nop 0
	s_nop 0
	s_nop 0
	s_nop 0
	s_nop 0
	s_nop 0
	s_nop 0
	s_nop 0
	s_nop 0
	s_nop 0
	s_nop 0
	s_nop 0
	s_nop 0
	s_nop 0
	s_nop 0
	s_nop 0
	s_nop 0
	s_nop 0
	s_nop 0
	s_nop 0
	s_nop 0
	s_nop 0
	s_nop 0
	s_nop 0
	s_nop 0
	s_nop 0
	s_nop 0
	s_nop 0
	s_nop 0
	s_nop 0
	s_nop 0
	s_nop 0
	s_nop 0
	s_nop 0
	s_nop 0
	s_nop 0
	s_nop 0
	s_nop 0
	s_nop 0
	s_nop 0
	s_nop 0
	s_nop 0
	s_nop 0
	s_nop 0
	s_nop 0
	s_nop 0
	s_nop 0
	s_nop 0
	s_nop 0
	s_nop 0
	s_nop 0
	s_nop 0
	s_nop 0
	s_nop 0
	s_nop 0
	s_nop 0
	s_nop 0
	s_nop 0
	s_nop 0
	s_nop 0
	s_nop 0
	s_nop 0
	s_nop 0
	s_nop 0
	s_nop 0
	s_nop 0
	s_nop 0
	s_nop 0
	s_nop 0
	s_nop 0
	s_nop 0
	s_nop 0
	s_nop 0
	s_nop 0
	s_nop 0
	s_nop 0
	s_nop 0
	s_nop 0
	s_nop 0
	s_nop 0
	s_nop 0
	s_nop 0
	s_nop 0
	s_nop 0
	s_nop 0
	s_nop 0
	s_nop 0
	s_nop 0
	s_nop 0
	s_nop 0
	s_nop 0
	s_nop 0
	s_nop 0
	s_nop 0
	s_nop 0
	s_nop 0
	s_nop 0
	s_nop 0
	s_nop 0
	s_nop 0
	s_nop 0
	s_nop 0
	s_nop 0
	s_nop 0
	s_nop 0
	s_nop 0
	s_nop 0
	s_nop 0
	s_nop 0
	s_nop 0
	s_nop 0
	s_nop 0
	s_nop 0
	s_nop 0
	s_nop 0
	s_nop 0
	s_nop 0
	s_nop 0
	s_nop 0
	s_nop 0
	s_nop 0
	s_nop 0
	s_nop 0
	s_nop 0
	s_nop 0
	s_nop 0
	s_nop 0
	s_nop 0
	s_nop 0
	s_nop 0
	s_nop 0
	s_nop 0
	s_nop 0
	s_nop 0
	s_nop 0
	s_nop 0
	s_nop 0
	s_nop 0
	s_nop 0
	s_nop 0
	s_nop 0
	s_nop 0
	s_nop 0
	s_nop 0
	s_nop 0
	s_nop 0
	s_nop 0
	s_nop 0
	s_nop 0
	s_nop 0
	s_nop 0
	s_nop 0
	s_nop 0
	s_nop 0
	s_nop 0
	s_nop 0
	s_nop 0
	s_nop 0
	s_nop 0
	s_nop 0
	s_nop 0
	s_nop 0
	s_nop 0
	s_nop 0
	s_nop 0
	s_nop 0
	s_nop 0
	s_nop 0
	s_nop 0
	s_nop 0
	s_nop 0
	s_nop 0
	s_nop 0
	s_nop 0
	s_nop 0
	s_nop 0
	s_nop 0
	s_nop 0
	s_nop 0
	s_nop 0
	s_nop 0
	s_nop 0
	s_nop 0
	s_nop 0
	s_nop 0
	s_nop 0
	s_nop 0
	s_nop 0
	s_nop 0
	s_nop 0
	s_nop 0
	s_nop 0
	s_nop 0
	s_nop 0
	s_nop 0
	s_nop 0
	s_nop 0
	s_nop 0
	s_nop 0
	s_nop 0
	s_nop 0
	s_nop 0
	s_nop 0
	s_nop 0
	s_nop 0
	s_nop 0
	s_nop 0
	s_nop 0
	s_nop 0
	s_nop 0
	s_nop 0
	s_nop 0
	s_nop 0
	s_nop 0
	s_nop 0
	s_nop 0
	s_nop 0
	s_nop 0
	s_nop 0
	s_nop 0
	s_nop 0
	s_nop 0
	s_nop 0
	s_nop 0
	s_nop 0
	s_nop 0
	s_nop 0
	s_nop 0
	s_nop 0
	s_nop 0
	s_nop 0
	s_nop 0
	s_nop 0
	s_nop 0
	s_nop 0
	s_nop 0
	s_nop 0
	s_nop 0
	s_nop 0
	s_nop 0
	s_nop 0
	s_nop 0
	s_nop 0
	s_nop 0
	s_nop 0
	s_nop 0
	s_nop 0
	s_nop 0
	s_nop 0
	s_nop 0
	s_nop 0
	s_nop 0
	s_nop 0
	s_nop 0
	s_nop 0
	s_nop 0
	s_nop 0
	s_nop 0
	s_nop 0
	s_nop 0
	s_nop 0
	s_nop 0
	s_nop 0
	s_nop 0
	s_nop 0
	s_nop 0
	s_nop 0
	s_nop 0
	s_nop 0
	s_nop 0
	s_nop 0
	s_nop 0
	s_nop 0
	s_nop 0
	s_nop 0
	s_nop 0
	s_nop 0
	s_nop 0
	s_nop 0
	s_nop 0
	s_nop 0
	s_nop 0
	s_nop 0
	s_nop 0
	s_nop 0
	s_nop 0
	s_nop 0
	s_nop 0
	s_nop 0
	s_nop 0
	s_nop 0
	s_nop 0
	s_nop 0
	s_nop 0
	s_nop 0
	s_nop 0
	s_nop 0
	s_nop 0
	s_nop 0
	s_nop 0
	s_nop 0
	s_nop 0
	s_nop 0
	s_nop 0
	s_nop 0
	s_nop 0
	s_nop 0
	s_nop 0
	s_nop 0
	s_nop 0
	s_nop 0
	s_nop 0
	s_nop 0
	s_nop 0
	s_nop 0
	s_nop 0
	s_nop 0
	s_nop 0
	s_nop 0
	s_nop 0
	s_nop 0
	s_nop 0
	s_nop 0
	s_nop 0
	s_nop 0
	s_nop 0
	s_nop 0
	s_nop 0
	s_nop 0
	s_nop 0
	s_nop 0
	s_nop 0
	s_nop 0
	s_nop 0
	s_nop 0
	s_nop 0
	s_nop 0
	s_nop 0
	s_nop 0
	s_nop 0
	s_nop 0
	s_nop 0
	s_nop 0
	s_nop 0
	s_nop 0
	s_nop 0
	s_nop 0
	s_nop 0
	s_nop 0
	s_nop 0
	s_nop 0
	s_nop 0
	s_nop 0
	s_nop 0
	s_nop 0
	s_nop 0
	s_nop 0
	s_nop 0
	s_nop 0
	s_nop 0
	s_nop 0
	s_nop 0
	s_nop 0
	s_nop 0
	s_nop 0
	s_nop 0
	s_nop 0
	s_nop 0
	s_nop 0
	s_nop 0
	s_nop 0
	s_nop 0
	s_nop 0
	s_nop 0
	s_nop 0
	s_nop 0
	s_nop 0
	s_nop 0
	s_nop 0
	s_nop 0
	s_nop 0
	s_nop 0
	s_nop 0
	s_nop 0
	s_nop 0
	s_nop 0
	s_nop 0
	s_nop 0
	s_nop 0
	s_nop 0
	s_nop 0
	s_nop 0
	s_nop 0
	s_nop 0
	s_nop 0
	s_nop 0
	s_nop 0
	s_nop 0
	s_nop 0
	s_nop 0
	s_nop 0
	s_nop 0
	s_nop 0
	s_nop 0
	s_nop 0
	s_nop 0
	s_nop 0
	s_nop 0
	s_nop 0
	s_nop 0
	s_nop 0
	s_nop 0
	s_nop 0
	s_nop 0
	s_nop 0
	s_nop 0
	s_nop 0
	s_nop 0
	s_nop 0
	s_nop 0
	s_nop 0
	s_nop 0

; __device__ __forceinline__ float sigm(float x) { return 1.f / (1.f + __expf(-x)); }
;     __device__ __forceinline__ void operator()(const pg8::f32x4 (&acc)[2][2][4][2], const pg8::Unit& u, int wr, int wc, int fr, int fq) const {
;     ...
;             for (int ai = 0; ai < 2; ++ai)
; #pragma unroll
;                 for (int m = 0; m < 4; ++m) {
;                     const int row = rowb + ai * 128 + m * 16;
;                     const float rsv = rs8[ai][m];
;                     float sacc = 0.f;
; #pragma unroll
;                     for (int bj = 0; bj < 2; ++bj) {
;                         float o[8];
; #pragma unroll
;                         for (int n = 0; n < 2; ++n)
; #pragma unroll
;                             for (int j = 0; j < 4; ++j) o[4 * n + j] = acc[ai][bj][m][n][j] * rsv;
;                         if (sig) {
; #pragma unroll
;                             for (int e = 0; e < 8; ++e) o[e] = sigm(o[e]);
;                             if (mode == EM_Z2) { const f32x4 h0 = *(const f32x4*)(gain0 + colb - 2048 + bj * 128 + cl), h1_ = *(const f32x4*)(gain0 + colb - 2048 + bj * 128 + cl + 4);
; #pragma unroll
;                                 for (int e = 0; e < 4; ++e) { o[e] *= h0[e]; o[4 + e] *= h1_[e]; } }
;                         }
.LBB0_350:
	s_xor_b64 s[18:19], s[54:55], -1
	v_add_u32_e32 v180, 0x80, v178
	s_andn2_b64 vcc, exec, s[18:19]
	s_mov_b64 s[18:19], -1
	s_cbranch_vccnz .LBB0_584
	s_ashr_i32 s87, s86, 31
	s_lshl_b64 s[18:19], s[86:87], 2
	s_add_u32 s18, s68, s18
	s_addc_u32 s19, s69, s19
	v_lshlrev_b32_e32 v0, 2, v156
	v_lshl_add_u64 v[130:131], s[18:19], 0, v[0:1]
	s_movk_i32 s18, 0xe000
	s_mov_b32 s19, -1
	v_cndmask_b32_e64 v0, 0, 1, s[22:23]
	v_lshl_add_u64 v[134:135], v[130:131], 0, s[18:19]
	v_pk_mul_f32 v[140:141], v[126:127], v[176:177] op_sel_hi:[1,0]
	v_pk_mul_f32 v[182:183], v[128:129], v[176:177] op_sel_hi:[1,0]
	v_pk_mul_f32 v[144:145], v[122:123], v[176:177] op_sel_hi:[1,0]
	v_pk_mul_f32 v[142:143], v[124:125], v[176:177] op_sel_hi:[1,0]
	s_and_b64 vcc, exec, s[50:51]
	v_cmp_ne_u32_e64 s[44:45], 1, v0
	s_cbranch_vccz .LBB0_354
	v_mul_f32_e32 v0, 0xbfb8aa3b, v140
	v_exp_f32_e32 v130, v0
	v_mul_f32_e32 v0, 0xbfb8aa3b, v141
	v_exp_f32_e32 v131, v0
	s_nop 0
	v_pk_add_f32 v[130:131], v[130:131], 1.0 op_sel_hi:[1,0]
	s_nop 0
	s_nop 0
	v_rcp_f32_e32 v141, v131
	s_nop 0
	s_nop 0
	v_rcp_f32_e32 v140, v130
	s_nop 0
	v_mul_f32_e32 v0, 0xbfb8aa3b, v182
	v_exp_f32_e32 v130, v0
	v_mul_f32_e32 v0, 0xbfb8aa3b, v183
	v_exp_f32_e32 v131, v0
	s_nop 0
	v_pk_add_f32 v[130:131], v[130:131], 1.0 op_sel_hi:[1,0]
	s_nop 0
	s_nop 0
	v_rcp_f32_e32 v183, v131
	s_nop 0
	s_nop 0
	v_rcp_f32_e32 v182, v130
	s_nop 0
	v_mul_f32_e32 v0, 0xbfb8aa3b, v144
	v_exp_f32_e32 v130, v0
	v_mul_f32_e32 v0, 0xbfb8aa3b, v145
	v_exp_f32_e32 v131, v0
	s_nop 0
	v_pk_add_f32 v[130:131], v[130:131], 1.0 op_sel_hi:[1,0]
	s_nop 0
	s_nop 0
	v_rcp_f32_e32 v145, v131
	s_nop 0
	s_nop 0
	v_rcp_f32_e32 v144, v130
	s_nop 0
	v_mul_f32_e32 v0, 0xbfb8aa3b, v142
	v_exp_f32_e32 v130, v0
	v_mul_f32_e32 v0, 0xbfb8aa3b, v143
	v_exp_f32_e32 v131, v0
	s_nop 0
	v_pk_add_f32 v[130:131], v[130:131], 1.0 op_sel_hi:[1,0]
	s_nop 0
	s_nop 0
	v_rcp_f32_e32 v143, v131
	s_nop 0
	s_nop 0
	v_rcp_f32_e32 v142, v130
	s_nop 0
	s_and_b64 vcc, exec, s[44:45]
	s_cbranch_vccnz .LBB0_354
	global_load_dwordx4 v[130:133], v[134:135], off
	global_load_dwordx4 v[136:139], v[134:135], off offset:16
	s_waitcnt vmcnt(1)
	v_pk_mul_f32 v[182:183], v[182:183], v[132:133]
	v_pk_mul_f32 v[140:141], v[140:141], v[130:131]
	s_waitcnt vmcnt(0)
	v_pk_mul_f32 v[142:143], v[142:143], v[138:139]
	v_pk_mul_f32 v[144:145], v[144:145], v[136:137]

; __device__ __forceinline__ float sigm(float x) { return 1.f / (1.f + __expf(-x)); }
;     __device__ __forceinline__ void operator()(const pg8::f32x4 (&acc)[2][2][4][2], const pg8::Unit& u, int wr, int wc, int fr, int fq) const {
;     ...
;                     for (int bj = 0; bj < 2; ++bj) {
;                         float o[8];
; #pragma unroll
;                         for (int n = 0; n < 2; ++n)
; #pragma unroll
;                             for (int j = 0; j < 4; ++j) o[4 * n + j] = acc[ai][bj][m][n][j] * rsv;
;                         if (sig) {
; #pragma unroll
;                             for (int e = 0; e < 8; ++e) o[e] = sigm(o[e]);
;                             if (mode == EM_Z2) { const f32x4 h0 = *(const f32x4*)(gain0 + colb - 2048 + bj * 128 + cl), h1_ = *(const f32x4*)(gain0 + colb - 2048 + bj * 128 + cl + 4);
; #pragma unroll
;                                 for (int e = 0; e < 4; ++e) { o[e] *= h0[e]; o[4 + e] *= h1_[e]; } }
;                         }
.LBB0_360:
	v_mov_b32_e32 v177, v176
	v_cndmask_b32_e64 v0, 0, 1, s[50:51]
	v_pk_mul_f32 v[186:187], v[118:119], v[176:177]
	v_pk_mul_f32 v[190:191], v[120:121], v[176:177]
	v_pk_mul_f32 v[188:189], v[114:115], v[176:177]
	v_cmp_ne_u32_e64 s[48:49], 1, v0
	s_andn2_b64 vcc, exec, s[50:51]
	v_pk_mul_f32 v[192:193], v[116:117], v[176:177]
	global_store_dwordx4 v[184:185], v[130:133], off
	s_cbranch_vccnz .LBB0_363
	v_mul_f32_e32 v0, 0xbfb8aa3b, v186
	v_exp_f32_e32 v130, v0
	v_mul_f32_e32 v0, 0xbfb8aa3b, v187
	v_exp_f32_e32 v131, v0
	s_nop 0
	v_pk_add_f32 v[130:131], v[130:131], 1.0 op_sel_hi:[1,0]
	s_nop 0
	s_nop 0
	v_rcp_f32_e32 v187, v131
	s_nop 0
	s_nop 0
	v_rcp_f32_e32 v186, v130
	s_nop 0
	v_mul_f32_e32 v0, 0xbfb8aa3b, v190
	v_exp_f32_e32 v130, v0
	v_mul_f32_e32 v0, 0xbfb8aa3b, v191
	v_exp_f32_e32 v131, v0
	s_nop 0
	v_pk_add_f32 v[130:131], v[130:131], 1.0 op_sel_hi:[1,0]
	s_nop 0
	s_nop 0
	v_rcp_f32_e32 v191, v131
	s_nop 0
	s_nop 0
	v_rcp_f32_e32 v190, v130
	s_nop 0
	v_mul_f32_e32 v0, 0xbfb8aa3b, v188
	v_exp_f32_e32 v130, v0
	v_mul_f32_e32 v0, 0xbfb8aa3b, v189
	v_exp_f32_e32 v131, v0
	s_nop 0
	v_pk_add_f32 v[130:131], v[130:131], 1.0 op_sel_hi:[1,0]
	s_nop 0
	s_nop 0
	v_rcp_f32_e32 v189, v131
	s_nop 0
	s_nop 0
	v_rcp_f32_e32 v188, v130
	s_nop 0
	v_mul_f32_e32 v0, 0xbfb8aa3b, v192
	v_exp_f32_e32 v130, v0
	v_mul_f32_e32 v0, 0xbfb8aa3b, v193
	v_exp_f32_e32 v131, v0
	s_nop 0
	v_pk_add_f32 v[130:131], v[130:131], 1.0 op_sel_hi:[1,0]
	s_nop 0
	s_nop 0
	v_rcp_f32_e32 v193, v131
	s_nop 0
	s_nop 0
	v_rcp_f32_e32 v192, v130
	s_nop 0
	s_and_b64 vcc, exec, s[44:45]
	s_cbranch_vccnz .LBB0_363
	global_load_dwordx4 v[130:133], v[134:135], off offset:512
	global_load_dwordx4 v[230:233], v[134:135], off offset:528
	s_waitcnt vmcnt(1)
	v_pk_mul_f32 v[190:191], v[190:191], v[132:133]
	v_pk_mul_f32 v[186:187], v[186:187], v[130:131]
	s_waitcnt vmcnt(0)
	v_pk_mul_f32 v[192:193], v[192:193], v[232:233]
	v_pk_mul_f32 v[188:189], v[188:189], v[230:231]

; __device__ __forceinline__ float sigm(float x) { return 1.f / (1.f + __expf(-x)); }
;     __device__ __forceinline__ void operator()(const pg8::f32x4 (&acc)[2][2][4][2], const pg8::Unit& u, int wr, int wc, int fr, int fq) const {
;     ...
;                 for (int m = 0; m < 4; ++m) {
;                     const int row = rowb + ai * 128 + m * 16;
;                     const float rsv = rs8[ai][m];
;                     float sacc = 0.f;
; #pragma unroll
;                     for (int bj = 0; bj < 2; ++bj) {
;                         float o[8];
; #pragma unroll
;                         for (int n = 0; n < 2; ++n)
; #pragma unroll
;                             for (int j = 0; j < 4; ++j) o[4 * n + j] = acc[ai][bj][m][n][j] * rsv;
;                         if (sig) {
; #pragma unroll
;                             for (int e = 0; e < 8; ++e) o[e] = sigm(o[e]);
;                             if (mode == EM_Z2) { const f32x4 h0 = *(const f32x4*)(gain0 + colb - 2048 + bj * 128 + cl), h1_ = *(const f32x4*)(gain0 + colb - 2048 + bj * 128 + cl + 4);
; #pragma unroll
;                                 for (int e = 0; e < 4; ++e) { o[e] *= h0[e]; o[4 + e] *= h1_[e]; } }
;                         }
.LBB0_378:
	v_pk_mul_f32 v[140:141], v[110:111], v[174:175] op_sel_hi:[1,0]
	v_pk_mul_f32 v[182:183], v[112:113], v[174:175] op_sel_hi:[1,0]
	v_pk_mul_f32 v[142:143], v[106:107], v[174:175] op_sel_hi:[1,0]
	s_and_b64 vcc, exec, s[48:49]
	v_pk_mul_f32 v[144:145], v[108:109], v[174:175] op_sel_hi:[1,0]
	s_cbranch_vccnz .LBB0_381
	v_mul_f32_e32 v0, 0xbfb8aa3b, v140
	s_waitcnt lgkmcnt(0)
	v_exp_f32_e32 v130, v0
	v_mul_f32_e32 v0, 0xbfb8aa3b, v141
	v_exp_f32_e32 v131, v0
	s_nop 0
	v_pk_add_f32 v[130:131], v[130:131], 1.0 op_sel_hi:[1,0]
	s_nop 0
	s_nop 0
	v_rcp_f32_e32 v141, v131
	s_nop 0
	s_nop 0
	v_rcp_f32_e32 v140, v130
	s_nop 0
	v_mul_f32_e32 v0, 0xbfb8aa3b, v182
	v_exp_f32_e32 v130, v0
	v_mul_f32_e32 v0, 0xbfb8aa3b, v183
	v_exp_f32_e32 v131, v0
	s_nop 0
	v_pk_add_f32 v[130:131], v[130:131], 1.0 op_sel_hi:[1,0]
	s_nop 0
	s_nop 0
	v_rcp_f32_e32 v183, v131
	s_nop 0
	s_nop 0
	v_rcp_f32_e32 v182, v130
	s_nop 0
	v_mul_f32_e32 v0, 0xbfb8aa3b, v142
	v_exp_f32_e32 v130, v0
	v_mul_f32_e32 v0, 0xbfb8aa3b, v143
	v_exp_f32_e32 v131, v0
	s_nop 0
	v_pk_add_f32 v[130:131], v[130:131], 1.0 op_sel_hi:[1,0]
	s_nop 0
	s_nop 0
	v_rcp_f32_e32 v143, v131
	s_nop 0
	s_nop 0
	v_rcp_f32_e32 v142, v130
	s_nop 0
	v_mul_f32_e32 v0, 0xbfb8aa3b, v144
	v_exp_f32_e32 v130, v0
	v_mul_f32_e32 v0, 0xbfb8aa3b, v145
	v_exp_f32_e32 v131, v0
	s_nop 0
	v_pk_add_f32 v[130:131], v[130:131], 1.0 op_sel_hi:[1,0]
	s_nop 0
	s_nop 0
	v_rcp_f32_e32 v145, v131
	s_nop 0
	s_nop 0
	v_rcp_f32_e32 v144, v130
	s_nop 0
	s_and_b64 vcc, exec, s[44:45]
	s_cbranch_vccnz .LBB0_381
	global_load_dwordx4 v[130:133], v[134:135], off
	global_load_dwordx4 v[184:187], v[134:135], off offset:16
	s_waitcnt vmcnt(1)
	v_pk_mul_f32 v[182:183], v[182:183], v[132:133]
	v_pk_mul_f32 v[140:141], v[140:141], v[130:131]
	s_waitcnt vmcnt(0)
	v_pk_mul_f32 v[144:145], v[144:145], v[186:187]
	v_pk_mul_f32 v[142:143], v[142:143], v[184:185]

; __device__ __forceinline__ float sigm(float x) { return 1.f / (1.f + __expf(-x)); }
;     __device__ __forceinline__ void operator()(const pg8::f32x4 (&acc)[2][2][4][2], const pg8::Unit& u, int wr, int wc, int fr, int fq) const {
;     ...
;                     for (int bj = 0; bj < 2; ++bj) {
;                         float o[8];
; #pragma unroll
;                         for (int n = 0; n < 2; ++n)
; #pragma unroll
;                             for (int j = 0; j < 4; ++j) o[4 * n + j] = acc[ai][bj][m][n][j] * rsv;
;                         if (sig) {
; #pragma unroll
;                             for (int e = 0; e < 8; ++e) o[e] = sigm(o[e]);
;                             if (mode == EM_Z2) { const f32x4 h0 = *(const f32x4*)(gain0 + colb - 2048 + bj * 128 + cl), h1_ = *(const f32x4*)(gain0 + colb - 2048 + bj * 128 + cl + 4);
; #pragma unroll
;                                 for (int e = 0; e < 4; ++e) { o[e] *= h0[e]; o[4 + e] *= h1_[e]; } }
;                         }
.LBB0_387:
	v_mov_b32_e32 v175, v174
	v_pk_mul_f32 v[186:187], v[102:103], v[174:175]
	v_pk_mul_f32 v[190:191], v[104:105], v[174:175]
	v_pk_mul_f32 v[188:189], v[98:99], v[174:175]
	s_and_b64 vcc, exec, s[48:49]
	v_pk_mul_f32 v[192:193], v[100:101], v[174:175]
	global_store_dwordx4 v[184:185], v[130:133], off
	s_cbranch_vccnz .LBB0_390
	v_mul_f32_e32 v0, 0xbfb8aa3b, v186
	v_exp_f32_e32 v130, v0
	v_mul_f32_e32 v0, 0xbfb8aa3b, v187
	v_exp_f32_e32 v131, v0
	s_nop 0
	v_pk_add_f32 v[130:131], v[130:131], 1.0 op_sel_hi:[1,0]
	s_nop 0
	s_nop 0
	v_rcp_f32_e32 v187, v131
	s_nop 0
	s_nop 0
	v_rcp_f32_e32 v186, v130
	s_nop 0
	v_mul_f32_e32 v0, 0xbfb8aa3b, v190
	v_exp_f32_e32 v130, v0
	v_mul_f32_e32 v0, 0xbfb8aa3b, v191
	v_exp_f32_e32 v131, v0
	s_nop 0
	v_pk_add_f32 v[130:131], v[130:131], 1.0 op_sel_hi:[1,0]
	s_nop 0
	s_nop 0
	v_rcp_f32_e32 v191, v131
	s_nop 0
	s_nop 0
	v_rcp_f32_e32 v190, v130
	s_nop 0
	v_mul_f32_e32 v0, 0xbfb8aa3b, v188
	v_exp_f32_e32 v130, v0
	v_mul_f32_e32 v0, 0xbfb8aa3b, v189
	v_exp_f32_e32 v131, v0
	s_nop 0
	v_pk_add_f32 v[130:131], v[130:131], 1.0 op_sel_hi:[1,0]
	s_nop 0
	s_nop 0
	v_rcp_f32_e32 v189, v131
	s_nop 0
	s_nop 0
	v_rcp_f32_e32 v188, v130
	s_nop 0
	v_mul_f32_e32 v0, 0xbfb8aa3b, v192
	v_exp_f32_e32 v130, v0
	v_mul_f32_e32 v0, 0xbfb8aa3b, v193
	v_exp_f32_e32 v131, v0
	s_nop 0
	v_pk_add_f32 v[130:131], v[130:131], 1.0 op_sel_hi:[1,0]
	s_nop 0
	s_nop 0
	v_rcp_f32_e32 v193, v131
	s_nop 0
	s_nop 0
	v_rcp_f32_e32 v192, v130
	s_nop 0
	s_and_b64 vcc, exec, s[44:45]
	s_cbranch_vccnz .LBB0_390
	global_load_dwordx4 v[130:133], v[134:135], off offset:512
	global_load_dwordx4 v[230:233], v[134:135], off offset:528
	s_waitcnt vmcnt(1)
	v_pk_mul_f32 v[190:191], v[190:191], v[132:133]
	v_pk_mul_f32 v[186:187], v[186:187], v[130:131]
	s_waitcnt vmcnt(0)
	v_pk_mul_f32 v[192:193], v[192:193], v[232:233]
	v_pk_mul_f32 v[188:189], v[188:189], v[230:231]

; __device__ __forceinline__ float sigm(float x) { return 1.f / (1.f + __expf(-x)); }
;     __device__ __forceinline__ void operator()(const pg8::f32x4 (&acc)[2][2][4][2], const pg8::Unit& u, int wr, int wc, int fr, int fq) const {
;     ...
;                 for (int m = 0; m < 4; ++m) {
;                     const int row = rowb + ai * 128 + m * 16;
;                     const float rsv = rs8[ai][m];
;                     float sacc = 0.f;
; #pragma unroll
;                     for (int bj = 0; bj < 2; ++bj) {
;                         float o[8];
; #pragma unroll
;                         for (int n = 0; n < 2; ++n)
; #pragma unroll
;                             for (int j = 0; j < 4; ++j) o[4 * n + j] = acc[ai][bj][m][n][j] * rsv;
;                         if (sig) {
; #pragma unroll
;                             for (int e = 0; e < 8; ++e) o[e] = sigm(o[e]);
;                             if (mode == EM_Z2) { const f32x4 h0 = *(const f32x4*)(gain0 + colb - 2048 + bj * 128 + cl), h1_ = *(const f32x4*)(gain0 + colb - 2048 + bj * 128 + cl + 4);
; #pragma unroll
;                                 for (int e = 0; e < 4; ++e) { o[e] *= h0[e]; o[4 + e] *= h1_[e]; } }
;                         }
.LBB0_409:
	v_pk_mul_f32 v[140:141], v[94:95], v[172:173] op_sel_hi:[1,0]
	v_pk_mul_f32 v[182:183], v[96:97], v[172:173] op_sel_hi:[1,0]
	v_pk_mul_f32 v[142:143], v[90:91], v[172:173] op_sel_hi:[1,0]
	s_and_b64 vcc, exec, s[48:49]
	v_pk_mul_f32 v[144:145], v[92:93], v[172:173] op_sel_hi:[1,0]
	s_cbranch_vccnz .LBB0_412
	v_mul_f32_e32 v0, 0xbfb8aa3b, v140
	s_waitcnt lgkmcnt(0)
	v_exp_f32_e32 v130, v0
	v_mul_f32_e32 v0, 0xbfb8aa3b, v141
	v_exp_f32_e32 v131, v0
	s_nop 0
	v_pk_add_f32 v[130:131], v[130:131], 1.0 op_sel_hi:[1,0]
	s_nop 0
	s_nop 0
	v_rcp_f32_e32 v141, v131
	s_nop 0
	s_nop 0
	v_rcp_f32_e32 v140, v130
	s_nop 0
	v_mul_f32_e32 v0, 0xbfb8aa3b, v182
	v_exp_f32_e32 v130, v0
	v_mul_f32_e32 v0, 0xbfb8aa3b, v183
	v_exp_f32_e32 v131, v0
	s_nop 0
	v_pk_add_f32 v[130:131], v[130:131], 1.0 op_sel_hi:[1,0]
	s_nop 0
	s_nop 0
	v_rcp_f32_e32 v183, v131
	s_nop 0
	s_nop 0
	v_rcp_f32_e32 v182, v130
	s_nop 0
	v_mul_f32_e32 v0, 0xbfb8aa3b, v142
	v_exp_f32_e32 v130, v0
	v_mul_f32_e32 v0, 0xbfb8aa3b, v143
	v_exp_f32_e32 v131, v0
	s_nop 0
	v_pk_add_f32 v[130:131], v[130:131], 1.0 op_sel_hi:[1,0]
	s_nop 0
	s_nop 0
	v_rcp_f32_e32 v143, v131
	s_nop 0
	s_nop 0
	v_rcp_f32_e32 v142, v130
	s_nop 0
	v_mul_f32_e32 v0, 0xbfb8aa3b, v144
	v_exp_f32_e32 v130, v0
	v_mul_f32_e32 v0, 0xbfb8aa3b, v145
	v_exp_f32_e32 v131, v0
	s_nop 0
	v_pk_add_f32 v[130:131], v[130:131], 1.0 op_sel_hi:[1,0]
	s_nop 0
	s_nop 0
	v_rcp_f32_e32 v145, v131
	s_nop 0
	s_nop 0
	v_rcp_f32_e32 v144, v130
	s_nop 0
	s_and_b64 vcc, exec, s[44:45]
	s_cbranch_vccnz .LBB0_412
	global_load_dwordx4 v[130:133], v[134:135], off
	global_load_dwordx4 v[184:187], v[134:135], off offset:16
	s_waitcnt vmcnt(1)
	v_pk_mul_f32 v[182:183], v[182:183], v[132:133]
	v_pk_mul_f32 v[140:141], v[140:141], v[130:131]
	s_waitcnt vmcnt(0)
	v_pk_mul_f32 v[144:145], v[144:145], v[186:187]
	v_pk_mul_f32 v[142:143], v[142:143], v[184:185]

; __device__ __forceinline__ float sigm(float x) { return 1.f / (1.f + __expf(-x)); }
;     __device__ __forceinline__ void operator()(const pg8::f32x4 (&acc)[2][2][4][2], const pg8::Unit& u, int wr, int wc, int fr, int fq) const {
;     ...
;                     for (int bj = 0; bj < 2; ++bj) {
;                         float o[8];
; #pragma unroll
;                         for (int n = 0; n < 2; ++n)
; #pragma unroll
;                             for (int j = 0; j < 4; ++j) o[4 * n + j] = acc[ai][bj][m][n][j] * rsv;
;                         if (sig) {
; #pragma unroll
;                             for (int e = 0; e < 8; ++e) o[e] = sigm(o[e]);
;                             if (mode == EM_Z2) { const f32x4 h0 = *(const f32x4*)(gain0 + colb - 2048 + bj * 128 + cl), h1_ = *(const f32x4*)(gain0 + colb - 2048 + bj * 128 + cl + 4);
; #pragma unroll
;                                 for (int e = 0; e < 4; ++e) { o[e] *= h0[e]; o[4 + e] *= h1_[e]; } }
;                         }
.LBB0_418:
	v_mov_b32_e32 v173, v172
	v_pk_mul_f32 v[186:187], v[86:87], v[172:173]
	v_pk_mul_f32 v[190:191], v[88:89], v[172:173]
	v_pk_mul_f32 v[188:189], v[82:83], v[172:173]
	s_and_b64 vcc, exec, s[48:49]
	v_pk_mul_f32 v[192:193], v[84:85], v[172:173]
	global_store_dwordx4 v[184:185], v[130:133], off
	s_cbranch_vccnz .LBB0_421
	v_mul_f32_e32 v0, 0xbfb8aa3b, v186
	v_exp_f32_e32 v130, v0
	v_mul_f32_e32 v0, 0xbfb8aa3b, v187
	v_exp_f32_e32 v131, v0
	s_nop 0
	v_pk_add_f32 v[130:131], v[130:131], 1.0 op_sel_hi:[1,0]
	s_nop 0
	s_nop 0
	v_rcp_f32_e32 v187, v131
	s_nop 0
	s_nop 0
	v_rcp_f32_e32 v186, v130
	s_nop 0
	v_mul_f32_e32 v0, 0xbfb8aa3b, v190
	v_exp_f32_e32 v130, v0
	v_mul_f32_e32 v0, 0xbfb8aa3b, v191
	v_exp_f32_e32 v131, v0
	s_nop 0
	v_pk_add_f32 v[130:131], v[130:131], 1.0 op_sel_hi:[1,0]
	s_nop 0
	s_nop 0
	v_rcp_f32_e32 v191, v131
	s_nop 0
	s_nop 0
	v_rcp_f32_e32 v190, v130
	s_nop 0
	v_mul_f32_e32 v0, 0xbfb8aa3b, v188
	v_exp_f32_e32 v130, v0
	v_mul_f32_e32 v0, 0xbfb8aa3b, v189
	v_exp_f32_e32 v131, v0
	s_nop 0
	v_pk_add_f32 v[130:131], v[130:131], 1.0 op_sel_hi:[1,0]
	s_nop 0
	s_nop 0
	v_rcp_f32_e32 v189, v131
	s_nop 0
	s_nop 0
	v_rcp_f32_e32 v188, v130
	s_nop 0
	v_mul_f32_e32 v0, 0xbfb8aa3b, v192
	v_exp_f32_e32 v130, v0
	v_mul_f32_e32 v0, 0xbfb8aa3b, v193
	v_exp_f32_e32 v131, v0
	s_nop 0
	v_pk_add_f32 v[130:131], v[130:131], 1.0 op_sel_hi:[1,0]
	s_nop 0
	s_nop 0
	v_rcp_f32_e32 v193, v131
	s_nop 0
	s_nop 0
	v_rcp_f32_e32 v192, v130
	s_nop 0
	s_and_b64 vcc, exec, s[44:45]
	s_cbranch_vccnz .LBB0_421
	global_load_dwordx4 v[130:133], v[134:135], off offset:512
	global_load_dwordx4 v[230:233], v[134:135], off offset:528
	s_waitcnt vmcnt(1)
	v_pk_mul_f32 v[190:191], v[190:191], v[132:133]
	v_pk_mul_f32 v[186:187], v[186:187], v[130:131]
	s_waitcnt vmcnt(0)
	v_pk_mul_f32 v[192:193], v[192:193], v[232:233]
	v_pk_mul_f32 v[188:189], v[188:189], v[230:231]

; __device__ __forceinline__ float sigm(float x) { return 1.f / (1.f + __expf(-x)); }
;     __device__ __forceinline__ void operator()(const pg8::f32x4 (&acc)[2][2][4][2], const pg8::Unit& u, int wr, int wc, int fr, int fq) const {
;     ...
;                 for (int m = 0; m < 4; ++m) {
;                     const int row = rowb + ai * 128 + m * 16;
;                     const float rsv = rs8[ai][m];
;                     float sacc = 0.f;
; #pragma unroll
;                     for (int bj = 0; bj < 2; ++bj) {
;                         float o[8];
; #pragma unroll
;                         for (int n = 0; n < 2; ++n)
; #pragma unroll
;                             for (int j = 0; j < 4; ++j) o[4 * n + j] = acc[ai][bj][m][n][j] * rsv;
;                         if (sig) {
; #pragma unroll
;                             for (int e = 0; e < 8; ++e) o[e] = sigm(o[e]);
;                             if (mode == EM_Z2) { const f32x4 h0 = *(const f32x4*)(gain0 + colb - 2048 + bj * 128 + cl), h1_ = *(const f32x4*)(gain0 + colb - 2048 + bj * 128 + cl + 4);
; #pragma unroll
;                                 for (int e = 0; e < 4; ++e) { o[e] *= h0[e]; o[4 + e] *= h1_[e]; } }
;                         }
.LBB0_438:
	v_pk_mul_f32 v[140:141], v[78:79], v[170:171] op_sel_hi:[1,0]
	v_pk_mul_f32 v[182:183], v[80:81], v[170:171] op_sel_hi:[1,0]
	v_pk_mul_f32 v[142:143], v[74:75], v[170:171] op_sel_hi:[1,0]
	s_and_b64 vcc, exec, s[48:49]
	v_pk_mul_f32 v[144:145], v[76:77], v[170:171] op_sel_hi:[1,0]
	s_cbranch_vccnz .LBB0_441
	v_mul_f32_e32 v0, 0xbfb8aa3b, v140
	s_waitcnt lgkmcnt(0)
	v_exp_f32_e32 v130, v0
	v_mul_f32_e32 v0, 0xbfb8aa3b, v141
	v_exp_f32_e32 v131, v0
	s_nop 0
	v_pk_add_f32 v[130:131], v[130:131], 1.0 op_sel_hi:[1,0]
	s_nop 0
	s_nop 0
	v_rcp_f32_e32 v141, v131
	s_nop 0
	s_nop 0
	v_rcp_f32_e32 v140, v130
	s_nop 0
	v_mul_f32_e32 v0, 0xbfb8aa3b, v182
	v_exp_f32_e32 v130, v0
	v_mul_f32_e32 v0, 0xbfb8aa3b, v183
	v_exp_f32_e32 v131, v0
	s_nop 0
	v_pk_add_f32 v[130:131], v[130:131], 1.0 op_sel_hi:[1,0]
	s_nop 0
	s_nop 0
	v_rcp_f32_e32 v183, v131
	s_nop 0
	s_nop 0
	v_rcp_f32_e32 v182, v130
	s_nop 0
	v_mul_f32_e32 v0, 0xbfb8aa3b, v142
	v_exp_f32_e32 v130, v0
	v_mul_f32_e32 v0, 0xbfb8aa3b, v143
	v_exp_f32_e32 v131, v0
	s_nop 0
	v_pk_add_f32 v[130:131], v[130:131], 1.0 op_sel_hi:[1,0]
	s_nop 0
	s_nop 0
	v_rcp_f32_e32 v143, v131
	s_nop 0
	s_nop 0
	v_rcp_f32_e32 v142, v130
	s_nop 0
	v_mul_f32_e32 v0, 0xbfb8aa3b, v144
	v_exp_f32_e32 v130, v0
	v_mul_f32_e32 v0, 0xbfb8aa3b, v145
	v_exp_f32_e32 v131, v0
	s_nop 0
	v_pk_add_f32 v[130:131], v[130:131], 1.0 op_sel_hi:[1,0]
	s_nop 0
	s_nop 0
	v_rcp_f32_e32 v145, v131
	s_nop 0
	s_nop 0
	v_rcp_f32_e32 v144, v130
	s_nop 0
	s_and_b64 vcc, exec, s[44:45]
	s_cbranch_vccnz .LBB0_441
	global_load_dwordx4 v[130:133], v[134:135], off
	global_load_dwordx4 v[184:187], v[134:135], off offset:16
	s_waitcnt vmcnt(1)
	v_pk_mul_f32 v[182:183], v[182:183], v[132:133]
	v_pk_mul_f32 v[140:141], v[140:141], v[130:131]
	s_waitcnt vmcnt(0)
	v_pk_mul_f32 v[144:145], v[144:145], v[186:187]
	v_pk_mul_f32 v[142:143], v[142:143], v[184:185]

; __device__ __forceinline__ float sigm(float x) { return 1.f / (1.f + __expf(-x)); }
;     __device__ __forceinline__ void operator()(const pg8::f32x4 (&acc)[2][2][4][2], const pg8::Unit& u, int wr, int wc, int fr, int fq) const {
;     ...
;                     for (int bj = 0; bj < 2; ++bj) {
;                         float o[8];
; #pragma unroll
;                         for (int n = 0; n < 2; ++n)
; #pragma unroll
;                             for (int j = 0; j < 4; ++j) o[4 * n + j] = acc[ai][bj][m][n][j] * rsv;
;                         if (sig) {
; #pragma unroll
;                             for (int e = 0; e < 8; ++e) o[e] = sigm(o[e]);
;                             if (mode == EM_Z2) { const f32x4 h0 = *(const f32x4*)(gain0 + colb - 2048 + bj * 128 + cl), h1_ = *(const f32x4*)(gain0 + colb - 2048 + bj * 128 + cl + 4);
; #pragma unroll
;                                 for (int e = 0; e < 4; ++e) { o[e] *= h0[e]; o[4 + e] *= h1_[e]; } }
;                         }
.LBB0_447:
	v_mov_b32_e32 v171, v170
	v_pk_mul_f32 v[186:187], v[70:71], v[170:171]
	v_pk_mul_f32 v[190:191], v[72:73], v[170:171]
	v_pk_mul_f32 v[188:189], v[66:67], v[170:171]
	s_and_b64 vcc, exec, s[48:49]
	v_pk_mul_f32 v[192:193], v[68:69], v[170:171]
	global_store_dwordx4 v[184:185], v[130:133], off
	s_cbranch_vccnz .LBB0_450
	v_mul_f32_e32 v0, 0xbfb8aa3b, v186
	v_exp_f32_e32 v130, v0
	v_mul_f32_e32 v0, 0xbfb8aa3b, v187
	v_exp_f32_e32 v131, v0
	s_nop 0
	v_pk_add_f32 v[130:131], v[130:131], 1.0 op_sel_hi:[1,0]
	s_nop 0
	s_nop 0
	v_rcp_f32_e32 v187, v131
	s_nop 0
	s_nop 0
	v_rcp_f32_e32 v186, v130
	s_nop 0
	v_mul_f32_e32 v0, 0xbfb8aa3b, v190
	v_exp_f32_e32 v130, v0
	v_mul_f32_e32 v0, 0xbfb8aa3b, v191
	v_exp_f32_e32 v131, v0
	s_nop 0
	v_pk_add_f32 v[130:131], v[130:131], 1.0 op_sel_hi:[1,0]
	s_nop 0
	s_nop 0
	v_rcp_f32_e32 v191, v131
	s_nop 0
	s_nop 0
	v_rcp_f32_e32 v190, v130
	s_nop 0
	v_mul_f32_e32 v0, 0xbfb8aa3b, v188
	v_exp_f32_e32 v130, v0
	v_mul_f32_e32 v0, 0xbfb8aa3b, v189
	v_exp_f32_e32 v131, v0
	s_nop 0
	v_pk_add_f32 v[130:131], v[130:131], 1.0 op_sel_hi:[1,0]
	s_nop 0
	s_nop 0
	v_rcp_f32_e32 v189, v131
	s_nop 0
	s_nop 0
	v_rcp_f32_e32 v188, v130
	s_nop 0
	v_mul_f32_e32 v0, 0xbfb8aa3b, v192
	v_exp_f32_e32 v130, v0
	v_mul_f32_e32 v0, 0xbfb8aa3b, v193
	v_exp_f32_e32 v131, v0
	s_nop 0
	v_pk_add_f32 v[130:131], v[130:131], 1.0 op_sel_hi:[1,0]
	s_nop 0
	s_nop 0
	v_rcp_f32_e32 v193, v131
	s_nop 0
	s_nop 0
	v_rcp_f32_e32 v192, v130
	s_nop 0
	s_and_b64 vcc, exec, s[44:45]
	s_cbranch_vccnz .LBB0_450
	global_load_dwordx4 v[130:133], v[134:135], off offset:512
	global_load_dwordx4 v[230:233], v[134:135], off offset:528
	s_waitcnt vmcnt(1)
	v_pk_mul_f32 v[190:191], v[190:191], v[132:133]
	v_pk_mul_f32 v[186:187], v[186:187], v[130:131]
	s_waitcnt vmcnt(0)
	v_pk_mul_f32 v[192:193], v[192:193], v[232:233]
	v_pk_mul_f32 v[188:189], v[188:189], v[230:231]

; __device__ __forceinline__ float sigm(float x) { return 1.f / (1.f + __expf(-x)); }
;     __device__ __forceinline__ void operator()(const pg8::f32x4 (&acc)[2][2][4][2], const pg8::Unit& u, int wr, int wc, int fr, int fq) const {
;     ...
;                 for (int m = 0; m < 4; ++m) {
;                     const int row = rowb + ai * 128 + m * 16;
;                     const float rsv = rs8[ai][m];
;                     float sacc = 0.f;
; #pragma unroll
;                     for (int bj = 0; bj < 2; ++bj) {
;                         float o[8];
; #pragma unroll
;                         for (int n = 0; n < 2; ++n)
; #pragma unroll
;                             for (int j = 0; j < 4; ++j) o[4 * n + j] = acc[ai][bj][m][n][j] * rsv;
;                         if (sig) {
; #pragma unroll
;                             for (int e = 0; e < 8; ++e) o[e] = sigm(o[e]);
;                             if (mode == EM_Z2) { const f32x4 h0 = *(const f32x4*)(gain0 + colb - 2048 + bj * 128 + cl), h1_ = *(const f32x4*)(gain0 + colb - 2048 + bj * 128 + cl + 4);
; #pragma unroll
;                                 for (int e = 0; e < 4; ++e) { o[e] *= h0[e]; o[4 + e] *= h1_[e]; } }
;                         }
.LBB0_467:
	v_pk_mul_f32 v[140:141], v[62:63], v[168:169] op_sel_hi:[1,0]
	v_pk_mul_f32 v[182:183], v[64:65], v[168:169] op_sel_hi:[1,0]
	v_pk_mul_f32 v[142:143], v[58:59], v[168:169] op_sel_hi:[1,0]
	s_and_b64 vcc, exec, s[48:49]
	v_pk_mul_f32 v[144:145], v[60:61], v[168:169] op_sel_hi:[1,0]
	s_cbranch_vccnz .LBB0_470
	v_mul_f32_e32 v0, 0xbfb8aa3b, v140
	s_waitcnt lgkmcnt(0)
	v_exp_f32_e32 v130, v0
	v_mul_f32_e32 v0, 0xbfb8aa3b, v141
	v_exp_f32_e32 v131, v0
	s_nop 0
	v_pk_add_f32 v[130:131], v[130:131], 1.0 op_sel_hi:[1,0]
	s_nop 0
	s_nop 0
	v_rcp_f32_e32 v141, v131
	s_nop 0
	s_nop 0
	v_rcp_f32_e32 v140, v130
	s_nop 0
	v_mul_f32_e32 v0, 0xbfb8aa3b, v182
	v_exp_f32_e32 v130, v0
	v_mul_f32_e32 v0, 0xbfb8aa3b, v183
	v_exp_f32_e32 v131, v0
	s_nop 0
	v_pk_add_f32 v[130:131], v[130:131], 1.0 op_sel_hi:[1,0]
	s_nop 0
	s_nop 0
	v_rcp_f32_e32 v183, v131
	s_nop 0
	s_nop 0
	v_rcp_f32_e32 v182, v130
	s_nop 0
	v_mul_f32_e32 v0, 0xbfb8aa3b, v142
	v_exp_f32_e32 v130, v0
	v_mul_f32_e32 v0, 0xbfb8aa3b, v143
	v_exp_f32_e32 v131, v0
	s_nop 0
	v_pk_add_f32 v[130:131], v[130:131], 1.0 op_sel_hi:[1,0]
	s_nop 0
	s_nop 0
	v_rcp_f32_e32 v143, v131
	s_nop 0
	s_nop 0
	v_rcp_f32_e32 v142, v130
	s_nop 0
	v_mul_f32_e32 v0, 0xbfb8aa3b, v144
	v_exp_f32_e32 v130, v0
	v_mul_f32_e32 v0, 0xbfb8aa3b, v145
	v_exp_f32_e32 v131, v0
	s_nop 0
	v_pk_add_f32 v[130:131], v[130:131], 1.0 op_sel_hi:[1,0]
	s_nop 0
	s_nop 0
	v_rcp_f32_e32 v145, v131
	s_nop 0
	s_nop 0
	v_rcp_f32_e32 v144, v130
	s_nop 0
	s_and_b64 vcc, exec, s[44:45]
	s_cbranch_vccnz .LBB0_470
	global_load_dwordx4 v[130:133], v[134:135], off
	global_load_dwordx4 v[184:187], v[134:135], off offset:16
	s_waitcnt vmcnt(1)
	v_pk_mul_f32 v[182:183], v[182:183], v[132:133]
	v_pk_mul_f32 v[140:141], v[140:141], v[130:131]
	s_waitcnt vmcnt(0)
	v_pk_mul_f32 v[144:145], v[144:145], v[186:187]
	v_pk_mul_f32 v[142:143], v[142:143], v[184:185]

; __device__ __forceinline__ float sigm(float x) { return 1.f / (1.f + __expf(-x)); }
;     __device__ __forceinline__ void operator()(const pg8::f32x4 (&acc)[2][2][4][2], const pg8::Unit& u, int wr, int wc, int fr, int fq) const {
;     ...
;                     for (int bj = 0; bj < 2; ++bj) {
;                         float o[8];
; #pragma unroll
;                         for (int n = 0; n < 2; ++n)
; #pragma unroll
;                             for (int j = 0; j < 4; ++j) o[4 * n + j] = acc[ai][bj][m][n][j] * rsv;
;                         if (sig) {
; #pragma unroll
;                             for (int e = 0; e < 8; ++e) o[e] = sigm(o[e]);
;                             if (mode == EM_Z2) { const f32x4 h0 = *(const f32x4*)(gain0 + colb - 2048 + bj * 128 + cl), h1_ = *(const f32x4*)(gain0 + colb - 2048 + bj * 128 + cl + 4);
; #pragma unroll
;                                 for (int e = 0; e < 4; ++e) { o[e] *= h0[e]; o[4 + e] *= h1_[e]; } }
;                         }
.LBB0_476:
	v_mov_b32_e32 v169, v168
	v_pk_mul_f32 v[186:187], v[54:55], v[168:169]
	v_pk_mul_f32 v[190:191], v[56:57], v[168:169]
	v_pk_mul_f32 v[188:189], v[50:51], v[168:169]
	s_and_b64 vcc, exec, s[48:49]
	v_pk_mul_f32 v[192:193], v[52:53], v[168:169]
	global_store_dwordx4 v[184:185], v[130:133], off
	s_cbranch_vccnz .LBB0_479
	v_mul_f32_e32 v0, 0xbfb8aa3b, v186
	v_exp_f32_e32 v130, v0
	v_mul_f32_e32 v0, 0xbfb8aa3b, v187
	v_exp_f32_e32 v131, v0
	s_nop 0
	v_pk_add_f32 v[130:131], v[130:131], 1.0 op_sel_hi:[1,0]
	s_nop 0
	s_nop 0
	v_rcp_f32_e32 v187, v131
	s_nop 0
	s_nop 0
	v_rcp_f32_e32 v186, v130
	s_nop 0
	v_mul_f32_e32 v0, 0xbfb8aa3b, v190
	v_exp_f32_e32 v130, v0
	v_mul_f32_e32 v0, 0xbfb8aa3b, v191
	v_exp_f32_e32 v131, v0
	s_nop 0
	v_pk_add_f32 v[130:131], v[130:131], 1.0 op_sel_hi:[1,0]
	s_nop 0
	s_nop 0
	v_rcp_f32_e32 v191, v131
	s_nop 0
	s_nop 0
	v_rcp_f32_e32 v190, v130
	s_nop 0
	v_mul_f32_e32 v0, 0xbfb8aa3b, v188
	v_exp_f32_e32 v130, v0
	v_mul_f32_e32 v0, 0xbfb8aa3b, v189
	v_exp_f32_e32 v131, v0
	s_nop 0
	v_pk_add_f32 v[130:131], v[130:131], 1.0 op_sel_hi:[1,0]
	s_nop 0
	s_nop 0
	v_rcp_f32_e32 v189, v131
	s_nop 0
	s_nop 0
	v_rcp_f32_e32 v188, v130
	s_nop 0
	v_mul_f32_e32 v0, 0xbfb8aa3b, v192
	v_exp_f32_e32 v130, v0
	v_mul_f32_e32 v0, 0xbfb8aa3b, v193
	v_exp_f32_e32 v131, v0
	s_nop 0
	v_pk_add_f32 v[130:131], v[130:131], 1.0 op_sel_hi:[1,0]
	s_nop 0
	s_nop 0
	v_rcp_f32_e32 v193, v131
	s_nop 0
	s_nop 0
	v_rcp_f32_e32 v192, v130
	s_nop 0
	s_and_b64 vcc, exec, s[44:45]
	s_cbranch_vccnz .LBB0_479
	global_load_dwordx4 v[130:133], v[134:135], off offset:512
	global_load_dwordx4 v[230:233], v[134:135], off offset:528
	s_waitcnt vmcnt(1)
	v_pk_mul_f32 v[190:191], v[190:191], v[132:133]
	v_pk_mul_f32 v[186:187], v[186:187], v[130:131]
	s_waitcnt vmcnt(0)
	v_pk_mul_f32 v[192:193], v[192:193], v[232:233]
	v_pk_mul_f32 v[188:189], v[188:189], v[230:231]

; __device__ __forceinline__ float sigm(float x) { return 1.f / (1.f + __expf(-x)); }
;     __device__ __forceinline__ void operator()(const pg8::f32x4 (&acc)[2][2][4][2], const pg8::Unit& u, int wr, int wc, int fr, int fq) const {
;     ...
;                 for (int m = 0; m < 4; ++m) {
;                     const int row = rowb + ai * 128 + m * 16;
;                     const float rsv = rs8[ai][m];
;                     float sacc = 0.f;
; #pragma unroll
;                     for (int bj = 0; bj < 2; ++bj) {
;                         float o[8];
; #pragma unroll
;                         for (int n = 0; n < 2; ++n)
; #pragma unroll
;                             for (int j = 0; j < 4; ++j) o[4 * n + j] = acc[ai][bj][m][n][j] * rsv;
;                         if (sig) {
; #pragma unroll
;                             for (int e = 0; e < 8; ++e) o[e] = sigm(o[e]);
;                             if (mode == EM_Z2) { const f32x4 h0 = *(const f32x4*)(gain0 + colb - 2048 + bj * 128 + cl), h1_ = *(const f32x4*)(gain0 + colb - 2048 + bj * 128 + cl + 4);
; #pragma unroll
;                                 for (int e = 0; e < 4; ++e) { o[e] *= h0[e]; o[4 + e] *= h1_[e]; } }
;                         }
.LBB0_496:
	v_pk_mul_f32 v[140:141], v[46:47], v[166:167] op_sel_hi:[1,0]
	v_pk_mul_f32 v[182:183], v[48:49], v[166:167] op_sel_hi:[1,0]
	v_pk_mul_f32 v[142:143], v[42:43], v[166:167] op_sel_hi:[1,0]
	s_and_b64 vcc, exec, s[48:49]
	v_pk_mul_f32 v[144:145], v[44:45], v[166:167] op_sel_hi:[1,0]
	s_cbranch_vccnz .LBB0_499
	v_mul_f32_e32 v0, 0xbfb8aa3b, v140
	s_waitcnt lgkmcnt(0)
	v_exp_f32_e32 v130, v0
	v_mul_f32_e32 v0, 0xbfb8aa3b, v141
	v_exp_f32_e32 v131, v0
	s_nop 0
	v_pk_add_f32 v[130:131], v[130:131], 1.0 op_sel_hi:[1,0]
	s_nop 0
	s_nop 0
	v_rcp_f32_e32 v141, v131
	s_nop 0
	s_nop 0
	v_rcp_f32_e32 v140, v130
	s_nop 0
	v_mul_f32_e32 v0, 0xbfb8aa3b, v182
	v_exp_f32_e32 v130, v0
	v_mul_f32_e32 v0, 0xbfb8aa3b, v183
	v_exp_f32_e32 v131, v0
	s_nop 0
	v_pk_add_f32 v[130:131], v[130:131], 1.0 op_sel_hi:[1,0]
	s_nop 0
	s_nop 0
	v_rcp_f32_e32 v183, v131
	s_nop 0
	s_nop 0
	v_rcp_f32_e32 v182, v130
	s_nop 0
	v_mul_f32_e32 v0, 0xbfb8aa3b, v142
	v_exp_f32_e32 v130, v0
	v_mul_f32_e32 v0, 0xbfb8aa3b, v143
	v_exp_f32_e32 v131, v0
	s_nop 0
	v_pk_add_f32 v[130:131], v[130:131], 1.0 op_sel_hi:[1,0]
	s_nop 0
	s_nop 0
	v_rcp_f32_e32 v143, v131
	s_nop 0
	s_nop 0
	v_rcp_f32_e32 v142, v130
	s_nop 0
	v_mul_f32_e32 v0, 0xbfb8aa3b, v144
	v_exp_f32_e32 v130, v0
	v_mul_f32_e32 v0, 0xbfb8aa3b, v145
	v_exp_f32_e32 v131, v0
	s_nop 0
	v_pk_add_f32 v[130:131], v[130:131], 1.0 op_sel_hi:[1,0]
	s_nop 0
	s_nop 0
	v_rcp_f32_e32 v145, v131
	s_nop 0
	s_nop 0
	v_rcp_f32_e32 v144, v130
	s_nop 0
	s_and_b64 vcc, exec, s[44:45]
	s_cbranch_vccnz .LBB0_499
	global_load_dwordx4 v[130:133], v[134:135], off
	global_load_dwordx4 v[184:187], v[134:135], off offset:16
	s_waitcnt vmcnt(1)
	v_pk_mul_f32 v[182:183], v[182:183], v[132:133]
	v_pk_mul_f32 v[140:141], v[140:141], v[130:131]
	s_waitcnt vmcnt(0)
	v_pk_mul_f32 v[144:145], v[144:145], v[186:187]
	v_pk_mul_f32 v[142:143], v[142:143], v[184:185]

; __device__ __forceinline__ float sigm(float x) { return 1.f / (1.f + __expf(-x)); }
;     __device__ __forceinline__ void operator()(const pg8::f32x4 (&acc)[2][2][4][2], const pg8::Unit& u, int wr, int wc, int fr, int fq) const {
;     ...
;                     for (int bj = 0; bj < 2; ++bj) {
;                         float o[8];
; #pragma unroll
;                         for (int n = 0; n < 2; ++n)
; #pragma unroll
;                             for (int j = 0; j < 4; ++j) o[4 * n + j] = acc[ai][bj][m][n][j] * rsv;
;                         if (sig) {
; #pragma unroll
;                             for (int e = 0; e < 8; ++e) o[e] = sigm(o[e]);
;                             if (mode == EM_Z2) { const f32x4 h0 = *(const f32x4*)(gain0 + colb - 2048 + bj * 128 + cl), h1_ = *(const f32x4*)(gain0 + colb - 2048 + bj * 128 + cl + 4);
; #pragma unroll
;                                 for (int e = 0; e < 4; ++e) { o[e] *= h0[e]; o[4 + e] *= h1_[e]; } }
;                         }
.LBB0_505:
	v_mov_b32_e32 v167, v166
	v_pk_mul_f32 v[186:187], v[38:39], v[166:167]
	v_pk_mul_f32 v[190:191], v[40:41], v[166:167]
	v_pk_mul_f32 v[188:189], v[34:35], v[166:167]
	s_and_b64 vcc, exec, s[48:49]
	v_pk_mul_f32 v[192:193], v[36:37], v[166:167]
	global_store_dwordx4 v[184:185], v[130:133], off
	s_cbranch_vccnz .LBB0_508
	v_mul_f32_e32 v0, 0xbfb8aa3b, v186
	v_exp_f32_e32 v130, v0
	v_mul_f32_e32 v0, 0xbfb8aa3b, v187
	v_exp_f32_e32 v131, v0
	s_nop 0
	v_pk_add_f32 v[130:131], v[130:131], 1.0 op_sel_hi:[1,0]
	s_nop 0
	s_nop 0
	v_rcp_f32_e32 v187, v131
	s_nop 0
	s_nop 0
	v_rcp_f32_e32 v186, v130
	s_nop 0
	v_mul_f32_e32 v0, 0xbfb8aa3b, v190
	v_exp_f32_e32 v130, v0
	v_mul_f32_e32 v0, 0xbfb8aa3b, v191
	v_exp_f32_e32 v131, v0
	s_nop 0
	v_pk_add_f32 v[130:131], v[130:131], 1.0 op_sel_hi:[1,0]
	s_nop 0
	s_nop 0
	v_rcp_f32_e32 v191, v131
	s_nop 0
	s_nop 0
	v_rcp_f32_e32 v190, v130
	s_nop 0
	v_mul_f32_e32 v0, 0xbfb8aa3b, v188
	v_exp_f32_e32 v130, v0
	v_mul_f32_e32 v0, 0xbfb8aa3b, v189
	v_exp_f32_e32 v131, v0
	s_nop 0
	v_pk_add_f32 v[130:131], v[130:131], 1.0 op_sel_hi:[1,0]
	s_nop 0
	s_nop 0
	v_rcp_f32_e32 v189, v131
	s_nop 0
	s_nop 0
	v_rcp_f32_e32 v188, v130
	s_nop 0
	v_mul_f32_e32 v0, 0xbfb8aa3b, v192
	v_exp_f32_e32 v130, v0
	v_mul_f32_e32 v0, 0xbfb8aa3b, v193
	v_exp_f32_e32 v131, v0
	s_nop 0
	v_pk_add_f32 v[130:131], v[130:131], 1.0 op_sel_hi:[1,0]
	s_nop 0
	s_nop 0
	v_rcp_f32_e32 v193, v131
	s_nop 0
	s_nop 0
	v_rcp_f32_e32 v192, v130
	s_nop 0
	s_and_b64 vcc, exec, s[44:45]
	s_cbranch_vccnz .LBB0_508
	global_load_dwordx4 v[130:133], v[134:135], off offset:512
	global_load_dwordx4 v[230:233], v[134:135], off offset:528
	s_waitcnt vmcnt(1)
	v_pk_mul_f32 v[190:191], v[190:191], v[132:133]
	v_pk_mul_f32 v[186:187], v[186:187], v[130:131]
	s_waitcnt vmcnt(0)
	v_pk_mul_f32 v[192:193], v[192:193], v[232:233]
	v_pk_mul_f32 v[188:189], v[188:189], v[230:231]

; __device__ __forceinline__ float sigm(float x) { return 1.f / (1.f + __expf(-x)); }
;     __device__ __forceinline__ void operator()(const pg8::f32x4 (&acc)[2][2][4][2], const pg8::Unit& u, int wr, int wc, int fr, int fq) const {
;     ...
;                 for (int m = 0; m < 4; ++m) {
;                     const int row = rowb + ai * 128 + m * 16;
;                     const float rsv = rs8[ai][m];
;                     float sacc = 0.f;
; #pragma unroll
;                     for (int bj = 0; bj < 2; ++bj) {
;                         float o[8];
; #pragma unroll
;                         for (int n = 0; n < 2; ++n)
; #pragma unroll
;                             for (int j = 0; j < 4; ++j) o[4 * n + j] = acc[ai][bj][m][n][j] * rsv;
;                         if (sig) {
; #pragma unroll
;                             for (int e = 0; e < 8; ++e) o[e] = sigm(o[e]);
;                             if (mode == EM_Z2) { const f32x4 h0 = *(const f32x4*)(gain0 + colb - 2048 + bj * 128 + cl), h1_ = *(const f32x4*)(gain0 + colb - 2048 + bj * 128 + cl + 4);
; #pragma unroll
;                                 for (int e = 0; e < 4; ++e) { o[e] *= h0[e]; o[4 + e] *= h1_[e]; } }
;                         }
.LBB0_525:
	v_pk_mul_f32 v[140:141], v[30:31], v[164:165] op_sel_hi:[1,0]
	v_pk_mul_f32 v[182:183], v[32:33], v[164:165] op_sel_hi:[1,0]
	v_pk_mul_f32 v[142:143], v[26:27], v[164:165] op_sel_hi:[1,0]
	s_and_b64 vcc, exec, s[48:49]
	v_pk_mul_f32 v[144:145], v[28:29], v[164:165] op_sel_hi:[1,0]
	s_cbranch_vccnz .LBB0_528
	v_mul_f32_e32 v0, 0xbfb8aa3b, v140
	s_waitcnt lgkmcnt(0)
	v_exp_f32_e32 v130, v0
	v_mul_f32_e32 v0, 0xbfb8aa3b, v141
	v_exp_f32_e32 v131, v0
	s_nop 0
	v_pk_add_f32 v[130:131], v[130:131], 1.0 op_sel_hi:[1,0]
	s_nop 0
	s_nop 0
	v_rcp_f32_e32 v141, v131
	s_nop 0
	s_nop 0
	v_rcp_f32_e32 v140, v130
	s_nop 0
	v_mul_f32_e32 v0, 0xbfb8aa3b, v182
	v_exp_f32_e32 v130, v0
	v_mul_f32_e32 v0, 0xbfb8aa3b, v183
	v_exp_f32_e32 v131, v0
	s_nop 0
	v_pk_add_f32 v[130:131], v[130:131], 1.0 op_sel_hi:[1,0]
	s_nop 0
	s_nop 0
	v_rcp_f32_e32 v183, v131
	s_nop 0
	s_nop 0
	v_rcp_f32_e32 v182, v130
	s_nop 0
	v_mul_f32_e32 v0, 0xbfb8aa3b, v142
	v_exp_f32_e32 v130, v0
	v_mul_f32_e32 v0, 0xbfb8aa3b, v143
	v_exp_f32_e32 v131, v0
	s_nop 0
	v_pk_add_f32 v[130:131], v[130:131], 1.0 op_sel_hi:[1,0]
	s_nop 0
	s_nop 0
	v_rcp_f32_e32 v143, v131
	s_nop 0
	s_nop 0
	v_rcp_f32_e32 v142, v130
	s_nop 0
	v_mul_f32_e32 v0, 0xbfb8aa3b, v144
	v_exp_f32_e32 v130, v0
	v_mul_f32_e32 v0, 0xbfb8aa3b, v145
	v_exp_f32_e32 v131, v0
	s_nop 0
	v_pk_add_f32 v[130:131], v[130:131], 1.0 op_sel_hi:[1,0]
	s_nop 0
	s_nop 0
	v_rcp_f32_e32 v145, v131
	s_nop 0
	s_nop 0
	v_rcp_f32_e32 v144, v130
	s_nop 0
	s_and_b64 vcc, exec, s[44:45]
	s_cbranch_vccnz .LBB0_528
	global_load_dwordx4 v[130:133], v[134:135], off
	global_load_dwordx4 v[184:187], v[134:135], off offset:16
	s_waitcnt vmcnt(1)
	v_pk_mul_f32 v[182:183], v[182:183], v[132:133]
	v_pk_mul_f32 v[140:141], v[140:141], v[130:131]
	s_waitcnt vmcnt(0)
	v_pk_mul_f32 v[144:145], v[144:145], v[186:187]
	v_pk_mul_f32 v[142:143], v[142:143], v[184:185]

; __device__ __forceinline__ float sigm(float x) { return 1.f / (1.f + __expf(-x)); }
;     __device__ __forceinline__ void operator()(const pg8::f32x4 (&acc)[2][2][4][2], const pg8::Unit& u, int wr, int wc, int fr, int fq) const {
;     ...
;                     for (int bj = 0; bj < 2; ++bj) {
;                         float o[8];
; #pragma unroll
;                         for (int n = 0; n < 2; ++n)
; #pragma unroll
;                             for (int j = 0; j < 4; ++j) o[4 * n + j] = acc[ai][bj][m][n][j] * rsv;
;                         if (sig) {
; #pragma unroll
;                             for (int e = 0; e < 8; ++e) o[e] = sigm(o[e]);
;                             if (mode == EM_Z2) { const f32x4 h0 = *(const f32x4*)(gain0 + colb - 2048 + bj * 128 + cl), h1_ = *(const f32x4*)(gain0 + colb - 2048 + bj * 128 + cl + 4);
; #pragma unroll
;                                 for (int e = 0; e < 4; ++e) { o[e] *= h0[e]; o[4 + e] *= h1_[e]; } }
;                         }
.LBB0_534:
	v_mov_b32_e32 v165, v164
	v_pk_mul_f32 v[186:187], v[22:23], v[164:165]
	v_pk_mul_f32 v[190:191], v[24:25], v[164:165]
	v_pk_mul_f32 v[188:189], v[18:19], v[164:165]
	s_and_b64 vcc, exec, s[48:49]
	v_pk_mul_f32 v[192:193], v[20:21], v[164:165]
	global_store_dwordx4 v[184:185], v[130:133], off
	s_cbranch_vccnz .LBB0_537
	v_mul_f32_e32 v0, 0xbfb8aa3b, v186
	v_exp_f32_e32 v130, v0
	v_mul_f32_e32 v0, 0xbfb8aa3b, v187
	v_exp_f32_e32 v131, v0
	s_nop 0
	v_pk_add_f32 v[130:131], v[130:131], 1.0 op_sel_hi:[1,0]
	s_nop 0
	s_nop 0
	v_rcp_f32_e32 v187, v131
	s_nop 0
	s_nop 0
	v_rcp_f32_e32 v186, v130
	s_nop 0
	v_mul_f32_e32 v0, 0xbfb8aa3b, v190
	v_exp_f32_e32 v130, v0
	v_mul_f32_e32 v0, 0xbfb8aa3b, v191
	v_exp_f32_e32 v131, v0
	s_nop 0
	v_pk_add_f32 v[130:131], v[130:131], 1.0 op_sel_hi:[1,0]
	s_nop 0
	s_nop 0
	v_rcp_f32_e32 v191, v131
	s_nop 0
	s_nop 0
	v_rcp_f32_e32 v190, v130
	s_nop 0
	v_mul_f32_e32 v0, 0xbfb8aa3b, v188
	v_exp_f32_e32 v130, v0
	v_mul_f32_e32 v0, 0xbfb8aa3b, v189
	v_exp_f32_e32 v131, v0
	s_nop 0
	v_pk_add_f32 v[130:131], v[130:131], 1.0 op_sel_hi:[1,0]
	s_nop 0
	s_nop 0
	v_rcp_f32_e32 v189, v131
	s_nop 0
	s_nop 0
	v_rcp_f32_e32 v188, v130
	s_nop 0
	v_mul_f32_e32 v0, 0xbfb8aa3b, v192
	v_exp_f32_e32 v130, v0
	v_mul_f32_e32 v0, 0xbfb8aa3b, v193
	v_exp_f32_e32 v131, v0
	s_nop 0
	v_pk_add_f32 v[130:131], v[130:131], 1.0 op_sel_hi:[1,0]
	s_nop 0
	s_nop 0
	v_rcp_f32_e32 v193, v131
	s_nop 0
	s_nop 0
	v_rcp_f32_e32 v192, v130
	s_nop 0
	s_and_b64 vcc, exec, s[44:45]
	s_cbranch_vccnz .LBB0_537
	global_load_dwordx4 v[130:133], v[134:135], off offset:512
	global_load_dwordx4 v[230:233], v[134:135], off offset:528
	s_waitcnt vmcnt(1)
	v_pk_mul_f32 v[190:191], v[190:191], v[132:133]
	v_pk_mul_f32 v[186:187], v[186:187], v[130:131]
	s_waitcnt vmcnt(0)
	v_pk_mul_f32 v[192:193], v[192:193], v[232:233]
	v_pk_mul_f32 v[188:189], v[188:189], v[230:231]

; __device__ __forceinline__ float sigm(float x) { return 1.f / (1.f + __expf(-x)); }
;     __device__ __forceinline__ void operator()(const pg8::f32x4 (&acc)[2][2][4][2], const pg8::Unit& u, int wr, int wc, int fr, int fq) const {
;     ...
;                 for (int m = 0; m < 4; ++m) {
;                     const int row = rowb + ai * 128 + m * 16;
;                     const float rsv = rs8[ai][m];
;                     float sacc = 0.f;
; #pragma unroll
;                     for (int bj = 0; bj < 2; ++bj) {
;                         float o[8];
; #pragma unroll
;                         for (int n = 0; n < 2; ++n)
; #pragma unroll
;                             for (int j = 0; j < 4; ++j) o[4 * n + j] = acc[ai][bj][m][n][j] * rsv;
;                         if (sig) {
; #pragma unroll
;                             for (int e = 0; e < 8; ++e) o[e] = sigm(o[e]);
;                             if (mode == EM_Z2) { const f32x4 h0 = *(const f32x4*)(gain0 + colb - 2048 + bj * 128 + cl), h1_ = *(const f32x4*)(gain0 + colb - 2048 + bj * 128 + cl + 4);
; #pragma unroll
;                                 for (int e = 0; e < 4; ++e) { o[e] *= h0[e]; o[4 + e] *= h1_[e]; } }
;                         }
.LBB0_554:
	v_pk_mul_f32 v[140:141], v[14:15], v[162:163] op_sel_hi:[1,0]
	v_pk_mul_f32 v[182:183], v[16:17], v[162:163] op_sel_hi:[1,0]
	v_pk_mul_f32 v[142:143], v[10:11], v[162:163] op_sel_hi:[1,0]
	s_and_b64 vcc, exec, s[48:49]
	v_pk_mul_f32 v[144:145], v[12:13], v[162:163] op_sel_hi:[1,0]
	s_cbranch_vccnz .LBB0_557
	v_mul_f32_e32 v0, 0xbfb8aa3b, v140
	s_waitcnt lgkmcnt(0)
	v_exp_f32_e32 v130, v0
	v_mul_f32_e32 v0, 0xbfb8aa3b, v141
	v_exp_f32_e32 v131, v0
	s_nop 0
	v_pk_add_f32 v[130:131], v[130:131], 1.0 op_sel_hi:[1,0]
	s_nop 0
	s_nop 0
	v_rcp_f32_e32 v141, v131
	s_nop 0
	s_nop 0
	v_rcp_f32_e32 v140, v130
	s_nop 0
	v_mul_f32_e32 v0, 0xbfb8aa3b, v182
	v_exp_f32_e32 v130, v0
	v_mul_f32_e32 v0, 0xbfb8aa3b, v183
	v_exp_f32_e32 v131, v0
	s_nop 0
	v_pk_add_f32 v[130:131], v[130:131], 1.0 op_sel_hi:[1,0]
	s_nop 0
	s_nop 0
	v_rcp_f32_e32 v183, v131
	s_nop 0
	s_nop 0
	v_rcp_f32_e32 v182, v130
	s_nop 0
	v_mul_f32_e32 v0, 0xbfb8aa3b, v142
	v_exp_f32_e32 v130, v0
	v_mul_f32_e32 v0, 0xbfb8aa3b, v143
	v_exp_f32_e32 v131, v0
	s_nop 0
	v_pk_add_f32 v[130:131], v[130:131], 1.0 op_sel_hi:[1,0]
	s_nop 0
	s_nop 0
	v_rcp_f32_e32 v143, v131
	s_nop 0
	s_nop 0
	v_rcp_f32_e32 v142, v130
	s_nop 0
	v_mul_f32_e32 v0, 0xbfb8aa3b, v144
	v_exp_f32_e32 v130, v0
	v_mul_f32_e32 v0, 0xbfb8aa3b, v145
	v_exp_f32_e32 v131, v0
	s_nop 0
	v_pk_add_f32 v[130:131], v[130:131], 1.0 op_sel_hi:[1,0]
	s_nop 0
	s_nop 0
	v_rcp_f32_e32 v145, v131
	s_nop 0
	s_nop 0
	v_rcp_f32_e32 v144, v130
	s_nop 0
	s_and_b64 vcc, exec, s[44:45]
	s_cbranch_vccnz .LBB0_557
	global_load_dwordx4 v[130:133], v[134:135], off
	global_load_dwordx4 v[184:187], v[134:135], off offset:16
	s_waitcnt vmcnt(1)
	v_pk_mul_f32 v[182:183], v[182:183], v[132:133]
	v_pk_mul_f32 v[140:141], v[140:141], v[130:131]
	s_waitcnt vmcnt(0)
	v_pk_mul_f32 v[144:145], v[144:145], v[186:187]
	v_pk_mul_f32 v[142:143], v[142:143], v[184:185]

; __device__ __forceinline__ float sigm(float x) { return 1.f / (1.f + __expf(-x)); }
;     __device__ __forceinline__ void operator()(const pg8::f32x4 (&acc)[2][2][4][2], const pg8::Unit& u, int wr, int wc, int fr, int fq) const {
;     ...
;                     for (int bj = 0; bj < 2; ++bj) {
;                         float o[8];
; #pragma unroll
;                         for (int n = 0; n < 2; ++n)
; #pragma unroll
;                             for (int j = 0; j < 4; ++j) o[4 * n + j] = acc[ai][bj][m][n][j] * rsv;
;                         if (sig) {
; #pragma unroll
;                             for (int e = 0; e < 8; ++e) o[e] = sigm(o[e]);
;                             if (mode == EM_Z2) { const f32x4 h0 = *(const f32x4*)(gain0 + colb - 2048 + bj * 128 + cl), h1_ = *(const f32x4*)(gain0 + colb - 2048 + bj * 128 + cl + 4);
; #pragma unroll
;                                 for (int e = 0; e < 4; ++e) { o[e] *= h0[e]; o[4 + e] *= h1_[e]; } }
;                         }
.LBB0_563:
	v_mov_b32_e32 v163, v162
	v_pk_mul_f32 v[138:139], v[6:7], v[162:163]
	v_pk_mul_f32 v[186:187], v[8:9], v[162:163]
	v_pk_mul_f32 v[184:185], v[2:3], v[162:163]
	s_and_b64 vcc, exec, s[48:49]
	v_pk_mul_f32 v[188:189], v[4:5], v[162:163]
	global_store_dwordx4 v[136:137], v[130:133], off
	s_cbranch_vccnz .LBB0_566
	v_mul_f32_e32 v0, 0xbfb8aa3b, v138
	v_exp_f32_e32 v130, v0
	v_mul_f32_e32 v0, 0xbfb8aa3b, v139
	v_exp_f32_e32 v131, v0
	s_nop 0
	v_pk_add_f32 v[130:131], v[130:131], 1.0 op_sel_hi:[1,0]
	s_nop 0
	s_nop 0
	v_rcp_f32_e32 v139, v131
	s_nop 0
	s_nop 0
	v_rcp_f32_e32 v138, v130
	s_nop 0
	v_mul_f32_e32 v0, 0xbfb8aa3b, v186
	v_exp_f32_e32 v130, v0
	v_mul_f32_e32 v0, 0xbfb8aa3b, v187
	v_exp_f32_e32 v131, v0
	s_nop 0
	v_pk_add_f32 v[130:131], v[130:131], 1.0 op_sel_hi:[1,0]
	s_nop 0
	s_nop 0
	v_rcp_f32_e32 v187, v131
	s_nop 0
	s_nop 0
	v_rcp_f32_e32 v186, v130
	s_nop 0
	v_mul_f32_e32 v0, 0xbfb8aa3b, v184
	v_exp_f32_e32 v130, v0
	v_mul_f32_e32 v0, 0xbfb8aa3b, v185
	v_exp_f32_e32 v131, v0
	s_nop 0
	v_pk_add_f32 v[130:131], v[130:131], 1.0 op_sel_hi:[1,0]
	s_nop 0
	s_nop 0
	v_rcp_f32_e32 v185, v131
	s_nop 0
	s_nop 0
	v_rcp_f32_e32 v184, v130
	s_nop 0
	v_mul_f32_e32 v0, 0xbfb8aa3b, v188
	v_exp_f32_e32 v130, v0
	v_mul_f32_e32 v0, 0xbfb8aa3b, v189
	v_exp_f32_e32 v131, v0
	s_nop 0
	v_pk_add_f32 v[130:131], v[130:131], 1.0 op_sel_hi:[1,0]
	s_nop 0
	s_nop 0
	v_rcp_f32_e32 v189, v131
	s_nop 0
	s_nop 0
	v_rcp_f32_e32 v188, v130
	s_nop 0
	s_and_b64 vcc, exec, s[44:45]
	s_cbranch_vccnz .LBB0_566
	global_load_dwordx4 v[130:133], v[134:135], off offset:512
	global_load_dwordx4 v[192:195], v[134:135], off offset:528
	s_waitcnt vmcnt(1)
	v_pk_mul_f32 v[186:187], v[186:187], v[132:133]
	v_pk_mul_f32 v[138:139], v[138:139], v[130:131]
	s_waitcnt vmcnt(0)
	v_pk_mul_f32 v[188:189], v[188:189], v[194:195]
	v_pk_mul_f32 v[184:185], v[184:185], v[192:193]

; #define PG8_BAR __builtin_amdgcn_s_barrier()
; template <class Epi, class Sched, bool ALIGN_EPI = false, bool SP2 = false>
; __device__ __forceinline__ void gemm_phase(PG8_LAS unsigned char* lds, int tid_in, const Gemm g, const Sched& S, const Epi& E) {
;     ...
;         cur = nxt; cA = nA; cB = nB; ++ui;
;         if constexpr (ALIGN_EPI) { if (wr == 1) PG8_BAR; }
;     }
.LBB0_620:
	s_andn2_b64 vcc, exec, s[56:57]
	s_cbranch_vccnz .LBB0_269
	s_barrier
	s_branch .LBB0_269
	s_nop 0
	s_nop 0
	s_nop 0
	s_nop 0
	s_nop 0
	s_nop 0
	s_nop 0
	s_nop 0
	s_nop 0
	s_nop 0
	s_nop 0
	s_nop 0
	s_nop 0
	s_nop 0
	s_nop 0
	s_nop 0
	s_nop 0
	s_nop 0
	s_nop 0
	s_nop 0
	s_nop 0
	s_nop 0
	s_nop 0
	s_nop 0
	s_nop 0
	s_nop 0
	s_nop 0
	s_nop 0
	s_nop 0
	s_nop 0
	s_nop 0
	s_nop 0
	s_nop 0
	s_nop 0
	s_nop 0
	s_nop 0
	s_nop 0
	s_nop 0
	s_nop 0
	s_nop 0
	s_nop 0
	s_nop 0
	s_nop 0
	s_nop 0
	s_nop 0
	s_nop 0
	s_nop 0
	s_nop 0
	s_nop 0
	s_nop 0
	s_nop 0
	s_nop 0
	s_nop 0
	s_nop 0
	s_nop 0
	s_nop 0
	s_nop 0
	s_nop 0
	s_nop 0
	s_nop 0
	s_nop 0
	s_nop 0
	s_nop 0
	s_nop 0
	s_nop 0
	s_nop 0
	s_nop 0
	s_nop 0
	s_nop 0
	s_nop 0
	s_nop 0
	s_nop 0
	s_nop 0
	s_nop 0
	s_nop 0
	s_nop 0
	s_nop 0
	s_nop 0
	s_nop 0
	s_nop 0
	s_nop 0
	s_nop 0
	s_nop 0
	s_nop 0
	s_nop 0
	s_nop 0
	s_nop 0
	s_nop 0
	s_nop 0
	s_nop 0
	s_nop 0
	s_nop 0
	s_nop 0
	s_nop 0
	s_nop 0
	s_nop 0
	s_nop 0
	s_nop 0
	s_nop 0
	s_nop 0
	s_nop 0
	s_nop 0
	s_nop 0
	s_nop 0
	s_nop 0
	s_nop 0
	s_nop 0
	s_nop 0
	s_nop 0
	s_nop 0
	s_nop 0
	s_nop 0
	s_nop 0
	s_nop 0
	s_nop 0
	s_nop 0
	s_nop 0
	s_nop 0
	s_nop 0
	s_nop 0
	s_nop 0
	s_nop 0
	s_nop 0
	s_nop 0
	s_nop 0
	s_nop 0
	s_nop 0
	s_nop 0
	s_nop 0
	s_nop 0
	s_nop 0
	s_nop 0
	s_nop 0
	s_nop 0
	s_nop 0
	s_nop 0
	s_nop 0
	s_nop 0
	s_nop 0
	s_nop 0
	s_nop 0
	s_nop 0
	s_nop 0
	s_nop 0
	s_nop 0
	s_nop 0
	s_nop 0
	s_nop 0
	s_nop 0
	s_nop 0
	s_nop 0
	s_nop 0
	s_nop 0
	s_nop 0
	s_nop 0
	s_nop 0
	s_nop 0
	s_nop 0
	s_nop 0
	s_nop 0
	s_nop 0
	s_nop 0
	s_nop 0
	s_nop 0
	s_nop 0
	s_nop 0
	s_nop 0
	s_nop 0
	s_nop 0
	s_nop 0
	s_nop 0
	s_nop 0
	s_nop 0
	s_nop 0
	s_nop 0
	s_nop 0
	s_nop 0
	s_nop 0
	s_nop 0
	s_nop 0
	s_nop 0
	s_nop 0
	s_nop 0
	s_nop 0
	s_nop 0
	s_nop 0
	s_nop 0
	s_nop 0
	s_nop 0
	s_nop 0
	s_nop 0
	s_nop 0
	s_nop 0
	s_nop 0
	s_nop 0
	s_nop 0
	s_nop 0
	s_nop 0
	s_nop 0
	s_nop 0
	s_nop 0
	s_nop 0
	s_nop 0
	s_nop 0
	s_nop 0
	s_nop 0
	s_nop 0
	s_nop 0
	s_nop 0
	s_nop 0
	s_nop 0
	s_nop 0
	s_nop 0
	s_nop 0
	s_nop 0
	s_nop 0
	s_nop 0
	s_nop 0
	s_nop 0
	s_nop 0
	s_nop 0
	s_nop 0
	s_nop 0
	s_nop 0
	s_nop 0
	s_nop 0
	s_nop 0
	s_nop 0
	s_nop 0
	s_nop 0
	s_nop 0
	s_nop 0
	s_nop 0
	s_nop 0
	s_nop 0
	s_nop 0
	s_nop 0
	s_nop 0
	s_nop 0
	s_nop 0
	s_nop 0
	s_nop 0
	s_nop 0
	s_nop 0
	s_nop 0
	s_nop 0
	s_nop 0
	s_nop 0
	s_nop 0
	s_nop 0
	s_nop 0
	s_nop 0
	s_nop 0
	s_nop 0
	s_nop 0
	s_nop 0
	s_nop 0
	s_nop 0
	s_nop 0
	s_nop 0
	s_nop 0
	s_nop 0
	s_nop 0
	s_nop 0
	s_nop 0
	s_nop 0
	s_nop 0
	s_nop 0
	s_nop 0
	s_nop 0
	s_nop 0
	s_nop 0
	s_nop 0
	s_nop 0
	s_nop 0
	s_nop 0
	s_nop 0
	s_nop 0
	s_nop 0
	s_nop 0
	s_nop 0
	s_nop 0
	s_nop 0
	s_nop 0
	s_nop 0
	s_nop 0
	s_nop 0
	s_nop 0
	s_nop 0
	s_nop 0
	s_nop 0
	s_nop 0
	s_nop 0
	s_nop 0
	s_nop 0
	s_nop 0
	s_nop 0
	s_nop 0
	s_nop 0
	s_nop 0
	s_nop 0
	s_nop 0
	s_nop 0
	s_nop 0
	s_nop 0
	s_nop 0
	s_nop 0
	s_nop 0
	s_nop 0
	s_nop 0
	s_nop 0
	s_nop 0
	s_nop 0
	s_nop 0
	s_nop 0
	s_nop 0
	s_nop 0
	s_nop 0
	s_nop 0
	s_nop 0
	s_nop 0
	s_nop 0
	s_nop 0
	s_nop 0
	s_nop 0
	s_nop 0
	s_nop 0
	s_nop 0
	s_nop 0
	s_nop 0
	s_nop 0
	s_nop 0
	s_nop 0
	s_nop 0
	s_nop 0
	s_nop 0
	s_nop 0
	s_nop 0
	s_nop 0
	s_nop 0
	s_nop 0
	s_nop 0
	s_nop 0
	s_nop 0
	s_nop 0
	s_nop 0
	s_nop 0
	s_nop 0
	s_nop 0
	s_nop 0
	s_nop 0
	s_nop 0
	s_nop 0
	s_nop 0
	s_nop 0
	s_nop 0
	s_nop 0
	s_nop 0
	s_nop 0
	s_nop 0
	s_nop 0
	s_nop 0
	s_nop 0
	s_nop 0
	s_nop 0
	s_nop 0
	s_nop 0
	s_nop 0
	s_nop 0
	s_nop 0
	s_nop 0
	s_nop 0
	s_nop 0
	s_nop 0
	s_nop 0
	s_nop 0
	s_nop 0
	s_nop 0
	s_nop 0
	s_nop 0
	s_nop 0
	s_nop 0
	s_nop 0
	s_nop 0
	s_nop 0
	s_nop 0
	s_nop 0
	s_nop 0
	s_nop 0
	s_nop 0
	s_nop 0
	s_nop 0
	s_nop 0
	s_nop 0
	s_nop 0
	s_nop 0
	s_nop 0
	s_nop 0
	s_nop 0
	s_nop 0
	s_nop 0
	s_nop 0
	s_nop 0
	s_nop 0
	s_nop 0
	s_nop 0
	s_nop 0
	s_nop 0
	s_nop 0
	s_nop 0
	s_nop 0
	s_nop 0
	s_nop 0
	s_nop 0
	s_nop 0
	s_nop 0
	s_nop 0
	s_nop 0
	s_nop 0
	s_nop 0
	s_nop 0
	s_nop 0
	s_nop 0
	s_nop 0
	s_nop 0
	s_nop 0
	s_nop 0
	s_nop 0
	s_nop 0
	s_nop 0
	s_nop 0
	s_nop 0
	s_nop 0
	s_nop 0
	s_nop 0
	s_nop 0
	s_nop 0
	s_nop 0
	s_nop 0
	s_nop 0
	s_nop 0
	s_nop 0
	s_nop 0
	s_nop 0
	s_nop 0
	s_nop 0
	s_nop 0
	s_nop 0
	s_nop 0
	s_nop 0
	s_nop 0
	s_nop 0
	s_nop 0
	s_nop 0
	s_nop 0
	s_nop 0
	s_nop 0
	s_nop 0
	s_nop 0
	s_nop 0
	s_nop 0
	s_nop 0
	s_nop 0
	s_nop 0
	s_nop 0
	s_nop 0
	s_nop 0
	s_nop 0
	s_nop 0
	s_nop 0
	s_nop 0
	s_nop 0
	s_nop 0
	s_nop 0
	s_nop 0
	s_nop 0
	s_nop 0
	s_nop 0
	s_nop 0
	s_nop 0
	s_nop 0
	s_nop 0
	s_nop 0
	s_nop 0
	s_nop 0
	s_nop 0
	s_nop 0
	s_nop 0
	s_nop 0
	s_nop 0
	s_nop 0
	s_nop 0
	s_nop 0
	s_nop 0
	s_nop 0
	s_nop 0
	s_nop 0
	s_nop 0
	s_nop 0
	s_nop 0
	s_nop 0
	s_nop 0
	s_nop 0
	s_nop 0
	s_nop 0
	s_nop 0
	s_nop 0
	s_nop 0
	s_nop 0
	s_nop 0
	s_nop 0
	s_nop 0
	s_nop 0
	s_nop 0
	s_nop 0
	s_nop 0
	s_nop 0
	s_nop 0
	s_nop 0
	s_nop 0
	s_nop 0
	s_nop 0
	s_nop 0
	s_nop 0
	s_nop 0
	s_nop 0
	s_nop 0
	s_nop 0
	s_nop 0
	s_nop 0
	s_nop 0
	s_nop 0
	s_nop 0
	s_nop 0
	s_nop 0
	s_nop 0
	s_nop 0
	s_nop 0
	s_nop 0
	s_nop 0
	s_nop 0
	s_nop 0
	s_nop 0
	s_nop 0
	s_nop 0
	s_nop 0
	s_nop 0
	s_nop 0
	s_nop 0
	s_nop 0
	s_nop 0
	s_nop 0
	s_nop 0
	s_nop 0
	s_nop 0
	s_nop 0
	s_nop 0
	s_nop 0
	s_nop 0
	s_nop 0
	s_nop 0
	s_nop 0
	s_nop 0
	s_nop 0
	s_nop 0
	s_nop 0
	s_nop 0
	s_nop 0
	s_nop 0
	s_nop 0
	s_nop 0
	s_nop 0
	s_nop 0
	s_nop 0
	s_nop 0
	s_nop 0
	s_nop 0
	s_nop 0
	s_nop 0
	s_nop 0
	s_nop 0
	s_nop 0
	s_nop 0
	s_nop 0
	s_nop 0
	s_nop 0
	s_nop 0
	s_nop 0
	s_nop 0
	s_nop 0
	s_nop 0
	s_nop 0
	s_nop 0
	s_nop 0
	s_nop 0
	s_nop 0
	s_nop 0
	s_nop 0
	s_nop 0
	s_nop 0
	s_nop 0
	s_nop 0
	s_nop 0
	s_nop 0
	s_nop 0
	s_nop 0
	s_nop 0
	s_nop 0
	s_nop 0
	s_nop 0
	s_nop 0
	s_nop 0
	s_nop 0
	s_nop 0
	s_nop 0
; #define PG8_BAR __builtin_amdgcn_s_barrier()
; template <class Epi, class Sched, bool ALIGN_EPI = false, bool SP2 = false>
; __device__ __forceinline__ void gemm_phase(PG8_LAS unsigned char* lds, int tid_in, const Gemm g, const Sched& S, const Epi& E) {
;     ...
;         cur = nxt; cA = nA; cB = nB; ++ui;
;         if constexpr (ALIGN_EPI) { if (wr == 1) PG8_BAR; }
;     }
	s_nop 0
	s_nop 0
	s_nop 0
	s_nop 0
	s_nop 0
	s_nop 0
	s_nop 0
	s_nop 0
	s_nop 0
	s_nop 0
	s_nop 0
	s_nop 0
	s_nop 0
	s_nop 0
	s_nop 0
	s_nop 0
	s_nop 0
	s_nop 0
	s_nop 0
	s_nop 0
	s_nop 0
	s_nop 0
	s_nop 0
	s_nop 0
	s_nop 0
	s_nop 0
	s_nop 0
	s_nop 0
	s_nop 0
	s_nop 0
	s_nop 0
	s_nop 0
	s_nop 0
	s_nop 0
	s_nop 0
	s_nop 0
	s_nop 0
	s_nop 0
	s_nop 0
	s_nop 0
	s_nop 0
	s_nop 0
	s_nop 0
	s_nop 0
	s_nop 0
	s_nop 0
	s_nop 0
	s_nop 0
	s_nop 0
	s_nop 0
	s_nop 0
	s_nop 0
	s_nop 0
	s_nop 0
	s_nop 0
	s_nop 0
	s_nop 0
	s_nop 0
	s_nop 0
	s_nop 0
	s_nop 0
	s_nop 0
	s_nop 0
	s_nop 0
	s_nop 0
	s_nop 0
	s_nop 0
	s_nop 0
	s_nop 0
	s_nop 0
	s_nop 0
	s_nop 0
	s_nop 0
	s_nop 0
	s_nop 0
	s_nop 0
	s_nop 0
	s_nop 0
	s_nop 0
	s_nop 0
	s_nop 0
	s_nop 0
	s_nop 0
	s_nop 0
	s_nop 0
	s_nop 0
	s_nop 0
	s_nop 0
	s_nop 0
	s_nop 0
	s_nop 0
	s_nop 0
	s_nop 0
	s_nop 0
	s_nop 0
	s_nop 0
	s_nop 0
	s_nop 0
	s_nop 0
	s_nop 0
	s_nop 0
	s_nop 0
	s_nop 0
	s_nop 0
	s_nop 0
	s_nop 0
	s_nop 0
	s_nop 0
	s_nop 0
	s_nop 0
	s_nop 0
	s_nop 0
	s_nop 0
	s_nop 0
	s_nop 0
	s_nop 0
	s_nop 0
	s_nop 0
	s_nop 0
	s_nop 0
	s_nop 0
	s_nop 0
	s_nop 0
	s_nop 0
	s_nop 0
	s_nop 0
	s_nop 0
	s_nop 0
	s_nop 0
	s_nop 0
	s_nop 0
	s_nop 0
	s_nop 0
	s_nop 0
	s_nop 0
	s_nop 0
	s_nop 0
	s_nop 0
	s_nop 0
	s_nop 0
	s_nop 0
	s_nop 0
	s_nop 0
	s_nop 0
	s_nop 0
	s_nop 0
	s_nop 0
	s_nop 0
	s_nop 0
	s_nop 0
	s_nop 0
	s_nop 0
	s_nop 0
	s_nop 0
	s_nop 0
	s_nop 0
	s_nop 0
	s_nop 0
	s_nop 0
	s_nop 0
	s_nop 0
	s_nop 0
	s_nop 0
	s_nop 0
	s_nop 0
	s_nop 0
	s_nop 0
	s_nop 0
	s_nop 0
	s_nop 0
	s_nop 0
	s_nop 0
	s_nop 0
	s_nop 0
	s_nop 0
	s_nop 0
	s_nop 0
	s_nop 0
	s_nop 0
	s_nop 0
	s_nop 0
	s_nop 0
	s_nop 0
	s_nop 0
	s_nop 0
	s_nop 0
	s_nop 0
	s_nop 0
	s_nop 0
	s_nop 0
	s_nop 0
	s_nop 0
	s_nop 0
	s_nop 0
	s_nop 0
	s_nop 0
	s_nop 0
	s_nop 0
	s_nop 0
	s_nop 0
	s_nop 0
	s_nop 0
	s_nop 0
	s_nop 0
	s_nop 0
	s_nop 0
	s_nop 0
	s_nop 0
	s_nop 0
	s_nop 0
	s_nop 0
	s_nop 0
	s_nop 0
	s_nop 0
	s_nop 0
	s_nop 0
	s_nop 0
	s_nop 0
	s_nop 0
	s_nop 0
	s_nop 0
	s_nop 0
	s_nop 0
	s_nop 0
	s_nop 0
	s_nop 0
	s_nop 0
	s_nop 0
	s_nop 0
	s_nop 0
	s_nop 0
	s_nop 0
	s_nop 0
	s_nop 0
	s_nop 0
	s_nop 0
	s_nop 0
	s_nop 0
	s_nop 0
	s_nop 0
	s_nop 0
	s_nop 0
	s_nop 0
	s_nop 0
	s_nop 0
	s_nop 0
	s_nop 0
	s_nop 0
	s_nop 0
	s_nop 0
	s_nop 0
	s_nop 0
	s_nop 0
	s_nop 0
	s_nop 0
	s_nop 0
	s_nop 0
	s_nop 0
	s_nop 0
	s_nop 0
	s_nop 0
	s_nop 0
	s_nop 0
	s_nop 0
	s_nop 0
	s_nop 0
	s_nop 0
	s_nop 0
	s_nop 0
	s_nop 0
	s_nop 0
	s_nop 0
	s_nop 0
	s_nop 0
	s_nop 0
	s_nop 0
	s_nop 0
	s_nop 0
	s_nop 0
	s_nop 0
	s_nop 0
	s_nop 0
	s_nop 0
	s_nop 0
	s_nop 0
	s_nop 0
	s_nop 0
	s_nop 0
	s_nop 0
	s_nop 0
	s_nop 0
	s_nop 0
	s_nop 0
	s_nop 0
	s_nop 0
	s_nop 0
	s_nop 0
	s_nop 0
	s_nop 0
	s_nop 0
	s_nop 0
	s_nop 0
	s_nop 0
	s_nop 0
	s_nop 0
	s_nop 0
	s_nop 0
	s_nop 0
	s_nop 0
	s_nop 0
	s_nop 0
	s_nop 0
	s_nop 0
	s_nop 0
	s_nop 0
	s_nop 0
	s_nop 0
	s_nop 0
	s_nop 0
	s_nop 0
	s_nop 0
	s_nop 0
	s_nop 0
	s_nop 0
	s_nop 0
	s_nop 0
	s_nop 0
	s_nop 0
	s_nop 0
	s_nop 0
	s_nop 0
	s_nop 0
	s_nop 0
	s_nop 0
	s_nop 0
	s_nop 0
	s_nop 0
	s_nop 0
	s_nop 0
	s_nop 0
	s_nop 0
	s_nop 0
	s_nop 0
	s_nop 0
	s_nop 0
	s_nop 0
	s_nop 0
	s_nop 0
	s_nop 0
	s_nop 0
	s_nop 0
	s_nop 0
	s_nop 0
	s_nop 0
	s_nop 0
	s_nop 0
	s_nop 0
	s_nop 0
	s_nop 0
	s_nop 0
	s_nop 0
	s_nop 0
	s_nop 0
	s_nop 0
	s_nop 0
	s_nop 0
	s_nop 0
	s_nop 0
	s_nop 0
	s_nop 0
	s_nop 0
	s_nop 0
	s_nop 0
	s_nop 0
	s_nop 0
	s_nop 0
	s_nop 0
	s_nop 0
	s_nop 0
	s_nop 0
	s_nop 0
	s_nop 0
	s_nop 0
	s_nop 0
	s_nop 0
	s_nop 0
	s_nop 0
	s_nop 0
	s_nop 0
	s_nop 0
	s_nop 0
	s_nop 0
	s_nop 0
	s_nop 0
	s_nop 0
	s_nop 0
	s_nop 0
	s_nop 0
	s_nop 0
	s_nop 0
	s_nop 0
	s_nop 0
	s_nop 0
	s_nop 0
	s_nop 0
	s_nop 0
	s_nop 0
	s_nop 0
	s_nop 0
	s_nop 0
	s_nop 0
	s_nop 0
	s_nop 0
	s_nop 0
	s_nop 0
	s_nop 0
	s_nop 0
	s_nop 0
	s_nop 0
	s_nop 0
	s_nop 0
	s_nop 0
	s_nop 0
	s_nop 0
	s_nop 0
	s_nop 0
	s_nop 0
	s_nop 0
	s_nop 0
	s_nop 0
	s_nop 0
	s_nop 0
	s_nop 0
	s_nop 0
	s_nop 0
	s_nop 0
	s_nop 0
	s_nop 0
	s_nop 0
	s_nop 0
	s_nop 0
	s_nop 0
	s_nop 0
	s_nop 0
	s_nop 0
	s_nop 0
	s_nop 0
	s_nop 0
	s_nop 0
	s_nop 0
	s_nop 0
	s_nop 0
	s_nop 0
	s_nop 0
	s_nop 0
	s_nop 0
	s_nop 0
	s_nop 0
	s_nop 0
	s_nop 0
	s_nop 0
	s_nop 0
	s_nop 0
	s_nop 0
	s_nop 0
	s_nop 0
	s_nop 0
	s_nop 0
	s_nop 0
	s_nop 0
	s_nop 0
	s_nop 0
	s_nop 0
	s_nop 0
	s_nop 0
	s_nop 0
	s_nop 0
	s_nop 0
	s_nop 0
	s_nop 0
	s_nop 0
	s_nop 0
	s_nop 0
	s_nop 0
	s_nop 0
	s_nop 0
	s_nop 0
	s_nop 0
	s_nop 0
	s_nop 0
	s_nop 0
	s_nop 0
	s_nop 0
	s_nop 0
	s_nop 0
	s_nop 0
	s_nop 0
	s_nop 0
	s_nop 0
	s_nop 0
	s_nop 0
	s_nop 0
	s_nop 0
	s_nop 0
	s_nop 0
	s_nop 0
	s_nop 0
	s_nop 0
	s_nop 0
	s_nop 0
	s_nop 0
	s_nop 0
	s_nop 0
	s_nop 0
	s_nop 0
	s_nop 0
	s_nop 0
	s_nop 0
	s_nop 0
	s_nop 0
	s_nop 0
	s_nop 0
	s_nop 0
	s_nop 0
	s_nop 0
	s_nop 0
	s_nop 0
	s_nop 0
	s_nop 0
	s_nop 0
	s_nop 0
	s_nop 0
	s_nop 0
	s_nop 0
	s_nop 0
	s_nop 0
	s_nop 0
	s_nop 0
	s_nop 0
	s_nop 0
	s_nop 0
	s_nop 0
	s_nop 0
	s_nop 0
	s_nop 0
	s_nop 0
	s_nop 0
	s_nop 0
	s_nop 0
	s_nop 0
	s_nop 0
	s_nop 0
	s_nop 0
	s_nop 0
	s_nop 0
	s_nop 0
	s_nop 0
	s_nop 0
	s_nop 0
	s_nop 0
	s_nop 0
	s_nop 0
	s_nop 0
	s_nop 0
	s_nop 0
	s_nop 0
	s_nop 0
	s_nop 0
	s_nop 0
	s_nop 0
	s_nop 0
	s_nop 0
	s_nop 0
	s_nop 0
	s_nop 0
	s_nop 0
	s_nop 0
	s_nop 0
	s_nop 0
	s_nop 0
	s_nop 0
	s_nop 0
	s_nop 0
	s_nop 0
	s_nop 0
	s_nop 0
	s_nop 0
	s_nop 0
	s_nop 0
	s_nop 0
	s_nop 0
	s_nop 0
	s_nop 0
	s_nop 0
	s_nop 0
	s_nop 0
	s_nop 0
	s_nop 0
	s_nop 0
	s_nop 0
	s_nop 0
	s_nop 0
	s_nop 0
	s_nop 0
	s_nop 0
	s_nop 0
	s_nop 0
	s_nop 0
	s_nop 0
	s_nop 0
	s_nop 0
	s_nop 0
	s_nop 0
	s_nop 0
	s_nop 0
	s_nop 0
	s_nop 0
	s_nop 0
	s_nop 0
	s_nop 0
	s_nop 0
	s_nop 0
	s_nop 0
	s_nop 0
	s_nop 0
	s_nop 0
	s_nop 0
; #define PG8_BAR __builtin_amdgcn_s_barrier()
; template <class Epi, class Sched, bool ALIGN_EPI = false, bool SP2 = false>
; __device__ __forceinline__ void gemm_phase(PG8_LAS unsigned char* lds, int tid_in, const Gemm g, const Sched& S, const Epi& E) {
;     ...
;         cur = nxt; cA = nA; cB = nB; ++ui;
;         if constexpr (ALIGN_EPI) { if (wr == 1) PG8_BAR; }
;     }
	s_nop 0
	s_nop 0
	s_nop 0
	s_nop 0
	s_nop 0
	s_nop 0
	s_nop 0
	s_nop 0
	s_nop 0
	s_nop 0
	s_nop 0
	s_nop 0
	s_nop 0
	s_nop 0
	s_nop 0
	s_nop 0
	s_nop 0
	s_nop 0
	s_nop 0
	s_nop 0
	s_nop 0
	s_nop 0
	s_nop 0
	s_nop 0
	s_nop 0
	s_nop 0
	s_nop 0
	s_nop 0
	s_nop 0
	s_nop 0
	s_nop 0
	s_nop 0
	s_nop 0
	s_nop 0
	s_nop 0
	s_nop 0
	s_nop 0
	s_nop 0
	s_nop 0
	s_nop 0
	s_nop 0
	s_nop 0
	s_nop 0
	s_nop 0
	s_nop 0
	s_nop 0
	s_nop 0
	s_nop 0
	s_nop 0
	s_nop 0
	s_nop 0
	s_nop 0
	s_nop 0
	s_nop 0
	s_nop 0
	s_nop 0
	s_nop 0
	s_nop 0
	s_nop 0
	s_nop 0
	s_nop 0
	s_nop 0
	s_nop 0
	s_nop 0
	s_nop 0
	s_nop 0
	s_nop 0
	s_nop 0
	s_nop 0
	s_nop 0
	s_nop 0
	s_nop 0
	s_nop 0
	s_nop 0
	s_nop 0
	s_nop 0
	s_nop 0
	s_nop 0
	s_nop 0
	s_nop 0
	s_nop 0
	s_nop 0
	s_nop 0
	s_nop 0
	s_nop 0
	s_nop 0
	s_nop 0
	s_nop 0
	s_nop 0
	s_nop 0
	s_nop 0
	s_nop 0
	s_nop 0
	s_nop 0
	s_nop 0
	s_nop 0
	s_nop 0
	s_nop 0
	s_nop 0
	s_nop 0
	s_nop 0
	s_nop 0
	s_nop 0
	s_nop 0
	s_nop 0
	s_nop 0
	s_nop 0
	s_nop 0
	s_nop 0
	s_nop 0
	s_nop 0
	s_nop 0
	s_nop 0
	s_nop 0
	s_nop 0
	s_nop 0
	s_nop 0
	s_nop 0
	s_nop 0
	s_nop 0
	s_nop 0
	s_nop 0
	s_nop 0
	s_nop 0
	s_nop 0
	s_nop 0
	s_nop 0
	s_nop 0
	s_nop 0
	s_nop 0
	s_nop 0
	s_nop 0
	s_nop 0
	s_nop 0
	s_nop 0
	s_nop 0
	s_nop 0
	s_nop 0
	s_nop 0
	s_nop 0
	s_nop 0
	s_nop 0
	s_nop 0
	s_nop 0
	s_nop 0
	s_nop 0
	s_nop 0
	s_nop 0
	s_nop 0
	s_nop 0
	s_nop 0
	s_nop 0
	s_nop 0
	s_nop 0
	s_nop 0
	s_nop 0
	s_nop 0
	s_nop 0
	s_nop 0
	s_nop 0
	s_nop 0
	s_nop 0
	s_nop 0
	s_nop 0
	s_nop 0
	s_nop 0
	s_nop 0
	s_nop 0
	s_nop 0
	s_nop 0
	s_nop 0
	s_nop 0
	s_nop 0
	s_nop 0
	s_nop 0
	s_nop 0
	s_nop 0
	s_nop 0
	s_nop 0
	s_nop 0
	s_nop 0
	s_nop 0
	s_nop 0
	s_nop 0
	s_nop 0
	s_nop 0
	s_nop 0
	s_nop 0
	s_nop 0
	s_nop 0
	s_nop 0
	s_nop 0
	s_nop 0
	s_nop 0
	s_nop 0
	s_nop 0
	s_nop 0
	s_nop 0
	s_nop 0
	s_nop 0
	s_nop 0
	s_nop 0
	s_nop 0
	s_nop 0
	s_nop 0
	s_nop 0
	s_nop 0
	s_nop 0
	s_nop 0
	s_nop 0
	s_nop 0
	s_nop 0
	s_nop 0
	s_nop 0
	s_nop 0
	s_nop 0
	s_nop 0
	s_nop 0
	s_nop 0
	s_nop 0
	s_nop 0
	s_nop 0
	s_nop 0
	s_nop 0
	s_nop 0
	s_nop 0
	s_nop 0
	s_nop 0
	s_nop 0
	s_nop 0
	s_nop 0
	s_nop 0
	s_nop 0
	s_nop 0
	s_nop 0
	s_nop 0
	s_nop 0
	s_nop 0
	s_nop 0
	s_nop 0
	s_nop 0
	s_nop 0
	s_nop 0
	s_nop 0
	s_nop 0
	s_nop 0
	s_nop 0
	s_nop 0
	s_nop 0
	s_nop 0
	s_nop 0
	s_nop 0
	s_nop 0
	s_nop 0
	s_nop 0
	s_nop 0
	s_nop 0
	s_nop 0
	s_nop 0
	s_nop 0
	s_nop 0
	s_nop 0
	s_nop 0
	s_nop 0
	s_nop 0
	s_nop 0
	s_nop 0
	s_nop 0
	s_nop 0
	s_nop 0
	s_nop 0
	s_nop 0
	s_nop 0
	s_nop 0
	s_nop 0
	s_nop 0
	s_nop 0
	s_nop 0
	s_nop 0
	s_nop 0
	s_nop 0
	s_nop 0
	s_nop 0
	s_nop 0
	s_nop 0
	s_nop 0
	s_nop 0
	s_nop 0
	s_nop 0
	s_nop 0
	s_nop 0
	s_nop 0
	s_nop 0
	s_nop 0
	s_nop 0
	s_nop 0
	s_nop 0
	s_nop 0
	s_nop 0
	s_nop 0
	s_nop 0
	s_nop 0
	s_nop 0
	s_nop 0
	s_nop 0
	s_nop 0
	s_nop 0
	s_nop 0
	s_nop 0
	s_nop 0
	s_nop 0
	s_nop 0
	s_nop 0
	s_nop 0
	s_nop 0
	s_nop 0
	s_nop 0
	s_nop 0
	s_nop 0
	s_nop 0
	s_nop 0
	s_nop 0
	s_nop 0
	s_nop 0
	s_nop 0
	s_nop 0
	s_nop 0
	s_nop 0
	s_nop 0
	s_nop 0
	s_nop 0
	s_nop 0
	s_nop 0
	s_nop 0
	s_nop 0
	s_nop 0
	s_nop 0
	s_nop 0
	s_nop 0
	s_nop 0
	s_nop 0
	s_nop 0
	s_nop 0
	s_nop 0
	s_nop 0
	s_nop 0
	s_nop 0
	s_nop 0
	s_nop 0
	s_nop 0
	s_nop 0
	s_nop 0
	s_nop 0
	s_nop 0
	s_nop 0
	s_nop 0
	s_nop 0
	s_nop 0
	s_nop 0
	s_nop 0
	s_nop 0
	s_nop 0
	s_nop 0
	s_nop 0
	s_nop 0
	s_nop 0
	s_nop 0
	s_nop 0
	s_nop 0
	s_nop 0
	s_nop 0
	s_nop 0
	s_nop 0
	s_nop 0
	s_nop 0
	s_nop 0
	s_nop 0
	s_nop 0
	s_nop 0
	s_nop 0
	s_nop 0
	s_nop 0
	s_nop 0
	s_nop 0
	s_nop 0
	s_nop 0
	s_nop 0
	s_nop 0
	s_nop 0
	s_nop 0
	s_nop 0
	s_nop 0
	s_nop 0
	s_nop 0
	s_nop 0
	s_nop 0
	s_nop 0
	s_nop 0
	s_nop 0
	s_nop 0
	s_nop 0
	s_nop 0
	s_nop 0
; #define PG8_BAR __builtin_amdgcn_s_barrier()
; template <class Epi, class Sched, bool ALIGN_EPI = false, bool SP2 = false>
; __device__ __forceinline__ void gemm_phase(PG8_LAS unsigned char* lds, int tid_in, const Gemm g, const Sched& S, const Epi& E) {
;     ...
;         cur = nxt; cA = nA; cB = nB; ++ui;
;         if constexpr (ALIGN_EPI) { if (wr == 1) PG8_BAR; }
;     }
	s_nop 0
	s_nop 0
	s_nop 0
	s_nop 0
	s_nop 0
	s_nop 0
	s_nop 0
	s_nop 0
	s_nop 0
	s_nop 0
	s_nop 0
	s_nop 0
	s_nop 0
	s_nop 0
	s_nop 0
	s_nop 0
	s_nop 0
	s_nop 0
	s_nop 0
	s_nop 0
	s_nop 0
	s_nop 0
	s_nop 0
	s_nop 0
	s_nop 0
	s_nop 0
	s_nop 0
	s_nop 0
	s_nop 0
	s_nop 0
	s_nop 0
	s_nop 0
	s_nop 0
	s_nop 0
	s_nop 0
	s_nop 0
	s_nop 0
	s_nop 0
	s_nop 0
	s_nop 0
	s_nop 0
	s_nop 0
	s_nop 0
	s_nop 0
	s_nop 0
	s_nop 0
	s_nop 0
	s_nop 0
	s_nop 0
	s_nop 0
	s_nop 0
	s_nop 0
	s_nop 0
	s_nop 0
	s_nop 0
	s_nop 0
	s_nop 0
	s_nop 0
	s_nop 0
	s_nop 0
	s_nop 0
	s_nop 0
	s_nop 0
	s_nop 0
	s_nop 0
	s_nop 0
	s_nop 0
	s_nop 0
	s_nop 0
	s_nop 0
	s_nop 0
	s_nop 0
	s_nop 0
	s_nop 0
	s_nop 0
	s_nop 0
	s_nop 0
	s_nop 0
	s_nop 0
	s_nop 0
	s_nop 0
	s_nop 0
	s_nop 0
	s_nop 0
	s_nop 0
	s_nop 0
	s_nop 0
	s_nop 0
	s_nop 0
	s_nop 0
	s_nop 0
	s_nop 0
	s_nop 0
	s_nop 0
	s_nop 0
	s_nop 0
	s_nop 0
	s_nop 0
	s_nop 0
	s_nop 0
	s_nop 0
	s_nop 0
	s_nop 0
	s_nop 0
	s_nop 0
	s_nop 0
	s_nop 0
	s_nop 0
	s_nop 0
	s_nop 0
	s_nop 0
	s_nop 0
	s_nop 0
	s_nop 0
	s_nop 0
	s_nop 0
	s_nop 0
	s_nop 0
	s_nop 0
	s_nop 0
	s_nop 0
	s_nop 0
	s_nop 0
	s_nop 0
	s_nop 0
	s_nop 0
	s_nop 0
	s_nop 0
	s_nop 0
	s_nop 0
	s_nop 0
	s_nop 0
	s_nop 0
	s_nop 0
	s_nop 0
	s_nop 0
	s_nop 0
	s_nop 0
	s_nop 0
	s_nop 0
	s_nop 0
	s_nop 0
	s_nop 0
	s_nop 0
	s_nop 0
	s_nop 0
	s_nop 0
	s_nop 0
	s_nop 0
	s_nop 0
	s_nop 0
	s_nop 0
	s_nop 0
	s_nop 0
	s_nop 0
	s_nop 0
	s_nop 0
	s_nop 0
	s_nop 0
	s_nop 0
	s_nop 0
	s_nop 0
	s_nop 0
	s_nop 0
	s_nop 0
	s_nop 0
	s_nop 0
	s_nop 0
	s_nop 0
	s_nop 0
	s_nop 0
	s_nop 0
	s_nop 0
	s_nop 0
	s_nop 0
	s_nop 0
	s_nop 0
	s_nop 0
	s_nop 0
	s_nop 0
	s_nop 0
	s_nop 0
	s_nop 0
	s_nop 0
	s_nop 0
	s_nop 0
	s_nop 0
	s_nop 0
	s_nop 0
	s_nop 0
	s_nop 0
	s_nop 0
	s_nop 0
	s_nop 0
	s_nop 0
	s_nop 0
	s_nop 0
	s_nop 0
	s_nop 0
	s_nop 0
	s_nop 0
	s_nop 0
	s_nop 0
	s_nop 0
	s_nop 0
	s_nop 0
	s_nop 0
	s_nop 0
	s_nop 0
	s_nop 0
	s_nop 0
	s_nop 0
	s_nop 0
	s_nop 0
	s_nop 0
	s_nop 0
	s_nop 0
	s_nop 0
	s_nop 0
	s_nop 0
	s_nop 0
	s_nop 0
	s_nop 0
	s_nop 0
	s_nop 0
	s_nop 0
	s_nop 0
	s_nop 0
	s_nop 0
	s_nop 0
	s_nop 0
	s_nop 0
	s_nop 0
	s_nop 0
	s_nop 0
	s_nop 0
	s_nop 0
	s_nop 0
	s_nop 0
	s_nop 0
	s_nop 0
	s_nop 0
	s_nop 0
	s_nop 0
	s_nop 0
	s_nop 0
	s_nop 0
	s_nop 0
	s_nop 0
	s_nop 0
	s_nop 0
	s_nop 0
	s_nop 0
	s_nop 0
	s_nop 0
	s_nop 0
	s_nop 0
	s_nop 0
	s_nop 0
	s_nop 0
	s_nop 0
	s_nop 0
	s_nop 0
	s_nop 0
	s_nop 0
	s_nop 0
	s_nop 0
	s_nop 0
	s_nop 0
	s_nop 0
	s_nop 0
	s_nop 0
	s_nop 0
	s_nop 0
	s_nop 0
	s_nop 0
	s_nop 0
	s_nop 0
	s_nop 0
	s_nop 0
	s_nop 0
	s_nop 0
	s_nop 0
	s_nop 0
	s_nop 0
	s_nop 0
	s_nop 0
	s_nop 0
	s_nop 0
	s_nop 0
	s_nop 0
	s_nop 0
	s_nop 0
	s_nop 0
	s_nop 0
	s_nop 0
	s_nop 0
	s_nop 0
	s_nop 0
	s_nop 0
	s_nop 0
	s_nop 0
	s_nop 0
	s_nop 0
	s_nop 0
	s_nop 0
	s_nop 0
	s_nop 0
	s_nop 0
	s_nop 0
	s_nop 0
	s_nop 0
	s_nop 0
	s_nop 0
	s_nop 0
	s_nop 0
	s_nop 0
	s_nop 0
	s_nop 0
	s_nop 0
	s_nop 0
	s_nop 0
	s_nop 0
	s_nop 0
	s_nop 0
	s_nop 0
	s_nop 0
	s_nop 0
	s_nop 0
	s_nop 0
	s_nop 0
	s_nop 0
	s_nop 0
	s_nop 0
	s_nop 0
	s_nop 0
	s_nop 0
	s_nop 0
	s_nop 0
	s_nop 0
	s_nop 0
	s_nop 0
	s_nop 0
	s_nop 0
	s_nop 0
	s_nop 0
	s_nop 0
	s_nop 0
	s_nop 0
	s_nop 0
	s_nop 0
	s_nop 0
	s_nop 0
	s_nop 0
	s_nop 0
	s_nop 0
	s_nop 0
	s_nop 0
	s_nop 0
	s_nop 0
	s_nop 0
	s_nop 0
	s_nop 0
	s_nop 0
	s_nop 0
	s_nop 0
	s_nop 0
	s_nop 0
	s_nop 0
	s_nop 0
	s_nop 0
	s_nop 0
	s_nop 0
	s_nop 0
	s_nop 0
	s_nop 0
	s_nop 0
	s_nop 0
	s_nop 0
	s_nop 0
	s_nop 0
	s_nop 0
	s_nop 0
	s_nop 0
	s_nop 0
	s_nop 0
	s_nop 0
	s_nop 0
	s_nop 0
	s_nop 0
	s_nop 0
	s_nop 0
	s_nop 0
	s_nop 0
	s_nop 0
	s_nop 0
	s_nop 0
	s_nop 0
	s_nop 0
	s_nop 0
	s_nop 0
	s_nop 0
	s_nop 0

; __device__ __forceinline__ u32x4 pack8(const float (&f)[8]) { u32x4 w; w.x = pk2(f[0], f[1]); w.y = pk2(f[2], f[3]); w.z = pk2(f[4], f[5]); w.w = pk2(f[6], f[7]); return w; }
; __device__ __forceinline__ float sigm(float x) { return 1.f / (1.f + __expf(-x)); }
; __device__ __forceinline__ void qk_conv_item(int tid_in, int b, int strip, bf16_t* z1, const float* conv_qk) {
;     ...
;         for (int j = 0; j < 4; ++j) {
;             bf16_t* p = base + (size_t)(32 * blk + 8 * j + rl) * Z1_LD;
;             const u32x4 cur = cur4[j];
;             float x[8], y[8]; unpack8(cur, x);
; #pragma unroll
;             for (int e = 0; e < 8; ++e) y[e] = w[3][e] * x[e];
; #pragma unroll
;             for (int d = 1; d <= 3; ++d) {
;                 const u32x4 snd = (rl + d <= 7) ? cur : prev; const int src = (lane + 64 - 8 * d) & 63;
;                 u32x4 g; g.x = __shfl(snd.x, src); g.y = __shfl(snd.y, src); g.z = __shfl(snd.z, src); g.w = __shfl(snd.w, src);
;                 float xd[8]; unpack8(g, xd);
; #pragma unroll
;                 for (int e = 0; e < 8; ++e) y[e] += w[3 - d][e] * xd[e];
;             }
; #pragma unroll
;             for (int e = 0; e < 8; ++e) y[e] = y[e] * sigm(y[e]) * qs;
;             *(u32x4*)p = pack8(y);
;             prev = cur;
;         }
.LBB0_883:
	v_cndmask_b32_e64 v82, v46, v50, s[40:41]
	ds_bpermute_b32 v84, v78, v82
	v_cndmask_b32_e64 v99, v50, v46, s[42:43]
	v_cndmask_b32_e64 v50, v50, v46, s[44:45]
	ds_bpermute_b32 v99, v79, v99
	ds_bpermute_b32 v100, v80, v50
	v_cndmask_b32_e64 v82, v47, v51, s[40:41]
	ds_bpermute_b32 v88, v78, v82
	s_waitcnt lgkmcnt(3)
	v_lshlrev_b32_e32 v83, 16, v84
	v_lshlrev_b32_e32 v82, 16, v46
	v_cndmask_b32_e64 v50, v51, v47, s[44:45]
	v_cndmask_b32_e64 v81, v48, v52, s[40:41]
	v_pk_mul_f32 v[82:83], v[68:69], v[82:83]
	v_cndmask_b32_e64 v98, v51, v47, s[42:43]
	ds_bpermute_b32 v101, v80, v50
	s_waitcnt lgkmcnt(2)
	v_lshlrev_b32_e32 v51, 16, v100
	v_lshlrev_b32_e32 v50, 16, v99
	ds_bpermute_b32 v81, v78, v81
	ds_bpermute_b32 v98, v79, v98
	v_pk_mul_f32 v[50:51], v[66:67], v[50:51]
	v_add_f32_e32 v82, v82, v83
	v_and_b32_e32 v85, 0xffff0000, v84
	v_and_b32_e32 v84, 0xffff0000, v46
	v_add_f32_e32 v50, v82, v50
	v_pk_mul_f32 v[84:85], v[10:11], v[84:85]
	v_add_f32_e32 v82, v50, v51
	v_and_b32_e32 v51, 0xffff0000, v100
	v_and_b32_e32 v50, 0xffff0000, v99
	v_pk_mul_f32 v[50:51], v[6:7], v[50:51]
	v_add_f32_e32 v83, v84, v85
	s_waitcnt lgkmcnt(3)
	v_lshlrev_b32_e32 v87, 16, v88
	v_lshlrev_b32_e32 v86, 16, v47
	v_add_f32_e32 v50, v83, v50
	v_cndmask_b32_e64 v0, v49, v53, s[40:41]
	v_pk_mul_f32 v[86:87], v[64:65], v[86:87]
	s_waitcnt lgkmcnt(1)
	v_lshlrev_b32_e32 v91, 16, v81
	v_and_b32_e32 v93, 0xffff0000, v81
	v_cndmask_b32_e64 v81, v52, v48, s[42:43]
	v_cndmask_b32_e64 v52, v52, v48, s[44:45]
	v_add_f32_e32 v83, v50, v51
	v_lshlrev_b32_e32 v51, 16, v101
	s_waitcnt lgkmcnt(0)
	v_lshlrev_b32_e32 v50, 16, v98
	ds_bpermute_b32 v0, v78, v0
	ds_bpermute_b32 v81, v79, v81
	ds_bpermute_b32 v52, v80, v52
	v_pk_mul_f32 v[50:51], v[62:63], v[50:51]
	v_add_f32_e32 v84, v86, v87
	v_and_b32_e32 v89, 0xffff0000, v88
	v_and_b32_e32 v88, 0xffff0000, v47
	v_add_f32_e32 v50, v84, v50
	v_pk_mul_f32 v[88:89], v[12:13], v[88:89]
	v_add_f32_e32 v84, v50, v51
	v_and_b32_e32 v51, 0xffff0000, v101
	v_and_b32_e32 v50, 0xffff0000, v98
	v_pk_mul_f32 v[50:51], v[8:9], v[50:51]
	v_add_f32_e32 v85, v88, v89
	v_lshlrev_b32_e32 v90, 16, v48
	v_add_f32_e32 v50, v85, v50
	v_pk_mul_f32 v[90:91], v[60:61], v[90:91]
	s_waitcnt lgkmcnt(2)
	v_lshlrev_b32_e32 v95, 16, v0
	v_and_b32_e32 v97, 0xffff0000, v0
	v_cndmask_b32_e64 v0, v53, v49, s[42:43]
	v_cndmask_b32_e64 v53, v53, v49, s[44:45]
	v_add_f32_e32 v85, v50, v51
	s_waitcnt lgkmcnt(0)
	v_lshlrev_b32_e32 v51, 16, v52
	v_lshlrev_b32_e32 v50, 16, v81
	ds_bpermute_b32 v0, v79, v0
	ds_bpermute_b32 v53, v80, v53
	v_pk_mul_f32 v[50:51], v[58:59], v[50:51]
	v_add_f32_e32 v86, v90, v91
	v_and_b32_e32 v92, 0xffff0000, v48
	v_add_f32_e32 v50, v86, v50
	v_pk_mul_f32 v[92:93], v[14:15], v[92:93]
	v_add_f32_e32 v86, v50, v51
	v_and_b32_e32 v51, 0xffff0000, v52
	v_and_b32_e32 v50, 0xffff0000, v81
	v_pk_mul_f32 v[50:51], v[2:3], v[50:51]
	v_add_f32_e32 v52, v92, v93
	v_lshlrev_b32_e32 v94, 16, v49
	v_add_f32_e32 v50, v52, v50
	v_pk_mul_f32 v[94:95], v[56:57], v[94:95]
	v_add_f32_e32 v52, v50, v51
	s_waitcnt lgkmcnt(0)
	v_lshlrev_b32_e32 v51, 16, v53
	v_lshlrev_b32_e32 v50, 16, v0
	v_pk_mul_f32 v[50:51], v[54:55], v[50:51]
	v_add_f32_e32 v81, v94, v95
	v_add_f32_e32 v50, v81, v50
	v_add_f32_e32 v81, v50, v51
	v_mul_f32_e32 v50, 0xbfb8aa3b, v82
	v_exp_f32_e32 v87, v50
	v_and_b32_e32 v50, 0xffff0000, v0
	v_and_b32_e32 v51, 0xffff0000, v53
	v_and_b32_e32 v96, 0xffff0000, v49
	v_add_f32_e32 v0, 1.0, v87
	v_pk_mul_f32 v[96:97], v[16:17], v[96:97]
	v_pk_mul_f32 v[50:51], v[4:5], v[50:51]
	v_add_f32_e32 v88, v96, v97
	v_add_f32_e32 v50, v88, v50
	v_add_f32_e32 v50, v50, v51
	v_mul_f32_e32 v89, 0xbfb8aa3b, v83
	v_exp_f32_e32 v89, v89
	v_rcp_f32_e32 v0, v0
	s_nop 0
	v_add_f32_e32 v53, 1.0, v89
	v_mul_f32_e32 v0, v82, v0
	v_mul_f32_e32 v0, v77, v0
	v_cndmask_b32_e64 v95, v46, v42, s[42:43]
	v_mul_f32_e32 v89, 0xbfb8aa3b, v84
	v_exp_f32_e32 v89, v89
	v_rcp_f32_e32 v51, v53
	s_nop 0
	v_add_f32_e32 v82, 1.0, v89
	v_mul_f32_e32 v51, v83, v51
	v_mul_f32_e32 v51, v77, v51
	ds_bpermute_b32 v95, v79, v95
	v_mul_f32_e32 v89, 0xbfb8aa3b, v85
	v_exp_f32_e32 v89, v89
	v_rcp_f32_e32 v53, v82
	s_nop 0
	v_add_f32_e32 v83, 1.0, v89
	v_mul_f32_e32 v53, v84, v53
	v_mul_f32_e32 v53, v77, v53
	v_cndmask_b32_e64 v94, v47, v43, s[42:43]
	v_mul_f32_e32 v89, 0xbfb8aa3b, v86
	v_exp_f32_e32 v89, v89
	v_rcp_f32_e32 v82, v83
	s_nop 0
	v_add_f32_e32 v84, 1.0, v89
	v_mul_f32_e32 v82, v85, v82
	v_mul_f32_e32 v82, v77, v82
	ds_bpermute_b32 v94, v79, v94
	v_mul_f32_e32 v89, 0xbfb8aa3b, v52
	v_exp_f32_e32 v89, v89
	v_rcp_f32_e32 v83, v84
	s_nop 0
	v_add_f32_e32 v85, 1.0, v89
	v_mul_f32_e32 v83, v86, v83
	v_mul_f32_e32 v83, v77, v83
	v_lshlrev_b32_e32 v90, 16, v45
	v_mul_f32_e32 v89, 0xbfb8aa3b, v81
	v_exp_f32_e32 v89, v89
	v_rcp_f32_e32 v84, v85
	s_nop 0
	v_add_f32_e32 v86, 1.0, v89
	v_mul_f32_e32 v52, v52, v84
	v_mul_f32_e32 v52, v77, v52
	v_and_b32_e32 v92, 0xffff0000, v45
	v_mul_f32_e32 v89, 0xbfb8aa3b, v50
	v_exp_f32_e32 v89, v89
	v_rcp_f32_e32 v84, v86
	s_nop 0
	v_add_f32_e32 v85, 1.0, v89
	v_mul_f32_e32 v81, v81, v84
	s_mov_b32 s16, 0x6000000
	v_mul_f32_e32 v81, v77, v81
	v_rcp_f32_e32 v84, v85
	s_nop 0
	v_mul_f32_e32 v50, v50, v84
	v_mul_f32_e32 v84, v77, v50
	v_cvt_pk_bf16_f32 v50, v0, v51
	v_cvt_pk_bf16_f32 v51, v53, v82
	v_add_co_u32_e32 v82, vcc, s16, v72
	v_cvt_pk_bf16_f32 v52, v83, v52
	v_cvt_pk_bf16_f32 v53, v81, v84
	v_cndmask_b32_e64 v0, v45, v49, s[40:41]
	s_nop 0
	v_addc_co_u32_e32 v83, vcc, 0, v73, vcc
	global_store_dwordx4 v[82:83], v[50:53], off offset:2560
	v_lshlrev_b32_e32 v82, 16, v43
	ds_bpermute_b32 v0, v78, v0
	v_cndmask_b32_e64 v51, v42, v46, s[40:41]
	ds_bpermute_b32 v52, v78, v51
	v_cndmask_b32_e64 v46, v46, v42, s[44:45]
	ds_bpermute_b32 v96, v80, v46
	v_cndmask_b32_e64 v50, v44, v48, s[40:41]
	v_cndmask_b32_e64 v51, v43, v47, s[40:41]
	ds_bpermute_b32 v81, v78, v51
	ds_bpermute_b32 v88, v78, v50
	s_waitcnt lgkmcnt(3)
; __device__ __forceinline__ u32x4 pack8(const float (&f)[8]) { u32x4 w; w.x = pk2(f[0], f[1]); w.y = pk2(f[2], f[3]); w.z = pk2(f[4], f[5]); w.w = pk2(f[6], f[7]); return w; }
; __device__ __forceinline__ float sigm(float x) { return 1.f / (1.f + __expf(-x)); }
; __device__ __forceinline__ void qk_conv_item(int tid_in, int b, int strip, bf16_t* z1, const float* conv_qk) {
;     ...
;         for (int j = 0; j < 4; ++j) {
;             bf16_t* p = base + (size_t)(32 * blk + 8 * j + rl) * Z1_LD;
;             const u32x4 cur = cur4[j];
;             float x[8], y[8]; unpack8(cur, x);
; #pragma unroll
;             for (int e = 0; e < 8; ++e) y[e] = w[3][e] * x[e];
; #pragma unroll
;             for (int d = 1; d <= 3; ++d) {
;                 const u32x4 snd = (rl + d <= 7) ? cur : prev; const int src = (lane + 64 - 8 * d) & 63;
;                 u32x4 g; g.x = __shfl(snd.x, src); g.y = __shfl(snd.y, src); g.z = __shfl(snd.z, src); g.w = __shfl(snd.w, src);
;                 float xd[8]; unpack8(g, xd);
; #pragma unroll
;                 for (int e = 0; e < 8; ++e) y[e] += w[3 - d][e] * xd[e];
;             }
; #pragma unroll
;             for (int e = 0; e < 8; ++e) y[e] = y[e] * sigm(y[e]) * qs;
;             *(u32x4*)p = pack8(y);
;             prev = cur;
;         }
	v_lshlrev_b32_e32 v51, 16, v52
	v_lshlrev_b32_e32 v50, 16, v42
	v_cndmask_b32_e64 v46, v47, v43, s[44:45]
	v_pk_mul_f32 v[50:51], v[68:69], v[50:51]
	ds_bpermute_b32 v97, v80, v46
	s_waitcnt lgkmcnt(3)
	v_lshlrev_b32_e32 v47, 16, v96
	v_lshlrev_b32_e32 v46, 16, v95
	v_pk_mul_f32 v[46:47], v[66:67], v[46:47]
	v_add_f32_e32 v50, v50, v51
	v_and_b32_e32 v53, 0xffff0000, v52
	v_and_b32_e32 v52, 0xffff0000, v42
	v_add_f32_e32 v46, v50, v46
	v_pk_mul_f32 v[52:53], v[10:11], v[52:53]
	v_add_f32_e32 v50, v46, v47
	v_and_b32_e32 v47, 0xffff0000, v96
	v_and_b32_e32 v46, 0xffff0000, v95
	v_pk_mul_f32 v[46:47], v[6:7], v[46:47]
	v_add_f32_e32 v51, v52, v53
	s_waitcnt lgkmcnt(2)
	v_lshlrev_b32_e32 v83, 16, v81
	v_add_f32_e32 v46, v51, v46
	v_pk_mul_f32 v[82:83], v[64:65], v[82:83]
	v_and_b32_e32 v85, 0xffff0000, v81
	v_cndmask_b32_e64 v81, v48, v44, s[42:43]
	v_cndmask_b32_e64 v48, v48, v44, s[44:45]
	v_add_f32_e32 v51, v46, v47
	s_waitcnt lgkmcnt(0)
	v_lshlrev_b32_e32 v47, 16, v97
	v_lshlrev_b32_e32 v46, 16, v94
	ds_bpermute_b32 v81, v79, v81
	ds_bpermute_b32 v48, v80, v48
	v_pk_mul_f32 v[46:47], v[62:63], v[46:47]
	v_add_f32_e32 v52, v82, v83
	v_and_b32_e32 v84, 0xffff0000, v43
	v_add_f32_e32 v46, v52, v46
	v_pk_mul_f32 v[84:85], v[12:13], v[84:85]
	v_add_f32_e32 v52, v46, v47
	v_and_b32_e32 v47, 0xffff0000, v97
	v_and_b32_e32 v46, 0xffff0000, v94
	v_pk_mul_f32 v[46:47], v[8:9], v[46:47]
	v_add_f32_e32 v53, v84, v85
	v_lshlrev_b32_e32 v87, 16, v88
	v_lshlrev_b32_e32 v86, 16, v44
	v_add_f32_e32 v46, v53, v46
	v_pk_mul_f32 v[86:87], v[60:61], v[86:87]
	v_lshlrev_b32_e32 v91, 16, v0
	v_and_b32_e32 v93, 0xffff0000, v0
	v_cndmask_b32_e64 v0, v49, v45, s[42:43]
	v_cndmask_b32_e64 v49, v49, v45, s[44:45]
	v_add_f32_e32 v53, v46, v47
	s_waitcnt lgkmcnt(0)
	v_lshlrev_b32_e32 v47, 16, v48
	v_lshlrev_b32_e32 v46, 16, v81
	ds_bpermute_b32 v0, v79, v0
	ds_bpermute_b32 v49, v80, v49
	v_pk_mul_f32 v[46:47], v[58:59], v[46:47]
	v_add_f32_e32 v82, v86, v87
	v_and_b32_e32 v89, 0xffff0000, v88
	v_and_b32_e32 v88, 0xffff0000, v44
	v_add_f32_e32 v46, v82, v46
	v_pk_mul_f32 v[88:89], v[14:15], v[88:89]
	v_add_f32_e32 v82, v46, v47
	v_and_b32_e32 v47, 0xffff0000, v48
	v_and_b32_e32 v46, 0xffff0000, v81
	v_pk_mul_f32 v[46:47], v[2:3], v[46:47]
	v_add_f32_e32 v48, v88, v89
	v_add_f32_e32 v46, v48, v46
	v_pk_mul_f32 v[90:91], v[56:57], v[90:91]
	v_add_f32_e32 v48, v46, v47
	s_waitcnt lgkmcnt(0)
	v_lshlrev_b32_e32 v47, 16, v49
	v_lshlrev_b32_e32 v46, 16, v0
	v_pk_mul_f32 v[46:47], v[54:55], v[46:47]
	v_add_f32_e32 v81, v90, v91
	v_add_f32_e32 v46, v81, v46
	v_add_f32_e32 v81, v46, v47
	v_mul_f32_e32 v46, 0xbfb8aa3b, v50
	v_exp_f32_e32 v83, v46
	v_and_b32_e32 v46, 0xffff0000, v0
	v_and_b32_e32 v47, 0xffff0000, v49
	v_pk_mul_f32 v[92:93], v[16:17], v[92:93]
	v_add_f32_e32 v0, 1.0, v83
	v_pk_mul_f32 v[46:47], v[4:5], v[46:47]
	v_add_f32_e32 v84, v92, v93
	v_add_f32_e32 v46, v84, v46
	v_add_f32_e32 v46, v46, v47
	v_mul_f32_e32 v85, 0xbfb8aa3b, v51
	v_exp_f32_e32 v85, v85
	v_rcp_f32_e32 v0, v0
	s_nop 0
	v_add_f32_e32 v49, 1.0, v85
	v_mul_f32_e32 v0, v50, v0
	v_mul_f32_e32 v0, v77, v0
	v_cndmask_b32_e64 v91, v42, v38, s[42:43]
	v_mul_f32_e32 v85, 0xbfb8aa3b, v52
	v_exp_f32_e32 v85, v85
	v_rcp_f32_e32 v47, v49
	s_nop 0
	v_add_f32_e32 v50, 1.0, v85
	v_mul_f32_e32 v47, v51, v47
	v_mul_f32_e32 v47, v77, v47
	ds_bpermute_b32 v91, v79, v91
	v_mul_f32_e32 v85, 0xbfb8aa3b, v53
	v_exp_f32_e32 v85, v85
	v_rcp_f32_e32 v49, v50
	s_nop 0
	v_add_f32_e32 v51, 1.0, v85
	v_mul_f32_e32 v49, v52, v49
	v_mul_f32_e32 v49, v77, v49
	v_cndmask_b32_e64 v90, v43, v39, s[42:43]
	v_mul_f32_e32 v85, 0xbfb8aa3b, v82
	v_exp_f32_e32 v85, v85
	v_rcp_f32_e32 v50, v51
	s_nop 0
	v_add_f32_e32 v52, 1.0, v85
	v_mul_f32_e32 v50, v53, v50
	v_mul_f32_e32 v50, v77, v50
	ds_bpermute_b32 v90, v79, v90
	v_mul_f32_e32 v85, 0xbfb8aa3b, v48
	v_exp_f32_e32 v85, v85
	v_rcp_f32_e32 v51, v52
	s_nop 0
	v_add_f32_e32 v53, 1.0, v85
	v_mul_f32_e32 v51, v82, v51
	v_mul_f32_e32 v51, v77, v51
	v_lshlrev_b32_e32 v86, 16, v41
	v_mul_f32_e32 v85, 0xbfb8aa3b, v81
	v_exp_f32_e32 v85, v85
	v_rcp_f32_e32 v52, v53
	s_nop 0
	v_add_f32_e32 v82, 1.0, v85
	v_mul_f32_e32 v48, v48, v52
	v_mul_f32_e32 v48, v77, v48
	v_and_b32_e32 v88, 0xffff0000, v41
	v_mul_f32_e32 v85, 0xbfb8aa3b, v46
	v_exp_f32_e32 v85, v85
	v_rcp_f32_e32 v52, v82
	s_nop 0
	v_add_f32_e32 v53, 1.0, v85
	v_mul_f32_e32 v52, v81, v52
	s_mov_b32 s16, 0x600d000
	v_mul_f32_e32 v52, v77, v52
	v_rcp_f32_e32 v53, v53
	s_nop 0
	v_mul_f32_e32 v46, v46, v53
	v_mul_f32_e32 v53, v77, v46
	v_cvt_pk_bf16_f32 v46, v0, v47
	v_cvt_pk_bf16_f32 v47, v49, v50
	v_add_co_u32_e32 v50, vcc, s16, v72
	v_cvt_pk_bf16_f32 v48, v51, v48
	v_cvt_pk_bf16_f32 v49, v52, v53
	v_cndmask_b32_e64 v0, v41, v45, s[40:41]
	s_nop 0
	v_addc_co_u32_e32 v51, vcc, 0, v73, vcc
	global_store_dwordx4 v[50:51], v[46:49], off offset:2560
	v_lshlrev_b32_e32 v50, 16, v39
	ds_bpermute_b32 v0, v78, v0
	v_cndmask_b32_e64 v47, v38, v42, s[40:41]
	ds_bpermute_b32 v48, v78, v47
	v_cndmask_b32_e64 v42, v42, v38, s[44:45]
	ds_bpermute_b32 v92, v80, v42
	v_cndmask_b32_e64 v46, v40, v44, s[40:41]
	v_cndmask_b32_e64 v47, v39, v43, s[40:41]
	ds_bpermute_b32 v52, v78, v47
	ds_bpermute_b32 v81, v78, v46
	s_waitcnt lgkmcnt(3)
	v_lshlrev_b32_e32 v47, 16, v48
	v_lshlrev_b32_e32 v46, 16, v38
	v_cndmask_b32_e64 v42, v43, v39, s[44:45]
	v_pk_mul_f32 v[46:47], v[68:69], v[46:47]
	ds_bpermute_b32 v93, v80, v42
	s_waitcnt lgkmcnt(3)
; __device__ __forceinline__ float sigm(float x) { return 1.f / (1.f + __expf(-x)); }
; __device__ __forceinline__ u32x4 pack8(const float (&f)[8]) { u32x4 w; w.x = pk2(f[0], f[1]); w.y = pk2(f[2], f[3]); w.z = pk2(f[4], f[5]); w.w = pk2(f[6], f[7]); return w; }
; __device__ __forceinline__ void qk_conv_item(int tid_in, int b, int strip, bf16_t* z1, const float* conv_qk) {
;     ...
;         for (int j = 0; j < 4; ++j) {
;             bf16_t* p = base + (size_t)(32 * blk + 8 * j + rl) * Z1_LD;
;             const u32x4 cur = cur4[j];
;             float x[8], y[8]; unpack8(cur, x);
; #pragma unroll
;             for (int e = 0; e < 8; ++e) y[e] = w[3][e] * x[e];
; #pragma unroll
;             for (int d = 1; d <= 3; ++d) {
;                 const u32x4 snd = (rl + d <= 7) ? cur : prev; const int src = (lane + 64 - 8 * d) & 63;
;                 u32x4 g; g.x = __shfl(snd.x, src); g.y = __shfl(snd.y, src); g.z = __shfl(snd.z, src); g.w = __shfl(snd.w, src);
;                 float xd[8]; unpack8(g, xd);
; #pragma unroll
;                 for (int e = 0; e < 8; ++e) y[e] += w[3 - d][e] * xd[e];
;             }
; #pragma unroll
;             for (int e = 0; e < 8; ++e) y[e] = y[e] * sigm(y[e]) * qs;
;             *(u32x4*)p = pack8(y);
;             prev = cur;
	v_lshlrev_b32_e32 v43, 16, v92
	v_lshlrev_b32_e32 v42, 16, v91
	v_pk_mul_f32 v[42:43], v[66:67], v[42:43]
	v_add_f32_e32 v46, v46, v47
	v_and_b32_e32 v49, 0xffff0000, v48
	v_and_b32_e32 v48, 0xffff0000, v38
	v_add_f32_e32 v42, v46, v42
	v_pk_mul_f32 v[48:49], v[10:11], v[48:49]
	v_add_f32_e32 v46, v42, v43
	v_and_b32_e32 v43, 0xffff0000, v92
	v_and_b32_e32 v42, 0xffff0000, v91
	v_pk_mul_f32 v[42:43], v[6:7], v[42:43]
	v_add_f32_e32 v47, v48, v49
	s_waitcnt lgkmcnt(2)
	v_lshlrev_b32_e32 v51, 16, v52
	v_add_f32_e32 v42, v47, v42
	v_pk_mul_f32 v[50:51], v[64:65], v[50:51]
	s_waitcnt lgkmcnt(1)
	v_lshlrev_b32_e32 v83, 16, v81
	v_and_b32_e32 v85, 0xffff0000, v81
	v_cndmask_b32_e64 v81, v44, v40, s[42:43]
	v_cndmask_b32_e64 v44, v44, v40, s[44:45]
	v_add_f32_e32 v47, v42, v43
	s_waitcnt lgkmcnt(0)
	v_lshlrev_b32_e32 v43, 16, v93
	v_lshlrev_b32_e32 v42, 16, v90
	ds_bpermute_b32 v81, v79, v81
	ds_bpermute_b32 v44, v80, v44
	v_pk_mul_f32 v[42:43], v[62:63], v[42:43]
	v_add_f32_e32 v48, v50, v51
	v_and_b32_e32 v53, 0xffff0000, v52
	v_and_b32_e32 v52, 0xffff0000, v39
	v_add_f32_e32 v42, v48, v42
	v_pk_mul_f32 v[52:53], v[12:13], v[52:53]
	v_add_f32_e32 v48, v42, v43
	v_and_b32_e32 v43, 0xffff0000, v93
	v_and_b32_e32 v42, 0xffff0000, v90
	v_pk_mul_f32 v[42:43], v[8:9], v[42:43]
	v_add_f32_e32 v49, v52, v53
	v_lshlrev_b32_e32 v82, 16, v40
	v_add_f32_e32 v42, v49, v42
	v_pk_mul_f32 v[82:83], v[60:61], v[82:83]
	v_lshlrev_b32_e32 v87, 16, v0
	v_and_b32_e32 v89, 0xffff0000, v0
	v_cndmask_b32_e64 v0, v45, v41, s[42:43]
	v_cndmask_b32_e64 v45, v45, v41, s[44:45]
	v_add_f32_e32 v49, v42, v43
	s_waitcnt lgkmcnt(0)
	v_lshlrev_b32_e32 v43, 16, v44
	v_lshlrev_b32_e32 v42, 16, v81
	ds_bpermute_b32 v0, v79, v0
	ds_bpermute_b32 v45, v80, v45
	v_pk_mul_f32 v[42:43], v[58:59], v[42:43]
	v_add_f32_e32 v50, v82, v83
	v_and_b32_e32 v84, 0xffff0000, v40
	v_add_f32_e32 v42, v50, v42
	v_pk_mul_f32 v[84:85], v[14:15], v[84:85]
	v_add_f32_e32 v50, v42, v43
	v_and_b32_e32 v43, 0xffff0000, v44
	v_and_b32_e32 v42, 0xffff0000, v81
	v_pk_mul_f32 v[42:43], v[2:3], v[42:43]
	v_add_f32_e32 v44, v84, v85
	v_add_f32_e32 v42, v44, v42
	v_pk_mul_f32 v[86:87], v[56:57], v[86:87]
	v_add_f32_e32 v44, v42, v43
	s_waitcnt lgkmcnt(0)
	v_lshlrev_b32_e32 v43, 16, v45
	v_lshlrev_b32_e32 v42, 16, v0
	v_pk_mul_f32 v[42:43], v[54:55], v[42:43]
	v_add_f32_e32 v51, v86, v87
	v_add_f32_e32 v42, v51, v42
	v_add_f32_e32 v51, v42, v43
	v_mul_f32_e32 v42, 0xbfb8aa3b, v46
	v_exp_f32_e32 v52, v42
	v_and_b32_e32 v42, 0xffff0000, v0
	v_and_b32_e32 v43, 0xffff0000, v45
	v_pk_mul_f32 v[88:89], v[16:17], v[88:89]
	v_add_f32_e32 v0, 1.0, v52
	v_pk_mul_f32 v[42:43], v[4:5], v[42:43]
	v_add_f32_e32 v53, v88, v89
	v_add_f32_e32 v42, v53, v42
	v_add_f32_e32 v42, v42, v43
	v_mul_f32_e32 v81, 0xbfb8aa3b, v47
	v_exp_f32_e32 v81, v81
	v_rcp_f32_e32 v0, v0
	s_nop 0
	v_add_f32_e32 v45, 1.0, v81
	v_mul_f32_e32 v0, v46, v0
	v_mul_f32_e32 v0, v77, v0
	v_cndmask_b32_e64 v87, v38, v22, s[42:43]
	v_mul_f32_e32 v81, 0xbfb8aa3b, v48
	v_exp_f32_e32 v81, v81
	v_rcp_f32_e32 v43, v45
	s_nop 0
	v_add_f32_e32 v46, 1.0, v81
	v_mul_f32_e32 v43, v47, v43
	v_mul_f32_e32 v43, v77, v43
	ds_bpermute_b32 v87, v79, v87
	v_mul_f32_e32 v81, 0xbfb8aa3b, v49
	v_exp_f32_e32 v81, v81
	v_rcp_f32_e32 v45, v46
	s_nop 0
	v_add_f32_e32 v47, 1.0, v81
	v_mul_f32_e32 v45, v48, v45
	v_mul_f32_e32 v45, v77, v45
	v_cndmask_b32_e64 v86, v39, v23, s[42:43]
	v_mul_f32_e32 v81, 0xbfb8aa3b, v50
	v_exp_f32_e32 v81, v81
	v_rcp_f32_e32 v46, v47
	s_nop 0
	v_add_f32_e32 v48, 1.0, v81
	v_mul_f32_e32 v46, v49, v46
	v_mul_f32_e32 v46, v77, v46
	ds_bpermute_b32 v86, v79, v86
	v_mul_f32_e32 v81, 0xbfb8aa3b, v44
	v_exp_f32_e32 v81, v81
	v_rcp_f32_e32 v47, v48
	s_nop 0
	v_add_f32_e32 v49, 1.0, v81
	v_mul_f32_e32 v47, v50, v47
	v_mul_f32_e32 v47, v77, v47
	v_lshlrev_b32_e32 v82, 16, v25
	v_mul_f32_e32 v81, 0xbfb8aa3b, v51
	v_exp_f32_e32 v81, v81
	v_rcp_f32_e32 v48, v49
	s_nop 0
	v_add_f32_e32 v50, 1.0, v81
	v_mul_f32_e32 v44, v44, v48
	v_mul_f32_e32 v44, v77, v44
	v_and_b32_e32 v84, 0xffff0000, v25
	v_mul_f32_e32 v81, 0xbfb8aa3b, v42
	v_exp_f32_e32 v81, v81
	v_rcp_f32_e32 v48, v50
	s_nop 0
	v_add_f32_e32 v49, 1.0, v81
	v_mul_f32_e32 v48, v51, v48
	s_mov_b32 s16, 0x601a000
	v_mul_f32_e32 v48, v77, v48
	v_rcp_f32_e32 v49, v49
	s_nop 0
	v_mul_f32_e32 v42, v42, v49
	v_mul_f32_e32 v49, v77, v42
	v_cvt_pk_bf16_f32 v42, v0, v43
	v_cvt_pk_bf16_f32 v43, v45, v46
	v_add_co_u32_e32 v46, vcc, s16, v72
	v_cvt_pk_bf16_f32 v44, v47, v44
	v_cvt_pk_bf16_f32 v45, v48, v49
	v_cndmask_b32_e64 v0, v25, v41, s[40:41]
	s_nop 0
	v_addc_co_u32_e32 v47, vcc, 0, v73, vcc
	global_store_dwordx4 v[46:47], v[42:45], off offset:2560
	v_lshlrev_b32_e32 v46, 16, v23
	v_cndmask_b32_e64 v81, v40, v24, s[42:43]
	v_cndmask_b32_e64 v43, v22, v38, s[40:41]
	ds_bpermute_b32 v44, v78, v43
	v_cndmask_b32_e64 v38, v38, v22, s[44:45]
	ds_bpermute_b32 v88, v80, v38
	v_cndmask_b32_e64 v42, v24, v40, s[40:41]
	v_cndmask_b32_e64 v43, v23, v39, s[40:41]
	ds_bpermute_b32 v48, v78, v43
	ds_bpermute_b32 v52, v78, v42
	s_waitcnt lgkmcnt(3)
; __device__ __forceinline__ float sigm(float x) { return 1.f / (1.f + __expf(-x)); }
; __device__ __forceinline__ u32x4 pack8(const float (&f)[8]) { u32x4 w; w.x = pk2(f[0], f[1]); w.y = pk2(f[2], f[3]); w.z = pk2(f[4], f[5]); w.w = pk2(f[6], f[7]); return w; }
; __device__ __forceinline__ void qk_conv_item(int tid_in, int b, int strip, bf16_t* z1, const float* conv_qk) {
;     ...
;         for (int j = 0; j < 4; ++j) {
;             bf16_t* p = base + (size_t)(32 * blk + 8 * j + rl) * Z1_LD;
;             const u32x4 cur = cur4[j];
;             float x[8], y[8]; unpack8(cur, x);
; #pragma unroll
;             for (int e = 0; e < 8; ++e) y[e] = w[3][e] * x[e];
; #pragma unroll
;             for (int d = 1; d <= 3; ++d) {
;                 const u32x4 snd = (rl + d <= 7) ? cur : prev; const int src = (lane + 64 - 8 * d) & 63;
;                 u32x4 g; g.x = __shfl(snd.x, src); g.y = __shfl(snd.y, src); g.z = __shfl(snd.z, src); g.w = __shfl(snd.w, src);
;                 float xd[8]; unpack8(g, xd);
; #pragma unroll
;                 for (int e = 0; e < 8; ++e) y[e] += w[3 - d][e] * xd[e];
;             }
; #pragma unroll
;             for (int e = 0; e < 8; ++e) y[e] = y[e] * sigm(y[e]) * qs;
;             *(u32x4*)p = pack8(y);
;             prev = cur;
;         }
; #pragma unroll
;         for (int j = 0; j < 4; ++j) cur4[j] = nxt4[j];
	v_lshlrev_b32_e32 v43, 16, v44
	v_lshlrev_b32_e32 v42, 16, v22
	v_cndmask_b32_e64 v38, v39, v23, s[44:45]
	v_pk_mul_f32 v[42:43], v[68:69], v[42:43]
	ds_bpermute_b32 v89, v80, v38
	s_waitcnt lgkmcnt(3)
	v_lshlrev_b32_e32 v39, 16, v88
	v_lshlrev_b32_e32 v38, 16, v87
	v_pk_mul_f32 v[38:39], v[66:67], v[38:39]
	v_add_f32_e32 v42, v42, v43
	v_and_b32_e32 v45, 0xffff0000, v44
	v_and_b32_e32 v44, 0xffff0000, v22
	v_add_f32_e32 v38, v42, v38
	v_pk_mul_f32 v[44:45], v[10:11], v[44:45]
	v_add_f32_e32 v42, v38, v39
	v_and_b32_e32 v39, 0xffff0000, v88
	v_and_b32_e32 v38, 0xffff0000, v87
	v_pk_mul_f32 v[38:39], v[6:7], v[38:39]
	v_add_f32_e32 v43, v44, v45
	s_waitcnt lgkmcnt(2)
	v_lshlrev_b32_e32 v47, 16, v48
	v_add_f32_e32 v38, v43, v38
	v_pk_mul_f32 v[46:47], v[64:65], v[46:47]
	v_cndmask_b32_e64 v40, v40, v24, s[44:45]
	v_add_f32_e32 v43, v38, v39
	s_waitcnt lgkmcnt(0)
	v_lshlrev_b32_e32 v39, 16, v89
	v_lshlrev_b32_e32 v38, 16, v86
	ds_bpermute_b32 v0, v78, v0
	ds_bpermute_b32 v81, v79, v81
	ds_bpermute_b32 v40, v80, v40
	v_pk_mul_f32 v[38:39], v[62:63], v[38:39]
	v_add_f32_e32 v44, v46, v47
	v_and_b32_e32 v49, 0xffff0000, v48
	v_and_b32_e32 v48, 0xffff0000, v23
	v_add_f32_e32 v38, v44, v38
	v_pk_mul_f32 v[48:49], v[12:13], v[48:49]
	v_add_f32_e32 v44, v38, v39
	v_and_b32_e32 v39, 0xffff0000, v89
	v_and_b32_e32 v38, 0xffff0000, v86
	v_pk_mul_f32 v[38:39], v[8:9], v[38:39]
	v_add_f32_e32 v45, v48, v49
	v_lshlrev_b32_e32 v51, 16, v52
	v_lshlrev_b32_e32 v50, 16, v24
	v_add_f32_e32 v38, v45, v38
	v_pk_mul_f32 v[50:51], v[60:61], v[50:51]
	s_waitcnt lgkmcnt(2)
	v_lshlrev_b32_e32 v83, 16, v0
	v_and_b32_e32 v85, 0xffff0000, v0
	v_cndmask_b32_e64 v0, v41, v25, s[42:43]
	v_cndmask_b32_e64 v41, v41, v25, s[44:45]
	v_add_f32_e32 v45, v38, v39
	s_waitcnt lgkmcnt(0)
	v_lshlrev_b32_e32 v39, 16, v40
	v_lshlrev_b32_e32 v38, 16, v81
	ds_bpermute_b32 v0, v79, v0
	ds_bpermute_b32 v41, v80, v41
	v_pk_mul_f32 v[38:39], v[58:59], v[38:39]
	v_add_f32_e32 v46, v50, v51
	v_and_b32_e32 v53, 0xffff0000, v52
	v_and_b32_e32 v52, 0xffff0000, v24
	v_add_f32_e32 v38, v46, v38
	v_pk_mul_f32 v[52:53], v[14:15], v[52:53]
	v_add_f32_e32 v46, v38, v39
	v_and_b32_e32 v39, 0xffff0000, v40
	v_and_b32_e32 v38, 0xffff0000, v81
	v_pk_mul_f32 v[38:39], v[2:3], v[38:39]
	v_add_f32_e32 v40, v52, v53
	v_add_f32_e32 v38, v40, v38
	v_pk_mul_f32 v[82:83], v[56:57], v[82:83]
	v_add_f32_e32 v40, v38, v39
	s_waitcnt lgkmcnt(0)
	v_lshlrev_b32_e32 v39, 16, v41
	v_lshlrev_b32_e32 v38, 16, v0
	v_pk_mul_f32 v[38:39], v[54:55], v[38:39]
	v_add_f32_e32 v47, v82, v83
	v_add_f32_e32 v38, v47, v38
	v_add_f32_e32 v47, v38, v39
	v_mul_f32_e32 v38, 0xbfb8aa3b, v42
	v_exp_f32_e32 v48, v38
	v_and_b32_e32 v38, 0xffff0000, v0
	v_and_b32_e32 v39, 0xffff0000, v41
	v_pk_mul_f32 v[84:85], v[16:17], v[84:85]
	v_add_f32_e32 v0, 1.0, v48
	v_pk_mul_f32 v[38:39], v[4:5], v[38:39]
	v_add_f32_e32 v49, v84, v85
	v_add_f32_e32 v38, v49, v38
	v_add_f32_e32 v38, v38, v39
	v_mul_f32_e32 v50, 0xbfb8aa3b, v43
	v_exp_f32_e32 v50, v50
	v_rcp_f32_e32 v0, v0
	s_nop 0
	v_add_f32_e32 v41, 1.0, v50
	v_mul_f32_e32 v0, v42, v0
	v_mul_f32_e32 v0, v77, v0
	s_add_u32 s6, s6, 0x34000
	v_mul_f32_e32 v50, 0xbfb8aa3b, v44
	v_exp_f32_e32 v50, v50
	v_rcp_f32_e32 v39, v41
	s_nop 0
	v_add_f32_e32 v42, 1.0, v50
	v_mul_f32_e32 v39, v43, v39
	v_mul_f32_e32 v39, v77, v39
	s_addc_u32 s7, s7, 0
	v_mul_f32_e32 v50, 0xbfb8aa3b, v45
	v_exp_f32_e32 v50, v50
	v_rcp_f32_e32 v41, v42
	s_nop 0
	v_add_f32_e32 v43, 1.0, v50
	v_mul_f32_e32 v41, v44, v41
	v_mul_f32_e32 v41, v77, v41
	s_cmp_lg_u32 s6, 0x340000
	v_mul_f32_e32 v50, 0xbfb8aa3b, v46
	v_exp_f32_e32 v50, v50
	v_rcp_f32_e32 v42, v43
	s_nop 0
	v_add_f32_e32 v44, 1.0, v50
	v_mul_f32_e32 v42, v45, v42
	v_mul_f32_e32 v42, v77, v42
	v_mul_f32_e32 v50, 0xbfb8aa3b, v40
	v_exp_f32_e32 v50, v50
	v_rcp_f32_e32 v43, v44
	s_nop 0
	v_add_f32_e32 v45, 1.0, v50
	v_mul_f32_e32 v43, v46, v43
	v_mul_f32_e32 v43, v77, v43
	v_mul_f32_e32 v50, 0xbfb8aa3b, v47
	v_exp_f32_e32 v50, v50
	v_rcp_f32_e32 v44, v45
	s_nop 0
	v_add_f32_e32 v46, 1.0, v50
	v_mul_f32_e32 v40, v40, v44
	v_mul_f32_e32 v40, v77, v40
	v_mul_f32_e32 v50, 0xbfb8aa3b, v38
	v_exp_f32_e32 v50, v50
	v_rcp_f32_e32 v44, v46
	s_nop 0
	v_add_f32_e32 v45, 1.0, v50
	v_mul_f32_e32 v44, v47, v44
	v_mul_f32_e32 v44, v77, v44
	v_rcp_f32_e32 v45, v45
	s_nop 0
	v_mul_f32_e32 v38, v38, v45
	v_mul_f32_e32 v45, v77, v38
	v_cvt_pk_bf16_f32 v38, v0, v39
	v_cvt_pk_bf16_f32 v39, v41, v42
	v_add_co_u32_e32 v42, vcc, 0x6027000, v72
	v_cvt_pk_bf16_f32 v40, v43, v40
	v_cvt_pk_bf16_f32 v41, v44, v45
	s_waitcnt vmcnt(6)
	v_mov_b64_e32 v[48:49], v[28:29]
	v_addc_co_u32_e32 v43, vcc, 0, v73, vcc
	global_store_dwordx4 v[42:43], v[38:41], off offset:2560
	s_waitcnt vmcnt(6)
	v_mov_b64_e32 v[44:45], v[32:33]
	v_mov_b64_e32 v[52:53], v[24:25]
	s_waitcnt vmcnt(5)
	v_mov_b64_e32 v[40:41], v[36:37]
	v_mov_b64_e32 v[38:39], v[34:35]
	v_mov_b64_e32 v[42:43], v[30:31]
	v_mov_b64_e32 v[46:47], v[26:27]
	v_mov_b64_e32 v[50:51], v[22:23]
	s_cbranch_scc0 .LBB0_878

; __global__ void __launch_bounds__(512, 2) mk_fwd(Args a_) {
;     ...
;         if (ph + 1 < ph_hi) { if (ph >= 1000) grid.sync(); else xcd_barrier(xbar); }
;     }
.Lpost_getpc0:
	s_add_u32 s98, s98, (.LBB0_7-.Lpost_getpc0)&4294967295
	s_addc_u32 s99, s99, (.LBB0_7-.Lpost_getpc0)>>32
	s_setpc_b64 s[98:99]
	s_nop 0
	s_nop 0
	s_nop 0
	s_nop 0
	s_nop 0
	s_nop 0
	s_nop 0
	s_nop 0
	s_nop 0
	s_nop 0
	s_nop 0
	s_nop 0
	s_nop 0
	s_nop 0
	s_nop 0
	s_nop 0
	s_nop 0
	s_nop 0
	s_nop 0
	s_nop 0
	s_nop 0
	s_nop 0
	s_nop 0
	s_nop 0
	s_nop 0
	s_nop 0
	s_nop 0
	s_nop 0
	s_nop 0
	s_nop 0
	s_nop 0
	s_nop 0
	s_nop 0
	s_nop 0
	s_nop 0
	s_nop 0
	s_nop 0
	s_nop 0
	s_nop 0
	s_nop 0
	s_nop 0
	s_nop 0
	s_nop 0
	s_nop 0
	s_nop 0
	s_nop 0
	s_nop 0
	s_nop 0
	s_nop 0
	s_nop 0
	s_nop 0
	s_nop 0
	s_nop 0
	s_nop 0
	s_nop 0
	s_nop 0
	s_nop 0
	s_nop 0
	s_nop 0
	s_nop 0
	s_nop 0
	s_nop 0
	s_nop 0
	s_nop 0
	s_nop 0
	s_nop 0
	s_nop 0
	s_nop 0
	s_nop 0
	s_nop 0
	s_nop 0
	s_nop 0
	s_nop 0
	s_nop 0
	s_nop 0
	s_nop 0
	s_nop 0
	s_nop 0
	s_nop 0
	s_nop 0
	s_nop 0
	s_nop 0
	s_nop 0
	s_nop 0
	s_nop 0
	s_nop 0
	s_nop 0
	s_nop 0
	s_nop 0
	s_nop 0
	s_nop 0
	s_nop 0
	s_nop 0
	s_nop 0
	s_nop 0
	s_nop 0
	s_nop 0
	s_nop 0
	s_nop 0
	s_nop 0
	s_nop 0
	s_nop 0
	s_nop 0
	s_nop 0
	s_nop 0
	s_nop 0
	s_nop 0
	s_nop 0
	s_nop 0
	s_nop 0
	s_nop 0
	s_nop 0
	s_nop 0
	s_nop 0
	s_nop 0
	s_nop 0
	s_nop 0
	s_nop 0
	s_nop 0
	s_nop 0
	s_nop 0
	s_nop 0
	s_nop 0
	s_nop 0
	s_nop 0
	s_nop 0
	s_nop 0
	s_nop 0
	s_nop 0
	s_nop 0
	s_nop 0
	s_nop 0
	s_nop 0
	s_nop 0
	s_nop 0
	s_nop 0
	s_nop 0
	s_nop 0
	s_nop 0
	s_nop 0
	s_nop 0
	s_nop 0
	s_nop 0
	s_nop 0
	s_nop 0
	s_nop 0
	s_nop 0
	s_nop 0
	s_nop 0
	s_nop 0
	s_nop 0
	s_nop 0
	s_nop 0
	s_nop 0
	s_nop 0
	s_nop 0
	s_nop 0
	s_nop 0
	s_nop 0
	s_nop 0
	s_nop 0
	s_nop 0
	s_nop 0
	s_nop 0
	s_nop 0
	s_nop 0
	s_nop 0
	s_nop 0
	s_nop 0
	s_nop 0
	s_nop 0
	s_nop 0
	s_nop 0
	s_nop 0
	s_nop 0
	s_nop 0
	s_nop 0
	s_nop 0
	s_nop 0
	s_nop 0
	s_nop 0
	s_nop 0
	s_nop 0
	s_nop 0
	s_nop 0
	s_nop 0
	s_nop 0
	s_nop 0
	s_nop 0
	s_nop 0
	s_nop 0
	s_nop 0
	s_nop 0
	s_nop 0
	s_nop 0
	s_nop 0
	s_nop 0
	s_nop 0
	s_nop 0
	s_nop 0
	s_nop 0
	s_nop 0
	s_nop 0
	s_nop 0
	s_nop 0
	s_nop 0
	s_nop 0
	s_nop 0
	s_nop 0
	s_nop 0
	s_nop 0
	s_nop 0
	s_nop 0
	s_nop 0
	s_nop 0
	s_nop 0
	s_nop 0
	s_nop 0
	s_nop 0
	s_nop 0
	s_nop 0
	s_nop 0
	s_nop 0
	s_nop 0
	s_nop 0
	s_nop 0
	s_nop 0
	s_nop 0
	s_nop 0
	s_nop 0
	s_nop 0
	s_nop 0
	s_nop 0
	s_nop 0
	s_nop 0
	s_nop 0
	s_nop 0
	s_nop 0
	s_nop 0
	s_nop 0
	s_nop 0
	s_nop 0
	s_nop 0
	s_nop 0
	s_nop 0
	s_nop 0
	s_nop 0
	s_nop 0
	s_nop 0
	s_nop 0
	s_nop 0
	s_nop 0
	s_nop 0
	s_nop 0
	s_nop 0
	s_nop 0
	s_nop 0
	s_nop 0
	s_nop 0
	s_nop 0
	s_nop 0
	s_nop 0
	s_nop 0
	s_nop 0
	s_nop 0
	s_nop 0
	s_nop 0
	s_nop 0
	s_nop 0
	s_nop 0
	s_nop 0
	s_nop 0
	s_nop 0
	s_nop 0
	s_nop 0
	s_nop 0
	s_nop 0
	s_nop 0
	s_nop 0
	s_nop 0
	s_nop 0
	s_nop 0
	s_nop 0
	s_nop 0
	s_nop 0
	s_nop 0
	s_nop 0
	s_nop 0
	s_nop 0
	s_nop 0
	s_nop 0
	s_nop 0
	s_nop 0
	s_nop 0
	s_nop 0
	s_nop 0
	s_nop 0
	s_nop 0
	s_nop 0
	s_nop 0
	s_nop 0
	s_nop 0
	s_nop 0
	s_nop 0
	s_nop 0
	s_nop 0
	s_nop 0
	s_nop 0
	s_nop 0
	s_nop 0
	s_nop 0
	s_nop 0
	s_nop 0
	s_nop 0
	s_nop 0
	s_nop 0
	s_nop 0
	s_nop 0
	s_nop 0
	s_nop 0
	s_nop 0
	s_nop 0
	s_nop 0
	s_nop 0
	s_nop 0
	s_nop 0
	s_nop 0
	s_nop 0
	s_nop 0
	s_nop 0
	s_nop 0
	s_nop 0
	s_nop 0
	s_nop 0
	s_nop 0
	s_nop 0
	s_nop 0
	s_nop 0
	s_nop 0
	s_nop 0
	s_nop 0
	s_nop 0
	s_nop 0
	s_nop 0
	s_nop 0
	s_nop 0
	s_nop 0
	s_nop 0
	s_nop 0
	s_nop 0
	s_nop 0
	s_nop 0
	s_nop 0
	s_nop 0
	s_nop 0
	s_nop 0
	s_nop 0
	s_nop 0
	s_nop 0
	s_nop 0
	s_nop 0
	s_nop 0
	s_nop 0
	s_nop 0
	s_nop 0
	s_nop 0
	s_nop 0
	s_nop 0
	s_nop 0
	s_nop 0
	s_nop 0
	s_nop 0
	s_nop 0
	s_nop 0
	s_nop 0
	s_nop 0
	s_nop 0
	s_nop 0
	s_nop 0
	s_nop 0
	s_nop 0
	s_nop 0
	s_nop 0
	s_nop 0
	s_nop 0
	s_nop 0
	s_nop 0
	s_nop 0
	s_nop 0
	s_nop 0
	s_nop 0
	s_nop 0
	s_nop 0
	s_nop 0
	s_nop 0
	s_nop 0
	s_nop 0
	s_nop 0
	s_nop 0
	s_nop 0
	s_nop 0
	s_nop 0
	s_nop 0
	s_nop 0
	s_nop 0
	s_nop 0
	s_nop 0
	s_nop 0
	s_nop 0
	s_nop 0
	s_nop 0
	s_nop 0
	s_nop 0
	s_nop 0
	s_nop 0
	s_nop 0
	s_nop 0
	s_nop 0
	s_nop 0
	s_nop 0
	s_nop 0
	s_nop 0
	s_nop 0
	s_nop 0
	s_nop 0
	s_nop 0
	s_nop 0
	s_nop 0
	s_nop 0
	s_nop 0
	s_nop 0
	s_nop 0
	s_nop 0
	s_nop 0
	s_nop 0
	s_nop 0
	s_nop 0
	s_nop 0
	s_nop 0
	s_nop 0
	s_nop 0
	s_nop 0
	s_nop 0
	s_nop 0
	s_nop 0
	s_nop 0
	s_nop 0
	s_nop 0
	s_nop 0
	s_nop 0
	s_nop 0
	s_nop 0
	s_nop 0
	s_nop 0
	s_nop 0
	s_nop 0
	s_nop 0
	s_nop 0
	s_nop 0
	s_nop 0
	s_nop 0
	s_nop 0
	s_nop 0
	s_nop 0
	s_nop 0
	s_nop 0
	s_nop 0
	s_nop 0
	s_nop 0
	s_nop 0
	s_nop 0
	s_nop 0
	s_nop 0
	s_nop 0
	s_nop 0
	s_nop 0
	s_nop 0
	s_nop 0
	s_nop 0
	s_nop 0
	s_nop 0
	s_nop 0
	s_nop 0
	s_nop 0
	s_nop 0
	s_nop 0
	s_nop 0
	s_nop 0
	s_nop 0
	s_nop 0
	s_nop 0
	s_nop 0
	s_nop 0
	s_nop 0
	s_nop 0
	s_nop 0
	s_nop 0
	s_nop 0
	s_nop 0
